# K-loop: s_setprio 3 raised before the section barrier instead of after it (40 sites)
# speedup vs baseline: 1.0029x; 1.0029x over previous
.LBB0_675:
	s_ashr_i32 s21, s20, 31
	s_lshl_b64 s[8:9], s[20:21], 19
	s_add_u32 s26, s36, s8
	s_addc_u32 s27, s37, s9
	s_and_b64 s[8:9], s[6:7], exec
	s_cselect_b32 s21, s27, s69
	s_cselect_b32 s31, s26, s68
	s_ashr_i32 s11, s10, 31
	s_lshl_b64 s[8:9], s[10:11], 19
	s_add_u32 s52, s40, s8
	s_addc_u32 s53, s60, s9
	s_and_b64 s[8:9], s[6:7], exec
	s_cselect_b32 s11, s53, s57
	s_cselect_b32 s82, s52, s56
	s_add_u32 s8, s68, 0x40080
	s_addc_u32 s9, s69, 0
	s_add_u32 s83, s56, 0x100
	s_addc_u32 s84, s57, 0
	s_mov_b32 s85, -2
	s_add_u32 s56, s8, 0xfffc0080
	s_addc_u32 s57, s9, -1
	s_add_i32 s64, 0, 0x10000
	s_cmp_eq_u32 s85, 12
	s_cselect_b32 s69, s21, s57
	s_cselect_b32 s68, s31, s56
	v_add_u32_e32 v160, s64, v163
	s_cselect_b32 s57, s11, s84
	s_cselect_b32 s56, s82, s83
	s_add_i32 s86, 0, 0x14000
	ds_read_b128 v[148:151], v160
	ds_read_b128 v[152:155], v160 offset:1024
	ds_read_b128 v[156:159], v160 offset:2048
	ds_read_b128 v[166:169], v160 offset:3072
	v_add_u32_e32 v160, s86, v163
	ds_read_b128 v[170:173], v160
	ds_read_b128 v[174:177], v160 offset:1024
	ds_read_b128 v[178:181], v160 offset:2048
	ds_read_b128 v[182:185], v160 offset:3072
	v_lshl_add_u64 v[160:161], s[8:9], 0, v[144:145]
	s_add_i32 m0, s72, 0xc000
	ds_read_b128 v[186:189], v165
	ds_read_b128 v[190:193], v165 offset:1024
	ds_read_b128 v[194:197], v165 offset:2048
	ds_read_b128 v[198:201], v165 offset:3072
	ds_read_b128 v[202:205], v165 offset:4096
	ds_read_b128 v[206:209], v165 offset:5120
	ds_read_b128 v[222:225], v165 offset:6144
	ds_read_b128 v[226:229], v165 offset:7168
	global_load_lds_dwordx4 v[160:161], off
	v_lshl_add_u64 v[160:161], s[8:9], 0, v[146:147]
	s_add_i32 m0, s72, 0xe000
	s_nop 0
	global_load_lds_dwordx4 v[160:161], off
	s_waitcnt vmcnt(8)
	s_waitcnt lgkmcnt(0)
	s_setprio 3
	s_barrier
	s_waitcnt lgkmcnt(0)
	v_mfma_f32_16x16x32_bf16 v[70:73], v[148:151], v[186:189], 0
	v_mfma_f32_16x16x32_bf16 v[66:69], v[156:159], v[186:189], 0
	v_mfma_f32_16x16x32_bf16 v[54:57], v[148:151], v[194:197], 0
	v_mfma_f32_16x16x32_bf16 v[50:53], v[156:159], v[194:197], 0
	v_mfma_f32_16x16x32_bf16 v[46:49], v[148:151], v[202:205], 0
	v_mfma_f32_16x16x32_bf16 v[42:45], v[156:159], v[202:205], 0
	v_mfma_f32_16x16x32_bf16 v[38:41], v[148:151], v[222:225], 0
	v_mfma_f32_16x16x32_bf16 v[34:37], v[156:159], v[222:225], 0
	v_mfma_f32_16x16x32_bf16 v[70:73], v[152:155], v[190:193], v[70:73]
	v_mfma_f32_16x16x32_bf16 v[66:69], v[166:169], v[190:193], v[66:69]
	v_mfma_f32_16x16x32_bf16 v[54:57], v[152:155], v[198:201], v[54:57]
	v_mfma_f32_16x16x32_bf16 v[50:53], v[166:169], v[198:201], v[50:53]
	v_mfma_f32_16x16x32_bf16 v[46:49], v[152:155], v[206:209], v[46:49]
	v_mfma_f32_16x16x32_bf16 v[42:45], v[166:169], v[206:209], v[42:45]
	v_mfma_f32_16x16x32_bf16 v[38:41], v[152:155], v[226:229], v[38:41]
	v_mfma_f32_16x16x32_bf16 v[34:37], v[166:169], v[226:229], v[34:37]
	v_mfma_f32_16x16x32_bf16 v[126:129], v[170:173], v[186:189], 0
	v_mfma_f32_16x16x32_bf16 v[122:125], v[178:181], v[186:189], 0
	v_mfma_f32_16x16x32_bf16 v[118:121], v[170:173], v[194:197], 0
	v_mfma_f32_16x16x32_bf16 v[114:117], v[178:181], v[194:197], 0
	v_mfma_f32_16x16x32_bf16 v[110:113], v[170:173], v[202:205], 0
	v_mfma_f32_16x16x32_bf16 v[106:109], v[178:181], v[202:205], 0
	v_mfma_f32_16x16x32_bf16 v[102:105], v[170:173], v[222:225], 0
	v_mfma_f32_16x16x32_bf16 v[98:101], v[178:181], v[222:225], 0
	v_mfma_f32_16x16x32_bf16 v[126:129], v[174:177], v[190:193], v[126:129]
	v_mfma_f32_16x16x32_bf16 v[122:125], v[182:185], v[190:193], v[122:125]
	v_mfma_f32_16x16x32_bf16 v[118:121], v[174:177], v[198:201], v[118:121]
	v_mfma_f32_16x16x32_bf16 v[114:117], v[182:185], v[198:201], v[114:117]
	v_mfma_f32_16x16x32_bf16 v[110:113], v[174:177], v[206:209], v[110:113]
	v_mfma_f32_16x16x32_bf16 v[106:109], v[182:185], v[206:209], v[106:109]
	v_mfma_f32_16x16x32_bf16 v[102:105], v[174:177], v[226:229], v[102:105]
	v_mfma_f32_16x16x32_bf16 v[98:101], v[182:185], v[226:229], v[98:101]
	s_setprio 0
	s_barrier
	s_add_i32 s64, s64, s63
	v_lshl_add_u64 v[160:161], s[56:57], 0, v[0:1]
	s_mov_b32 m0, s64
	ds_read_b128 v[186:189], v165 offset:16384
	ds_read_b128 v[190:193], v165 offset:17408
	ds_read_b128 v[194:197], v165 offset:18432
	ds_read_b128 v[198:201], v165 offset:19456
	ds_read_b128 v[202:205], v165 offset:20480
	ds_read_b128 v[206:209], v165 offset:21504
	ds_read_b128 v[222:225], v165 offset:22528
	ds_read_b128 v[226:229], v165 offset:23552
	global_load_lds_dwordx4 v[160:161], off
	s_add_i32 m0, s64, 0x2000
	s_add_u32 s64, s56, 0x40000
	v_lshl_add_u64 v[210:211], s[56:57], 0, v[134:135]
	s_addc_u32 s65, s57, 0
	s_add_i32 s86, s86, s63
	global_load_lds_dwordx4 v[210:211], off
	v_lshl_add_u64 v[230:231], s[64:65], 0, v[0:1]
	s_mov_b32 m0, s86
	v_lshl_add_u64 v[232:233], s[68:69], 0, v[136:137]
	global_load_lds_dwordx4 v[230:231], off
	v_lshl_add_u64 v[230:231], s[64:65], 0, v[134:135]
	s_add_i32 m0, s86, 0x2000
	s_nop 0
	global_load_lds_dwordx4 v[230:231], off
	v_lshl_add_u64 v[230:231], s[68:69], 0, v[138:139]
	s_mov_b32 m0, s72
	s_nop 0
	global_load_lds_dwordx4 v[230:231], off
	s_mov_b32 m0, s73
	s_nop 0
	global_load_lds_dwordx4 v[232:233], off
	s_waitcnt vmcnt(8)
	s_waitcnt lgkmcnt(0)
	s_setprio 3
	s_barrier
	s_waitcnt lgkmcnt(0)
	v_mfma_f32_16x16x32_bf16 v[30:33], v[148:151], v[186:189], 0
	v_mfma_f32_16x16x32_bf16 v[26:29], v[156:159], v[186:189], 0
	v_mfma_f32_16x16x32_bf16 v[22:25], v[148:151], v[194:197], 0
	v_mfma_f32_16x16x32_bf16 v[18:21], v[156:159], v[194:197], 0
	v_mfma_f32_16x16x32_bf16 v[14:17], v[148:151], v[202:205], 0
	v_mfma_f32_16x16x32_bf16 v[10:13], v[156:159], v[202:205], 0
	v_mfma_f32_16x16x32_bf16 v[6:9], v[148:151], v[222:225], 0
	v_mfma_f32_16x16x32_bf16 v[2:5], v[156:159], v[222:225], 0
	v_mfma_f32_16x16x32_bf16 v[30:33], v[152:155], v[190:193], v[30:33]
	v_mfma_f32_16x16x32_bf16 v[26:29], v[166:169], v[190:193], v[26:29]
	v_mfma_f32_16x16x32_bf16 v[22:25], v[152:155], v[198:201], v[22:25]
	v_mfma_f32_16x16x32_bf16 v[18:21], v[166:169], v[198:201], v[18:21]
	v_mfma_f32_16x16x32_bf16 v[14:17], v[152:155], v[206:209], v[14:17]
	v_mfma_f32_16x16x32_bf16 v[10:13], v[166:169], v[206:209], v[10:13]
	v_mfma_f32_16x16x32_bf16 v[6:9], v[152:155], v[226:229], v[6:9]
	v_mfma_f32_16x16x32_bf16 v[2:5], v[166:169], v[226:229], v[2:5]
	v_mfma_f32_16x16x32_bf16 v[94:97], v[170:173], v[186:189], 0
	v_mfma_f32_16x16x32_bf16 v[90:93], v[178:181], v[186:189], 0
	v_mfma_f32_16x16x32_bf16 v[86:89], v[170:173], v[194:197], 0
	v_mfma_f32_16x16x32_bf16 v[82:85], v[178:181], v[194:197], 0
	v_mfma_f32_16x16x32_bf16 v[78:81], v[170:173], v[202:205], 0
	v_mfma_f32_16x16x32_bf16 v[74:77], v[178:181], v[202:205], 0
	v_mfma_f32_16x16x32_bf16 v[62:65], v[170:173], v[222:225], 0
	v_mfma_f32_16x16x32_bf16 v[58:61], v[178:181], v[222:225], 0
	v_mfma_f32_16x16x32_bf16 v[94:97], v[174:177], v[190:193], v[94:97]
	v_mfma_f32_16x16x32_bf16 v[90:93], v[182:185], v[190:193], v[90:93]
	v_mfma_f32_16x16x32_bf16 v[86:89], v[174:177], v[198:201], v[86:89]
	v_mfma_f32_16x16x32_bf16 v[82:85], v[182:185], v[198:201], v[82:85]
	v_mfma_f32_16x16x32_bf16 v[78:81], v[174:177], v[206:209], v[78:81]
	v_mfma_f32_16x16x32_bf16 v[74:77], v[182:185], v[206:209], v[74:77]
	v_mfma_f32_16x16x32_bf16 v[62:65], v[174:177], v[226:229], v[62:65]
	v_mfma_f32_16x16x32_bf16 v[58:61], v[182:185], v[226:229], v[58:61]
	s_setprio 0
	s_barrier
	s_add_i32 s86, 0, 0x18000
	s_add_i32 s87, 0, 0x1c000
	v_add_u32_e32 v166, s86, v163
	v_add_u32_e32 v182, s87, v163
	ds_read_b128 v[148:151], v166
	ds_read_b128 v[152:155], v166 offset:1024
	ds_read_b128 v[156:159], v166 offset:2048
	ds_read_b128 v[166:169], v166 offset:3072
	ds_read_b128 v[170:173], v182
	ds_read_b128 v[174:177], v182 offset:1024
	ds_read_b128 v[178:181], v182 offset:2048
	ds_read_b128 v[182:185], v182 offset:3072
	s_add_u32 s64, s68, 0x40000
	s_addc_u32 s65, s69, 0
	s_mov_b32 m0, s74
	v_lshl_add_u64 v[234:235], s[64:65], 0, v[138:139]
	ds_read_b128 v[186:189], v165 offset:32768
	ds_read_b128 v[190:193], v165 offset:33792
	ds_read_b128 v[194:197], v165 offset:34816
	ds_read_b128 v[198:201], v165 offset:35840
	ds_read_b128 v[202:205], v165 offset:36864
	ds_read_b128 v[206:209], v165 offset:37888
	ds_read_b128 v[222:225], v165 offset:38912
	ds_read_b128 v[226:229], v165 offset:39936
	global_load_lds_dwordx4 v[234:235], off
	v_lshl_add_u64 v[234:235], s[64:65], 0, v[136:137]
	s_mov_b32 m0, s75
	s_nop 0
	global_load_lds_dwordx4 v[234:235], off
	s_waitcnt vmcnt(8)
	s_waitcnt lgkmcnt(0)
	s_setprio 3
	s_barrier
	s_waitcnt lgkmcnt(0)
	v_mfma_f32_16x16x32_bf16 v[70:73], v[148:151], v[186:189], v[70:73]
	v_mfma_f32_16x16x32_bf16 v[66:69], v[156:159], v[186:189], v[66:69]
	v_mfma_f32_16x16x32_bf16 v[54:57], v[148:151], v[194:197], v[54:57]
	v_mfma_f32_16x16x32_bf16 v[50:53], v[156:159], v[194:197], v[50:53]
	v_mfma_f32_16x16x32_bf16 v[46:49], v[148:151], v[202:205], v[46:49]
	v_mfma_f32_16x16x32_bf16 v[42:45], v[156:159], v[202:205], v[42:45]
	v_mfma_f32_16x16x32_bf16 v[38:41], v[148:151], v[222:225], v[38:41]
	v_mfma_f32_16x16x32_bf16 v[34:37], v[156:159], v[222:225], v[34:37]
	v_mfma_f32_16x16x32_bf16 v[70:73], v[152:155], v[190:193], v[70:73]
	v_mfma_f32_16x16x32_bf16 v[66:69], v[166:169], v[190:193], v[66:69]
	v_mfma_f32_16x16x32_bf16 v[54:57], v[152:155], v[198:201], v[54:57]
	v_mfma_f32_16x16x32_bf16 v[50:53], v[166:169], v[198:201], v[50:53]
	v_mfma_f32_16x16x32_bf16 v[46:49], v[152:155], v[206:209], v[46:49]
	v_mfma_f32_16x16x32_bf16 v[42:45], v[166:169], v[206:209], v[42:45]
	v_mfma_f32_16x16x32_bf16 v[38:41], v[152:155], v[226:229], v[38:41]
	v_mfma_f32_16x16x32_bf16 v[34:37], v[166:169], v[226:229], v[34:37]
	v_mfma_f32_16x16x32_bf16 v[126:129], v[170:173], v[186:189], v[126:129]
	v_mfma_f32_16x16x32_bf16 v[122:125], v[178:181], v[186:189], v[122:125]
	v_mfma_f32_16x16x32_bf16 v[118:121], v[170:173], v[194:197], v[118:121]
	v_mfma_f32_16x16x32_bf16 v[114:117], v[178:181], v[194:197], v[114:117]
	v_mfma_f32_16x16x32_bf16 v[110:113], v[170:173], v[202:205], v[110:113]
	v_mfma_f32_16x16x32_bf16 v[106:109], v[178:181], v[202:205], v[106:109]
	v_mfma_f32_16x16x32_bf16 v[102:105], v[170:173], v[222:225], v[102:105]
	v_mfma_f32_16x16x32_bf16 v[98:101], v[178:181], v[222:225], v[98:101]
	v_mfma_f32_16x16x32_bf16 v[126:129], v[174:177], v[190:193], v[126:129]
	v_mfma_f32_16x16x32_bf16 v[122:125], v[182:185], v[190:193], v[122:125]
	v_mfma_f32_16x16x32_bf16 v[118:121], v[174:177], v[198:201], v[118:121]
	v_mfma_f32_16x16x32_bf16 v[114:117], v[182:185], v[198:201], v[114:117]
	v_mfma_f32_16x16x32_bf16 v[110:113], v[174:177], v[206:209], v[110:113]
	v_mfma_f32_16x16x32_bf16 v[106:109], v[182:185], v[206:209], v[106:109]
	v_mfma_f32_16x16x32_bf16 v[102:105], v[174:177], v[226:229], v[102:105]
	v_mfma_f32_16x16x32_bf16 v[98:101], v[182:185], v[226:229], v[98:101]
	s_setprio 0
	s_barrier
	s_add_i32 s64, s86, s63
	v_lshl_add_u64 v[160:161], v[160:161], 0, s[48:49]
	s_mov_b32 m0, s64
	ds_read_b128 v[186:189], v165 offset:49152
	ds_read_b128 v[190:193], v165 offset:50176
	ds_read_b128 v[194:197], v165 offset:51200
	ds_read_b128 v[198:201], v165 offset:52224
	ds_read_b128 v[202:205], v165 offset:53248
	ds_read_b128 v[206:209], v165 offset:54272
	ds_read_b128 v[222:225], v165 offset:55296
	ds_read_b128 v[226:229], v165 offset:56320
	global_load_lds_dwordx4 v[160:161], off
	s_add_i32 m0, s64, 0x2000
	s_add_u32 s56, s56, 0x40080
	v_lshl_add_u64 v[160:161], v[210:211], 0, s[48:49]
	s_addc_u32 s57, s57, 0
	s_add_i32 s64, s87, s63
	global_load_lds_dwordx4 v[160:161], off
	v_lshl_add_u64 v[160:161], s[56:57], 0, v[0:1]
	s_mov_b32 m0, s64
	s_nop 0
	global_load_lds_dwordx4 v[160:161], off
	v_lshl_add_u64 v[160:161], s[56:57], 0, v[134:135]
	s_add_i32 m0, s64, 0x2000
	s_nop 0
	global_load_lds_dwordx4 v[160:161], off
	v_lshl_add_u64 v[160:161], v[230:231], 0, s[48:49]
	s_mov_b32 m0, s78
	s_nop 0
	global_load_lds_dwordx4 v[160:161], off
	v_lshl_add_u64 v[160:161], v[232:233], 0, s[48:49]
	s_mov_b32 m0, s79
	s_nop 0
	global_load_lds_dwordx4 v[160:161], off
	s_waitcnt vmcnt(8)
	s_waitcnt lgkmcnt(0)
	s_setprio 3
	s_barrier
	s_waitcnt lgkmcnt(0)
	v_mfma_f32_16x16x32_bf16 v[30:33], v[148:151], v[186:189], v[30:33]
	v_mfma_f32_16x16x32_bf16 v[26:29], v[156:159], v[186:189], v[26:29]
	v_mfma_f32_16x16x32_bf16 v[22:25], v[148:151], v[194:197], v[22:25]
	v_mfma_f32_16x16x32_bf16 v[18:21], v[156:159], v[194:197], v[18:21]
	v_mfma_f32_16x16x32_bf16 v[14:17], v[148:151], v[202:205], v[14:17]
	v_mfma_f32_16x16x32_bf16 v[10:13], v[156:159], v[202:205], v[10:13]
	v_mfma_f32_16x16x32_bf16 v[6:9], v[148:151], v[222:225], v[6:9]
	v_mfma_f32_16x16x32_bf16 v[2:5], v[156:159], v[222:225], v[2:5]
	v_mfma_f32_16x16x32_bf16 v[30:33], v[152:155], v[190:193], v[30:33]
	v_mfma_f32_16x16x32_bf16 v[26:29], v[166:169], v[190:193], v[26:29]
	v_mfma_f32_16x16x32_bf16 v[22:25], v[152:155], v[198:201], v[22:25]
	v_mfma_f32_16x16x32_bf16 v[18:21], v[166:169], v[198:201], v[18:21]
	v_mfma_f32_16x16x32_bf16 v[14:17], v[152:155], v[206:209], v[14:17]
	v_mfma_f32_16x16x32_bf16 v[10:13], v[166:169], v[206:209], v[10:13]
	v_mfma_f32_16x16x32_bf16 v[6:9], v[152:155], v[226:229], v[6:9]
	v_mfma_f32_16x16x32_bf16 v[2:5], v[166:169], v[226:229], v[2:5]
	v_mfma_f32_16x16x32_bf16 v[94:97], v[170:173], v[186:189], v[94:97]
	v_mfma_f32_16x16x32_bf16 v[90:93], v[178:181], v[186:189], v[90:93]
	v_mfma_f32_16x16x32_bf16 v[86:89], v[170:173], v[194:197], v[86:89]
	v_mfma_f32_16x16x32_bf16 v[82:85], v[178:181], v[194:197], v[82:85]
	v_mfma_f32_16x16x32_bf16 v[78:81], v[170:173], v[202:205], v[78:81]
	v_mfma_f32_16x16x32_bf16 v[74:77], v[178:181], v[202:205], v[74:77]
	v_mfma_f32_16x16x32_bf16 v[62:65], v[170:173], v[222:225], v[62:65]
	v_mfma_f32_16x16x32_bf16 v[58:61], v[178:181], v[222:225], v[58:61]
	v_mfma_f32_16x16x32_bf16 v[94:97], v[174:177], v[190:193], v[94:97]
	v_mfma_f32_16x16x32_bf16 v[90:93], v[182:185], v[190:193], v[90:93]
	v_mfma_f32_16x16x32_bf16 v[86:89], v[174:177], v[198:201], v[86:89]
	v_mfma_f32_16x16x32_bf16 v[82:85], v[182:185], v[198:201], v[82:85]
	v_mfma_f32_16x16x32_bf16 v[78:81], v[174:177], v[206:209], v[78:81]
	v_mfma_f32_16x16x32_bf16 v[74:77], v[182:185], v[206:209], v[74:77]
	v_mfma_f32_16x16x32_bf16 v[62:65], v[174:177], v[226:229], v[62:65]
	v_mfma_f32_16x16x32_bf16 v[58:61], v[182:185], v[226:229], v[58:61]
	s_setprio 0
	s_barrier
	s_add_i32 s85, s85, 2
	s_add_u32 s8, s8, 0x100
	s_addc_u32 s9, s9, 0
	s_add_u32 s83, s83, 0x100
	s_addc_u32 s84, s84, 0
.LBB0_676:
	s_add_u32 s56, s8, 0xfffc0080
	s_addc_u32 s57, s9, -1
	s_add_i32 s64, 0, 0x10000
	s_cmp_eq_u32 s85, 12
	s_cselect_b32 s69, s21, s57
	s_cselect_b32 s68, s31, s56
	v_add_u32_e32 v160, s64, v163
	s_cselect_b32 s57, s11, s84
	s_cselect_b32 s56, s82, s83
	s_add_i32 s86, 0, 0x14000
	ds_read_b128 v[148:151], v160
	ds_read_b128 v[152:155], v160 offset:1024
	ds_read_b128 v[156:159], v160 offset:2048
	ds_read_b128 v[166:169], v160 offset:3072
	v_add_u32_e32 v160, s86, v163
	ds_read_b128 v[170:173], v160
	ds_read_b128 v[174:177], v160 offset:1024
	ds_read_b128 v[178:181], v160 offset:2048
	ds_read_b128 v[182:185], v160 offset:3072
	v_lshl_add_u64 v[160:161], s[8:9], 0, v[144:145]
	s_add_i32 m0, s72, 0xc000
	ds_read_b128 v[186:189], v165
	ds_read_b128 v[190:193], v165 offset:1024
	ds_read_b128 v[194:197], v165 offset:2048
	ds_read_b128 v[198:201], v165 offset:3072
	ds_read_b128 v[202:205], v165 offset:4096
	ds_read_b128 v[206:209], v165 offset:5120
	ds_read_b128 v[222:225], v165 offset:6144
	ds_read_b128 v[226:229], v165 offset:7168
	global_load_lds_dwordx4 v[160:161], off
	v_lshl_add_u64 v[160:161], s[8:9], 0, v[146:147]
	s_add_i32 m0, s72, 0xe000
	s_nop 0
	global_load_lds_dwordx4 v[160:161], off
	s_waitcnt vmcnt(8)
	s_waitcnt lgkmcnt(0)
	s_setprio 3
	s_barrier
	s_waitcnt lgkmcnt(0)
	v_mfma_f32_16x16x32_bf16 v[70:73], v[148:151], v[186:189], v[70:73]
	v_mfma_f32_16x16x32_bf16 v[66:69], v[156:159], v[186:189], v[66:69]
	v_mfma_f32_16x16x32_bf16 v[54:57], v[148:151], v[194:197], v[54:57]
	v_mfma_f32_16x16x32_bf16 v[50:53], v[156:159], v[194:197], v[50:53]
	v_mfma_f32_16x16x32_bf16 v[46:49], v[148:151], v[202:205], v[46:49]
	v_mfma_f32_16x16x32_bf16 v[42:45], v[156:159], v[202:205], v[42:45]
	v_mfma_f32_16x16x32_bf16 v[38:41], v[148:151], v[222:225], v[38:41]
	v_mfma_f32_16x16x32_bf16 v[34:37], v[156:159], v[222:225], v[34:37]
	v_mfma_f32_16x16x32_bf16 v[70:73], v[152:155], v[190:193], v[70:73]
	v_mfma_f32_16x16x32_bf16 v[66:69], v[166:169], v[190:193], v[66:69]
	v_mfma_f32_16x16x32_bf16 v[54:57], v[152:155], v[198:201], v[54:57]
	v_mfma_f32_16x16x32_bf16 v[50:53], v[166:169], v[198:201], v[50:53]
	v_mfma_f32_16x16x32_bf16 v[46:49], v[152:155], v[206:209], v[46:49]
	v_mfma_f32_16x16x32_bf16 v[42:45], v[166:169], v[206:209], v[42:45]
	v_mfma_f32_16x16x32_bf16 v[38:41], v[152:155], v[226:229], v[38:41]
	v_mfma_f32_16x16x32_bf16 v[34:37], v[166:169], v[226:229], v[34:37]
	v_mfma_f32_16x16x32_bf16 v[126:129], v[170:173], v[186:189], v[126:129]
	v_mfma_f32_16x16x32_bf16 v[122:125], v[178:181], v[186:189], v[122:125]
	v_mfma_f32_16x16x32_bf16 v[118:121], v[170:173], v[194:197], v[118:121]
	v_mfma_f32_16x16x32_bf16 v[114:117], v[178:181], v[194:197], v[114:117]
	v_mfma_f32_16x16x32_bf16 v[110:113], v[170:173], v[202:205], v[110:113]
	v_mfma_f32_16x16x32_bf16 v[106:109], v[178:181], v[202:205], v[106:109]
	v_mfma_f32_16x16x32_bf16 v[102:105], v[170:173], v[222:225], v[102:105]
	v_mfma_f32_16x16x32_bf16 v[98:101], v[178:181], v[222:225], v[98:101]
	v_mfma_f32_16x16x32_bf16 v[126:129], v[174:177], v[190:193], v[126:129]
	v_mfma_f32_16x16x32_bf16 v[122:125], v[182:185], v[190:193], v[122:125]
	v_mfma_f32_16x16x32_bf16 v[118:121], v[174:177], v[198:201], v[118:121]
	v_mfma_f32_16x16x32_bf16 v[114:117], v[182:185], v[198:201], v[114:117]
	v_mfma_f32_16x16x32_bf16 v[110:113], v[174:177], v[206:209], v[110:113]
	v_mfma_f32_16x16x32_bf16 v[106:109], v[182:185], v[206:209], v[106:109]
	v_mfma_f32_16x16x32_bf16 v[102:105], v[174:177], v[226:229], v[102:105]
	v_mfma_f32_16x16x32_bf16 v[98:101], v[182:185], v[226:229], v[98:101]
	s_setprio 0
	s_barrier
	s_add_i32 s64, s64, s63
	v_lshl_add_u64 v[160:161], s[56:57], 0, v[0:1]
	s_mov_b32 m0, s64
	ds_read_b128 v[186:189], v165 offset:16384
	ds_read_b128 v[190:193], v165 offset:17408
	ds_read_b128 v[194:197], v165 offset:18432
	ds_read_b128 v[198:201], v165 offset:19456
	ds_read_b128 v[202:205], v165 offset:20480
	ds_read_b128 v[206:209], v165 offset:21504
	ds_read_b128 v[222:225], v165 offset:22528
	ds_read_b128 v[226:229], v165 offset:23552
	global_load_lds_dwordx4 v[160:161], off
	s_add_i32 m0, s64, 0x2000
	s_add_u32 s64, s56, 0x40000
	v_lshl_add_u64 v[210:211], s[56:57], 0, v[134:135]
	s_addc_u32 s65, s57, 0
	s_add_i32 s86, s86, s63
	global_load_lds_dwordx4 v[210:211], off
	v_lshl_add_u64 v[230:231], s[64:65], 0, v[0:1]
	s_mov_b32 m0, s86
	v_lshl_add_u64 v[232:233], s[68:69], 0, v[136:137]
	global_load_lds_dwordx4 v[230:231], off
	v_lshl_add_u64 v[230:231], s[64:65], 0, v[134:135]
	s_add_i32 m0, s86, 0x2000
	s_nop 0
	global_load_lds_dwordx4 v[230:231], off
	v_lshl_add_u64 v[230:231], s[68:69], 0, v[138:139]
	s_mov_b32 m0, s72
	s_nop 0
	global_load_lds_dwordx4 v[230:231], off
	s_mov_b32 m0, s73
	s_nop 0
	global_load_lds_dwordx4 v[232:233], off
	s_waitcnt vmcnt(8)
	s_waitcnt lgkmcnt(0)
	s_setprio 3
	s_barrier
	s_waitcnt lgkmcnt(0)
	v_mfma_f32_16x16x32_bf16 v[30:33], v[148:151], v[186:189], v[30:33]
	v_mfma_f32_16x16x32_bf16 v[26:29], v[156:159], v[186:189], v[26:29]
	v_mfma_f32_16x16x32_bf16 v[22:25], v[148:151], v[194:197], v[22:25]
	v_mfma_f32_16x16x32_bf16 v[18:21], v[156:159], v[194:197], v[18:21]
	v_mfma_f32_16x16x32_bf16 v[14:17], v[148:151], v[202:205], v[14:17]
	v_mfma_f32_16x16x32_bf16 v[10:13], v[156:159], v[202:205], v[10:13]
	v_mfma_f32_16x16x32_bf16 v[6:9], v[148:151], v[222:225], v[6:9]
	v_mfma_f32_16x16x32_bf16 v[2:5], v[156:159], v[222:225], v[2:5]
	v_mfma_f32_16x16x32_bf16 v[30:33], v[152:155], v[190:193], v[30:33]
	v_mfma_f32_16x16x32_bf16 v[26:29], v[166:169], v[190:193], v[26:29]
	v_mfma_f32_16x16x32_bf16 v[22:25], v[152:155], v[198:201], v[22:25]
	v_mfma_f32_16x16x32_bf16 v[18:21], v[166:169], v[198:201], v[18:21]
	v_mfma_f32_16x16x32_bf16 v[14:17], v[152:155], v[206:209], v[14:17]
	v_mfma_f32_16x16x32_bf16 v[10:13], v[166:169], v[206:209], v[10:13]
	v_mfma_f32_16x16x32_bf16 v[6:9], v[152:155], v[226:229], v[6:9]
	v_mfma_f32_16x16x32_bf16 v[2:5], v[166:169], v[226:229], v[2:5]
	v_mfma_f32_16x16x32_bf16 v[94:97], v[170:173], v[186:189], v[94:97]
	v_mfma_f32_16x16x32_bf16 v[90:93], v[178:181], v[186:189], v[90:93]
	v_mfma_f32_16x16x32_bf16 v[86:89], v[170:173], v[194:197], v[86:89]
	v_mfma_f32_16x16x32_bf16 v[82:85], v[178:181], v[194:197], v[82:85]
	v_mfma_f32_16x16x32_bf16 v[78:81], v[170:173], v[202:205], v[78:81]
	v_mfma_f32_16x16x32_bf16 v[74:77], v[178:181], v[202:205], v[74:77]
	v_mfma_f32_16x16x32_bf16 v[62:65], v[170:173], v[222:225], v[62:65]
	v_mfma_f32_16x16x32_bf16 v[58:61], v[178:181], v[222:225], v[58:61]
	v_mfma_f32_16x16x32_bf16 v[94:97], v[174:177], v[190:193], v[94:97]
	v_mfma_f32_16x16x32_bf16 v[90:93], v[182:185], v[190:193], v[90:93]
	v_mfma_f32_16x16x32_bf16 v[86:89], v[174:177], v[198:201], v[86:89]
	v_mfma_f32_16x16x32_bf16 v[82:85], v[182:185], v[198:201], v[82:85]
	v_mfma_f32_16x16x32_bf16 v[78:81], v[174:177], v[206:209], v[78:81]
	v_mfma_f32_16x16x32_bf16 v[74:77], v[182:185], v[206:209], v[74:77]
	v_mfma_f32_16x16x32_bf16 v[62:65], v[174:177], v[226:229], v[62:65]
	v_mfma_f32_16x16x32_bf16 v[58:61], v[182:185], v[226:229], v[58:61]
	s_setprio 0
	s_barrier
	s_add_i32 s86, 0, 0x18000
	s_add_i32 s87, 0, 0x1c000
	v_add_u32_e32 v166, s86, v163
	v_add_u32_e32 v182, s87, v163
	ds_read_b128 v[148:151], v166
	ds_read_b128 v[152:155], v166 offset:1024
	ds_read_b128 v[156:159], v166 offset:2048
	ds_read_b128 v[166:169], v166 offset:3072
	ds_read_b128 v[170:173], v182
	ds_read_b128 v[174:177], v182 offset:1024
	ds_read_b128 v[178:181], v182 offset:2048
	ds_read_b128 v[182:185], v182 offset:3072
	s_add_u32 s64, s68, 0x40000
	s_addc_u32 s65, s69, 0
	s_mov_b32 m0, s74
	v_lshl_add_u64 v[234:235], s[64:65], 0, v[138:139]
	ds_read_b128 v[186:189], v165 offset:32768
	ds_read_b128 v[190:193], v165 offset:33792
	ds_read_b128 v[194:197], v165 offset:34816
	ds_read_b128 v[198:201], v165 offset:35840
	ds_read_b128 v[202:205], v165 offset:36864
	ds_read_b128 v[206:209], v165 offset:37888
	ds_read_b128 v[222:225], v165 offset:38912
	ds_read_b128 v[226:229], v165 offset:39936
	global_load_lds_dwordx4 v[234:235], off
	v_lshl_add_u64 v[234:235], s[64:65], 0, v[136:137]
	s_mov_b32 m0, s75
	s_nop 0
	global_load_lds_dwordx4 v[234:235], off
	s_waitcnt vmcnt(8)
	s_waitcnt lgkmcnt(0)
	s_setprio 3
	s_barrier
	s_waitcnt lgkmcnt(0)
	v_mfma_f32_16x16x32_bf16 v[70:73], v[148:151], v[186:189], v[70:73]
	v_mfma_f32_16x16x32_bf16 v[66:69], v[156:159], v[186:189], v[66:69]
	v_mfma_f32_16x16x32_bf16 v[54:57], v[148:151], v[194:197], v[54:57]
	v_mfma_f32_16x16x32_bf16 v[50:53], v[156:159], v[194:197], v[50:53]
	v_mfma_f32_16x16x32_bf16 v[46:49], v[148:151], v[202:205], v[46:49]
	v_mfma_f32_16x16x32_bf16 v[42:45], v[156:159], v[202:205], v[42:45]
	v_mfma_f32_16x16x32_bf16 v[38:41], v[148:151], v[222:225], v[38:41]
	v_mfma_f32_16x16x32_bf16 v[34:37], v[156:159], v[222:225], v[34:37]
	v_mfma_f32_16x16x32_bf16 v[70:73], v[152:155], v[190:193], v[70:73]
	v_mfma_f32_16x16x32_bf16 v[66:69], v[166:169], v[190:193], v[66:69]
	v_mfma_f32_16x16x32_bf16 v[54:57], v[152:155], v[198:201], v[54:57]
	v_mfma_f32_16x16x32_bf16 v[50:53], v[166:169], v[198:201], v[50:53]
	v_mfma_f32_16x16x32_bf16 v[46:49], v[152:155], v[206:209], v[46:49]
	v_mfma_f32_16x16x32_bf16 v[42:45], v[166:169], v[206:209], v[42:45]
	v_mfma_f32_16x16x32_bf16 v[38:41], v[152:155], v[226:229], v[38:41]
	v_mfma_f32_16x16x32_bf16 v[34:37], v[166:169], v[226:229], v[34:37]
	v_mfma_f32_16x16x32_bf16 v[126:129], v[170:173], v[186:189], v[126:129]
	v_mfma_f32_16x16x32_bf16 v[122:125], v[178:181], v[186:189], v[122:125]
	v_mfma_f32_16x16x32_bf16 v[118:121], v[170:173], v[194:197], v[118:121]
	v_mfma_f32_16x16x32_bf16 v[114:117], v[178:181], v[194:197], v[114:117]
	v_mfma_f32_16x16x32_bf16 v[110:113], v[170:173], v[202:205], v[110:113]
	v_mfma_f32_16x16x32_bf16 v[106:109], v[178:181], v[202:205], v[106:109]
	v_mfma_f32_16x16x32_bf16 v[102:105], v[170:173], v[222:225], v[102:105]
	v_mfma_f32_16x16x32_bf16 v[98:101], v[178:181], v[222:225], v[98:101]
	v_mfma_f32_16x16x32_bf16 v[126:129], v[174:177], v[190:193], v[126:129]
	v_mfma_f32_16x16x32_bf16 v[122:125], v[182:185], v[190:193], v[122:125]
	v_mfma_f32_16x16x32_bf16 v[118:121], v[174:177], v[198:201], v[118:121]
	v_mfma_f32_16x16x32_bf16 v[114:117], v[182:185], v[198:201], v[114:117]
	v_mfma_f32_16x16x32_bf16 v[110:113], v[174:177], v[206:209], v[110:113]
	v_mfma_f32_16x16x32_bf16 v[106:109], v[182:185], v[206:209], v[106:109]
	v_mfma_f32_16x16x32_bf16 v[102:105], v[174:177], v[226:229], v[102:105]
	v_mfma_f32_16x16x32_bf16 v[98:101], v[182:185], v[226:229], v[98:101]
	s_setprio 0
	s_barrier
	s_add_i32 s64, s86, s63
	v_lshl_add_u64 v[160:161], v[160:161], 0, s[48:49]
	s_mov_b32 m0, s64
	ds_read_b128 v[186:189], v165 offset:49152
	ds_read_b128 v[190:193], v165 offset:50176
	ds_read_b128 v[194:197], v165 offset:51200
	ds_read_b128 v[198:201], v165 offset:52224
	ds_read_b128 v[202:205], v165 offset:53248
	ds_read_b128 v[206:209], v165 offset:54272
	ds_read_b128 v[222:225], v165 offset:55296
	ds_read_b128 v[226:229], v165 offset:56320
	global_load_lds_dwordx4 v[160:161], off
	s_add_i32 m0, s64, 0x2000
	s_add_u32 s56, s56, 0x40080
	v_lshl_add_u64 v[160:161], v[210:211], 0, s[48:49]
	s_addc_u32 s57, s57, 0
	s_add_i32 s64, s87, s63
	global_load_lds_dwordx4 v[160:161], off
	v_lshl_add_u64 v[160:161], s[56:57], 0, v[0:1]
	s_mov_b32 m0, s64
	s_nop 0
	global_load_lds_dwordx4 v[160:161], off
	v_lshl_add_u64 v[160:161], s[56:57], 0, v[134:135]
	s_add_i32 m0, s64, 0x2000
	s_nop 0
	global_load_lds_dwordx4 v[160:161], off
	v_lshl_add_u64 v[160:161], v[230:231], 0, s[48:49]
	s_mov_b32 m0, s78
	s_nop 0
	global_load_lds_dwordx4 v[160:161], off
	v_lshl_add_u64 v[160:161], v[232:233], 0, s[48:49]
	s_mov_b32 m0, s79
	s_nop 0
	global_load_lds_dwordx4 v[160:161], off
	s_waitcnt vmcnt(8)
	s_waitcnt lgkmcnt(0)
	s_setprio 3
	s_barrier
	s_waitcnt lgkmcnt(0)
	v_mfma_f32_16x16x32_bf16 v[30:33], v[148:151], v[186:189], v[30:33]
	v_mfma_f32_16x16x32_bf16 v[26:29], v[156:159], v[186:189], v[26:29]
	v_mfma_f32_16x16x32_bf16 v[22:25], v[148:151], v[194:197], v[22:25]
	v_mfma_f32_16x16x32_bf16 v[18:21], v[156:159], v[194:197], v[18:21]
	v_mfma_f32_16x16x32_bf16 v[14:17], v[148:151], v[202:205], v[14:17]
	v_mfma_f32_16x16x32_bf16 v[10:13], v[156:159], v[202:205], v[10:13]
	v_mfma_f32_16x16x32_bf16 v[6:9], v[148:151], v[222:225], v[6:9]
	v_mfma_f32_16x16x32_bf16 v[2:5], v[156:159], v[222:225], v[2:5]
	v_mfma_f32_16x16x32_bf16 v[30:33], v[152:155], v[190:193], v[30:33]
	v_mfma_f32_16x16x32_bf16 v[26:29], v[166:169], v[190:193], v[26:29]
	v_mfma_f32_16x16x32_bf16 v[22:25], v[152:155], v[198:201], v[22:25]
	v_mfma_f32_16x16x32_bf16 v[18:21], v[166:169], v[198:201], v[18:21]
	v_mfma_f32_16x16x32_bf16 v[14:17], v[152:155], v[206:209], v[14:17]
	v_mfma_f32_16x16x32_bf16 v[10:13], v[166:169], v[206:209], v[10:13]
	v_mfma_f32_16x16x32_bf16 v[6:9], v[152:155], v[226:229], v[6:9]
	v_mfma_f32_16x16x32_bf16 v[2:5], v[166:169], v[226:229], v[2:5]
	v_mfma_f32_16x16x32_bf16 v[94:97], v[170:173], v[186:189], v[94:97]
	v_mfma_f32_16x16x32_bf16 v[90:93], v[178:181], v[186:189], v[90:93]
	v_mfma_f32_16x16x32_bf16 v[86:89], v[170:173], v[194:197], v[86:89]
	v_mfma_f32_16x16x32_bf16 v[82:85], v[178:181], v[194:197], v[82:85]
	v_mfma_f32_16x16x32_bf16 v[78:81], v[170:173], v[202:205], v[78:81]
	v_mfma_f32_16x16x32_bf16 v[74:77], v[178:181], v[202:205], v[74:77]
	v_mfma_f32_16x16x32_bf16 v[62:65], v[170:173], v[222:225], v[62:65]
	v_mfma_f32_16x16x32_bf16 v[58:61], v[178:181], v[222:225], v[58:61]
	v_mfma_f32_16x16x32_bf16 v[94:97], v[174:177], v[190:193], v[94:97]
	v_mfma_f32_16x16x32_bf16 v[90:93], v[182:185], v[190:193], v[90:93]
	v_mfma_f32_16x16x32_bf16 v[86:89], v[174:177], v[198:201], v[86:89]
	v_mfma_f32_16x16x32_bf16 v[82:85], v[182:185], v[198:201], v[82:85]
	v_mfma_f32_16x16x32_bf16 v[78:81], v[174:177], v[206:209], v[78:81]
	v_mfma_f32_16x16x32_bf16 v[74:77], v[182:185], v[206:209], v[74:77]
	v_mfma_f32_16x16x32_bf16 v[62:65], v[174:177], v[226:229], v[62:65]
	v_mfma_f32_16x16x32_bf16 v[58:61], v[182:185], v[226:229], v[58:61]
	s_setprio 0
	s_barrier
	s_add_i32 s85, s85, 2
	s_add_u32 s8, s8, 0x100
	s_addc_u32 s9, s9, 0
	s_add_u32 s83, s83, 0x100
	s_addc_u32 s84, s84, 0
	s_cmp_gt_u32 s85, 13
	s_cbranch_scc0 .LBB0_676
	s_and_b64 vcc, exec, s[16:17]
	s_cbranch_vccnz .LBB0_681
	s_cmp_lt_i32 s30, 16
	s_mov_b64 s[8:9], -1
	s_cbranch_scc1 .LBB0_682

.LBB0_1458:
	s_ashr_i32 s11, s12, 3
	s_add_i32 s11, s12, s11
	s_and_b64 s[16:17], s[66:67], s[4:5]
	s_add_i32 s11, s11, 1
	s_and_b64 s[16:17], s[16:17], exec
	s_cselect_b32 s12, s11, s12
	s_ashr_i32 s13, s12, 31
	s_lshl_b64 s[16:17], s[12:13], 19
	s_add_u32 s16, s37, s16
	s_addc_u32 s17, s60, s17
	s_and_b64 s[18:19], s[4:5], exec
	s_cselect_b32 s13, s17, s53
	s_cselect_b32 s27, s16, s52
	s_ashr_i32 s11, s10, 31
	s_lshl_b64 s[18:19], s[10:11], 19
	s_add_u32 s18, s63, s18
	s_addc_u32 s19, s70, s19
	s_and_b64 s[30:31], s[4:5], exec
	s_cselect_b32 s11, s19, s57
	s_cselect_b32 s30, s18, s56
	s_add_u32 s52, s52, 0x40080
	s_addc_u32 s53, s53, 0
	s_add_u32 s31, s56, 0x100
	s_addc_u32 s84, s57, 0
	s_mov_b32 s85, -2
	s_add_u32 s56, s52, 0xfffc0080
	s_addc_u32 s57, s53, -1
	s_add_i32 s64, 0, 0x10000
	s_cmp_eq_u32 s85, 12
	s_cselect_b32 s69, s13, s57
	s_cselect_b32 s68, s27, s56
	v_add_u32_e32 v0, s64, v167
	s_cselect_b32 s57, s11, s84
	s_cselect_b32 s56, s30, s31
	s_add_i32 s86, 0, 0x14000
	ds_read_b128 v[134:137], v0
	ds_read_b128 v[150:153], v0 offset:1024
	ds_read_b128 v[154:157], v0 offset:2048
	ds_read_b128 v[158:161], v0 offset:3072
	v_add_u32_e32 v0, s86, v167
	ds_read_b128 v[162:165], v0
	ds_read_b128 v[170:173], v0 offset:1024
	ds_read_b128 v[174:177], v0 offset:2048
	ds_read_b128 v[178:181], v0 offset:3072
	v_lshl_add_u64 v[210:211], s[52:53], 0, v[146:147]
	s_add_i32 m0, s21, 0xc000
	ds_read_b128 v[182:185], v169
	ds_read_b128 v[186:189], v169 offset:1024
	ds_read_b128 v[190:193], v169 offset:2048
	ds_read_b128 v[194:197], v169 offset:3072
	ds_read_b128 v[198:201], v169 offset:4096
	ds_read_b128 v[202:205], v169 offset:5120
	ds_read_b128 v[206:209], v169 offset:6144
	ds_read_b128 v[224:227], v169 offset:7168
	global_load_lds_dwordx4 v[210:211], off
	v_lshl_add_u64 v[210:211], s[52:53], 0, v[148:149]
	s_add_i32 m0, s21, 0xe000
	s_nop 0
	global_load_lds_dwordx4 v[210:211], off
	s_waitcnt vmcnt(8)
	s_waitcnt lgkmcnt(0)
	s_setprio 3
	s_barrier
	s_waitcnt lgkmcnt(0)
	v_mfma_f32_16x16x32_bf16 v[126:129], v[134:137], v[182:185], 0
	v_mfma_f32_16x16x32_bf16 v[122:125], v[154:157], v[182:185], 0
	v_mfma_f32_16x16x32_bf16 v[110:113], v[134:137], v[190:193], 0
	v_mfma_f32_16x16x32_bf16 v[106:109], v[154:157], v[190:193], 0
	v_mfma_f32_16x16x32_bf16 v[94:97], v[134:137], v[198:201], 0
	v_mfma_f32_16x16x32_bf16 v[90:93], v[154:157], v[198:201], 0
	v_mfma_f32_16x16x32_bf16 v[78:81], v[134:137], v[206:209], 0
	v_mfma_f32_16x16x32_bf16 v[74:77], v[154:157], v[206:209], 0
	v_mfma_f32_16x16x32_bf16 v[126:129], v[150:153], v[186:189], v[126:129]
	v_mfma_f32_16x16x32_bf16 v[122:125], v[158:161], v[186:189], v[122:125]
	v_mfma_f32_16x16x32_bf16 v[110:113], v[150:153], v[194:197], v[110:113]
	v_mfma_f32_16x16x32_bf16 v[106:109], v[158:161], v[194:197], v[106:109]
	v_mfma_f32_16x16x32_bf16 v[94:97], v[150:153], v[202:205], v[94:97]
	v_mfma_f32_16x16x32_bf16 v[90:93], v[158:161], v[202:205], v[90:93]
	v_mfma_f32_16x16x32_bf16 v[78:81], v[150:153], v[224:227], v[78:81]
	v_mfma_f32_16x16x32_bf16 v[74:77], v[158:161], v[224:227], v[74:77]
	v_mfma_f32_16x16x32_bf16 v[118:121], v[162:165], v[182:185], 0
	v_mfma_f32_16x16x32_bf16 v[114:117], v[174:177], v[182:185], 0
	v_mfma_f32_16x16x32_bf16 v[102:105], v[162:165], v[190:193], 0
	v_mfma_f32_16x16x32_bf16 v[98:101], v[174:177], v[190:193], 0
	v_mfma_f32_16x16x32_bf16 v[86:89], v[162:165], v[198:201], 0
	v_mfma_f32_16x16x32_bf16 v[82:85], v[174:177], v[198:201], 0
	v_mfma_f32_16x16x32_bf16 v[70:73], v[162:165], v[206:209], 0
	v_mfma_f32_16x16x32_bf16 v[66:69], v[174:177], v[206:209], 0
	v_mfma_f32_16x16x32_bf16 v[118:121], v[170:173], v[186:189], v[118:121]
	v_mfma_f32_16x16x32_bf16 v[114:117], v[178:181], v[186:189], v[114:117]
	v_mfma_f32_16x16x32_bf16 v[102:105], v[170:173], v[194:197], v[102:105]
	v_mfma_f32_16x16x32_bf16 v[98:101], v[178:181], v[194:197], v[98:101]
	v_mfma_f32_16x16x32_bf16 v[86:89], v[170:173], v[202:205], v[86:89]
	v_mfma_f32_16x16x32_bf16 v[82:85], v[178:181], v[202:205], v[82:85]
	v_mfma_f32_16x16x32_bf16 v[70:73], v[170:173], v[224:227], v[70:73]
	v_mfma_f32_16x16x32_bf16 v[66:69], v[178:181], v[224:227], v[66:69]
	s_setprio 0
	s_barrier
	s_add_i32 s64, s64, s71
	v_lshl_add_u64 v[210:211], s[56:57], 0, v[142:143]
	s_mov_b32 m0, s64
	ds_read_b128 v[182:185], v169 offset:16384
	ds_read_b128 v[186:189], v169 offset:17408
	ds_read_b128 v[190:193], v169 offset:18432
	ds_read_b128 v[194:197], v169 offset:19456
	ds_read_b128 v[198:201], v169 offset:20480
	ds_read_b128 v[202:205], v169 offset:21504
	ds_read_b128 v[206:209], v169 offset:22528
	ds_read_b128 v[224:227], v169 offset:23552
	global_load_lds_dwordx4 v[210:211], off
	s_add_i32 m0, s64, 0x2000
	s_add_u32 s64, s56, 0x40000
	v_lshl_add_u64 v[228:229], s[56:57], 0, v[138:139]
	s_addc_u32 s65, s57, 0
	s_add_i32 s86, s86, s71
	global_load_lds_dwordx4 v[228:229], off
	v_lshl_add_u64 v[230:231], s[64:65], 0, v[142:143]
	s_mov_b32 m0, s86
	v_lshl_add_u64 v[232:233], s[68:69], 0, v[140:141]
	global_load_lds_dwordx4 v[230:231], off
	v_lshl_add_u64 v[230:231], s[64:65], 0, v[138:139]
	s_add_i32 m0, s86, 0x2000
	s_nop 0
	global_load_lds_dwordx4 v[230:231], off
	v_lshl_add_u64 v[230:231], s[68:69], 0, v[144:145]
	s_mov_b32 m0, s21
	s_nop 0
	global_load_lds_dwordx4 v[230:231], off
	s_mov_b32 m0, s73
	s_nop 0
	global_load_lds_dwordx4 v[232:233], off
	s_waitcnt vmcnt(8)
	s_waitcnt lgkmcnt(0)
	s_setprio 3
	s_barrier
	s_waitcnt lgkmcnt(0)
	v_mfma_f32_16x16x32_bf16 v[62:65], v[134:137], v[182:185], 0
	v_mfma_f32_16x16x32_bf16 v[58:61], v[154:157], v[182:185], 0
	v_mfma_f32_16x16x32_bf16 v[46:49], v[134:137], v[190:193], 0
	v_mfma_f32_16x16x32_bf16 v[42:45], v[154:157], v[190:193], 0
	v_mfma_f32_16x16x32_bf16 v[30:33], v[134:137], v[198:201], 0
	v_mfma_f32_16x16x32_bf16 v[26:29], v[154:157], v[198:201], 0
	v_mfma_f32_16x16x32_bf16 v[14:17], v[134:137], v[206:209], 0
	v_mfma_f32_16x16x32_bf16 v[10:13], v[154:157], v[206:209], 0
	v_mfma_f32_16x16x32_bf16 v[62:65], v[150:153], v[186:189], v[62:65]
	v_mfma_f32_16x16x32_bf16 v[58:61], v[158:161], v[186:189], v[58:61]
	v_mfma_f32_16x16x32_bf16 v[46:49], v[150:153], v[194:197], v[46:49]
	v_mfma_f32_16x16x32_bf16 v[42:45], v[158:161], v[194:197], v[42:45]
	v_mfma_f32_16x16x32_bf16 v[30:33], v[150:153], v[202:205], v[30:33]
	v_mfma_f32_16x16x32_bf16 v[26:29], v[158:161], v[202:205], v[26:29]
	v_mfma_f32_16x16x32_bf16 v[14:17], v[150:153], v[224:227], v[14:17]
	v_mfma_f32_16x16x32_bf16 v[10:13], v[158:161], v[224:227], v[10:13]
	v_mfma_f32_16x16x32_bf16 v[54:57], v[162:165], v[182:185], 0
	v_mfma_f32_16x16x32_bf16 v[50:53], v[174:177], v[182:185], 0
	v_mfma_f32_16x16x32_bf16 v[38:41], v[162:165], v[190:193], 0
	v_mfma_f32_16x16x32_bf16 v[34:37], v[174:177], v[190:193], 0
	v_mfma_f32_16x16x32_bf16 v[22:25], v[162:165], v[198:201], 0
	v_mfma_f32_16x16x32_bf16 v[18:21], v[174:177], v[198:201], 0
	v_mfma_f32_16x16x32_bf16 v[6:9], v[162:165], v[206:209], 0
	v_mfma_f32_16x16x32_bf16 v[2:5], v[174:177], v[206:209], 0
	v_mfma_f32_16x16x32_bf16 v[54:57], v[170:173], v[186:189], v[54:57]
	v_mfma_f32_16x16x32_bf16 v[50:53], v[178:181], v[186:189], v[50:53]
	v_mfma_f32_16x16x32_bf16 v[38:41], v[170:173], v[194:197], v[38:41]
	v_mfma_f32_16x16x32_bf16 v[34:37], v[178:181], v[194:197], v[34:37]
	v_mfma_f32_16x16x32_bf16 v[22:25], v[170:173], v[202:205], v[22:25]
	v_mfma_f32_16x16x32_bf16 v[18:21], v[178:181], v[202:205], v[18:21]
	v_mfma_f32_16x16x32_bf16 v[6:9], v[170:173], v[224:227], v[6:9]
	v_mfma_f32_16x16x32_bf16 v[2:5], v[178:181], v[224:227], v[2:5]
	s_setprio 0
	s_barrier
	s_add_i32 s86, 0, 0x18000
	v_add_u32_e32 v0, s86, v167
	s_add_i32 s87, 0, 0x1c000
	ds_read_b128 v[134:137], v0
	ds_read_b128 v[150:153], v0 offset:1024
	ds_read_b128 v[154:157], v0 offset:2048
	ds_read_b128 v[158:161], v0 offset:3072
	v_add_u32_e32 v0, s87, v167
	ds_read_b128 v[162:165], v0
	ds_read_b128 v[170:173], v0 offset:1024
	ds_read_b128 v[174:177], v0 offset:2048
	ds_read_b128 v[178:181], v0 offset:3072
	s_add_u32 s64, s68, 0x40000
	s_addc_u32 s65, s69, 0
	s_mov_b32 m0, s74
	v_lshl_add_u64 v[234:235], s[64:65], 0, v[144:145]
	ds_read_b128 v[182:185], v169 offset:32768
	ds_read_b128 v[186:189], v169 offset:33792
	ds_read_b128 v[190:193], v169 offset:34816
	ds_read_b128 v[194:197], v169 offset:35840
	ds_read_b128 v[198:201], v169 offset:36864
	ds_read_b128 v[202:205], v169 offset:37888
	ds_read_b128 v[206:209], v169 offset:38912
	ds_read_b128 v[224:227], v169 offset:39936
	global_load_lds_dwordx4 v[234:235], off
	v_lshl_add_u64 v[234:235], s[64:65], 0, v[140:141]
	s_mov_b32 m0, s75
	s_nop 0
	global_load_lds_dwordx4 v[234:235], off
	s_waitcnt vmcnt(8)
	s_waitcnt lgkmcnt(0)
	s_setprio 3
	s_barrier
	s_waitcnt lgkmcnt(0)
	v_mfma_f32_16x16x32_bf16 v[126:129], v[134:137], v[182:185], v[126:129]
	v_mfma_f32_16x16x32_bf16 v[122:125], v[154:157], v[182:185], v[122:125]
	v_mfma_f32_16x16x32_bf16 v[110:113], v[134:137], v[190:193], v[110:113]
	v_mfma_f32_16x16x32_bf16 v[106:109], v[154:157], v[190:193], v[106:109]
	v_mfma_f32_16x16x32_bf16 v[94:97], v[134:137], v[198:201], v[94:97]
	v_mfma_f32_16x16x32_bf16 v[90:93], v[154:157], v[198:201], v[90:93]
	v_mfma_f32_16x16x32_bf16 v[78:81], v[134:137], v[206:209], v[78:81]
	v_mfma_f32_16x16x32_bf16 v[74:77], v[154:157], v[206:209], v[74:77]
	v_mfma_f32_16x16x32_bf16 v[126:129], v[150:153], v[186:189], v[126:129]
	v_mfma_f32_16x16x32_bf16 v[122:125], v[158:161], v[186:189], v[122:125]
	v_mfma_f32_16x16x32_bf16 v[110:113], v[150:153], v[194:197], v[110:113]
	v_mfma_f32_16x16x32_bf16 v[106:109], v[158:161], v[194:197], v[106:109]
	v_mfma_f32_16x16x32_bf16 v[94:97], v[150:153], v[202:205], v[94:97]
	v_mfma_f32_16x16x32_bf16 v[90:93], v[158:161], v[202:205], v[90:93]
	v_mfma_f32_16x16x32_bf16 v[78:81], v[150:153], v[224:227], v[78:81]
	v_mfma_f32_16x16x32_bf16 v[74:77], v[158:161], v[224:227], v[74:77]
	v_mfma_f32_16x16x32_bf16 v[118:121], v[162:165], v[182:185], v[118:121]
	v_mfma_f32_16x16x32_bf16 v[114:117], v[174:177], v[182:185], v[114:117]
	v_mfma_f32_16x16x32_bf16 v[102:105], v[162:165], v[190:193], v[102:105]
	v_mfma_f32_16x16x32_bf16 v[98:101], v[174:177], v[190:193], v[98:101]
	v_mfma_f32_16x16x32_bf16 v[86:89], v[162:165], v[198:201], v[86:89]
	v_mfma_f32_16x16x32_bf16 v[82:85], v[174:177], v[198:201], v[82:85]
	v_mfma_f32_16x16x32_bf16 v[70:73], v[162:165], v[206:209], v[70:73]
	v_mfma_f32_16x16x32_bf16 v[66:69], v[174:177], v[206:209], v[66:69]
	v_mfma_f32_16x16x32_bf16 v[118:121], v[170:173], v[186:189], v[118:121]
	v_mfma_f32_16x16x32_bf16 v[114:117], v[178:181], v[186:189], v[114:117]
	v_mfma_f32_16x16x32_bf16 v[102:105], v[170:173], v[194:197], v[102:105]
	v_mfma_f32_16x16x32_bf16 v[98:101], v[178:181], v[194:197], v[98:101]
	v_mfma_f32_16x16x32_bf16 v[86:89], v[170:173], v[202:205], v[86:89]
	v_mfma_f32_16x16x32_bf16 v[82:85], v[178:181], v[202:205], v[82:85]
	v_mfma_f32_16x16x32_bf16 v[70:73], v[170:173], v[224:227], v[70:73]
	v_mfma_f32_16x16x32_bf16 v[66:69], v[178:181], v[224:227], v[66:69]
	s_setprio 0
	s_barrier
	s_add_i32 s64, s86, s71
	v_lshl_add_u64 v[210:211], v[210:211], 0, s[48:49]
	s_mov_b32 m0, s64
	ds_read_b128 v[182:185], v169 offset:49152
	ds_read_b128 v[186:189], v169 offset:50176
	ds_read_b128 v[190:193], v169 offset:51200
	ds_read_b128 v[194:197], v169 offset:52224
	ds_read_b128 v[198:201], v169 offset:53248
	ds_read_b128 v[202:205], v169 offset:54272
	ds_read_b128 v[206:209], v169 offset:55296
	ds_read_b128 v[224:227], v169 offset:56320
	global_load_lds_dwordx4 v[210:211], off
	s_add_i32 m0, s64, 0x2000
	s_add_u32 s56, s56, 0x40080
	v_lshl_add_u64 v[210:211], v[228:229], 0, s[48:49]
	s_addc_u32 s57, s57, 0
	s_add_i32 s64, s87, s71
	global_load_lds_dwordx4 v[210:211], off
	v_lshl_add_u64 v[210:211], s[56:57], 0, v[142:143]
	s_mov_b32 m0, s64
	s_nop 0
	global_load_lds_dwordx4 v[210:211], off
	v_lshl_add_u64 v[210:211], s[56:57], 0, v[138:139]
	s_add_i32 m0, s64, 0x2000
	s_nop 0
	global_load_lds_dwordx4 v[210:211], off
	v_lshl_add_u64 v[210:211], v[230:231], 0, s[48:49]
	s_mov_b32 m0, s80
	s_nop 0
	global_load_lds_dwordx4 v[210:211], off
	v_lshl_add_u64 v[210:211], v[232:233], 0, s[48:49]
	s_mov_b32 m0, s81
	s_nop 0
	global_load_lds_dwordx4 v[210:211], off
	s_waitcnt vmcnt(8)
	s_waitcnt lgkmcnt(0)
	s_setprio 3
	s_barrier
	s_waitcnt lgkmcnt(0)
	v_mfma_f32_16x16x32_bf16 v[62:65], v[134:137], v[182:185], v[62:65]
	v_mfma_f32_16x16x32_bf16 v[58:61], v[154:157], v[182:185], v[58:61]
	v_mfma_f32_16x16x32_bf16 v[46:49], v[134:137], v[190:193], v[46:49]
	v_mfma_f32_16x16x32_bf16 v[42:45], v[154:157], v[190:193], v[42:45]
	v_mfma_f32_16x16x32_bf16 v[30:33], v[134:137], v[198:201], v[30:33]
	v_mfma_f32_16x16x32_bf16 v[26:29], v[154:157], v[198:201], v[26:29]
	v_mfma_f32_16x16x32_bf16 v[14:17], v[134:137], v[206:209], v[14:17]
	v_mfma_f32_16x16x32_bf16 v[10:13], v[154:157], v[206:209], v[10:13]
	v_mfma_f32_16x16x32_bf16 v[62:65], v[150:153], v[186:189], v[62:65]
	v_mfma_f32_16x16x32_bf16 v[58:61], v[158:161], v[186:189], v[58:61]
	v_mfma_f32_16x16x32_bf16 v[46:49], v[150:153], v[194:197], v[46:49]
	v_mfma_f32_16x16x32_bf16 v[42:45], v[158:161], v[194:197], v[42:45]
	v_mfma_f32_16x16x32_bf16 v[30:33], v[150:153], v[202:205], v[30:33]
	v_mfma_f32_16x16x32_bf16 v[26:29], v[158:161], v[202:205], v[26:29]
	v_mfma_f32_16x16x32_bf16 v[14:17], v[150:153], v[224:227], v[14:17]
	v_mfma_f32_16x16x32_bf16 v[10:13], v[158:161], v[224:227], v[10:13]
	v_mfma_f32_16x16x32_bf16 v[54:57], v[162:165], v[182:185], v[54:57]
	v_mfma_f32_16x16x32_bf16 v[50:53], v[174:177], v[182:185], v[50:53]
	v_mfma_f32_16x16x32_bf16 v[38:41], v[162:165], v[190:193], v[38:41]
	v_mfma_f32_16x16x32_bf16 v[34:37], v[174:177], v[190:193], v[34:37]
	v_mfma_f32_16x16x32_bf16 v[22:25], v[162:165], v[198:201], v[22:25]
	v_mfma_f32_16x16x32_bf16 v[18:21], v[174:177], v[198:201], v[18:21]
	v_mfma_f32_16x16x32_bf16 v[6:9], v[162:165], v[206:209], v[6:9]
	v_mfma_f32_16x16x32_bf16 v[2:5], v[174:177], v[206:209], v[2:5]
	v_mfma_f32_16x16x32_bf16 v[54:57], v[170:173], v[186:189], v[54:57]
	v_mfma_f32_16x16x32_bf16 v[50:53], v[178:181], v[186:189], v[50:53]
	v_mfma_f32_16x16x32_bf16 v[38:41], v[170:173], v[194:197], v[38:41]
	v_mfma_f32_16x16x32_bf16 v[34:37], v[178:181], v[194:197], v[34:37]
	v_mfma_f32_16x16x32_bf16 v[22:25], v[170:173], v[202:205], v[22:25]
	v_mfma_f32_16x16x32_bf16 v[18:21], v[178:181], v[202:205], v[18:21]
	v_mfma_f32_16x16x32_bf16 v[6:9], v[170:173], v[224:227], v[6:9]
	v_mfma_f32_16x16x32_bf16 v[2:5], v[178:181], v[224:227], v[2:5]
	s_setprio 0
	s_barrier
	s_add_i32 s85, s85, 2
	s_add_u32 s52, s52, 0x100
	s_addc_u32 s53, s53, 0
	s_add_u32 s31, s31, 0x100
	s_addc_u32 s84, s84, 0
.LBB0_1459:
	s_add_u32 s56, s52, 0xfffc0080
	s_addc_u32 s57, s53, -1
	s_add_i32 s64, 0, 0x10000
	s_cmp_eq_u32 s85, 12
	s_cselect_b32 s69, s13, s57
	s_cselect_b32 s68, s27, s56
	v_add_u32_e32 v0, s64, v167
	s_cselect_b32 s57, s11, s84
	s_cselect_b32 s56, s30, s31
	s_add_i32 s86, 0, 0x14000
	ds_read_b128 v[134:137], v0
	ds_read_b128 v[150:153], v0 offset:1024
	ds_read_b128 v[154:157], v0 offset:2048
	ds_read_b128 v[158:161], v0 offset:3072
	v_add_u32_e32 v0, s86, v167
	ds_read_b128 v[162:165], v0
	ds_read_b128 v[170:173], v0 offset:1024
	ds_read_b128 v[174:177], v0 offset:2048
	ds_read_b128 v[178:181], v0 offset:3072
	v_lshl_add_u64 v[210:211], s[52:53], 0, v[146:147]
	s_add_i32 m0, s21, 0xc000
	ds_read_b128 v[182:185], v169
	ds_read_b128 v[186:189], v169 offset:1024
	ds_read_b128 v[190:193], v169 offset:2048
	ds_read_b128 v[194:197], v169 offset:3072
	ds_read_b128 v[198:201], v169 offset:4096
	ds_read_b128 v[202:205], v169 offset:5120
	ds_read_b128 v[206:209], v169 offset:6144
	ds_read_b128 v[224:227], v169 offset:7168
	global_load_lds_dwordx4 v[210:211], off
	v_lshl_add_u64 v[210:211], s[52:53], 0, v[148:149]
	s_add_i32 m0, s21, 0xe000
	s_nop 0
	global_load_lds_dwordx4 v[210:211], off
	s_waitcnt vmcnt(8)
	s_waitcnt lgkmcnt(0)
	s_setprio 3
	s_barrier
	s_waitcnt lgkmcnt(0)
	v_mfma_f32_16x16x32_bf16 v[126:129], v[134:137], v[182:185], v[126:129]
	v_mfma_f32_16x16x32_bf16 v[122:125], v[154:157], v[182:185], v[122:125]
	v_mfma_f32_16x16x32_bf16 v[110:113], v[134:137], v[190:193], v[110:113]
	v_mfma_f32_16x16x32_bf16 v[106:109], v[154:157], v[190:193], v[106:109]
	v_mfma_f32_16x16x32_bf16 v[94:97], v[134:137], v[198:201], v[94:97]
	v_mfma_f32_16x16x32_bf16 v[90:93], v[154:157], v[198:201], v[90:93]
	v_mfma_f32_16x16x32_bf16 v[78:81], v[134:137], v[206:209], v[78:81]
	v_mfma_f32_16x16x32_bf16 v[74:77], v[154:157], v[206:209], v[74:77]
	v_mfma_f32_16x16x32_bf16 v[126:129], v[150:153], v[186:189], v[126:129]
	v_mfma_f32_16x16x32_bf16 v[122:125], v[158:161], v[186:189], v[122:125]
	v_mfma_f32_16x16x32_bf16 v[110:113], v[150:153], v[194:197], v[110:113]
	v_mfma_f32_16x16x32_bf16 v[106:109], v[158:161], v[194:197], v[106:109]
	v_mfma_f32_16x16x32_bf16 v[94:97], v[150:153], v[202:205], v[94:97]
	v_mfma_f32_16x16x32_bf16 v[90:93], v[158:161], v[202:205], v[90:93]
	v_mfma_f32_16x16x32_bf16 v[78:81], v[150:153], v[224:227], v[78:81]
	v_mfma_f32_16x16x32_bf16 v[74:77], v[158:161], v[224:227], v[74:77]
	v_mfma_f32_16x16x32_bf16 v[118:121], v[162:165], v[182:185], v[118:121]
	v_mfma_f32_16x16x32_bf16 v[114:117], v[174:177], v[182:185], v[114:117]
	v_mfma_f32_16x16x32_bf16 v[102:105], v[162:165], v[190:193], v[102:105]
	v_mfma_f32_16x16x32_bf16 v[98:101], v[174:177], v[190:193], v[98:101]
	v_mfma_f32_16x16x32_bf16 v[86:89], v[162:165], v[198:201], v[86:89]
	v_mfma_f32_16x16x32_bf16 v[82:85], v[174:177], v[198:201], v[82:85]
	v_mfma_f32_16x16x32_bf16 v[70:73], v[162:165], v[206:209], v[70:73]
	v_mfma_f32_16x16x32_bf16 v[66:69], v[174:177], v[206:209], v[66:69]
	v_mfma_f32_16x16x32_bf16 v[118:121], v[170:173], v[186:189], v[118:121]
	v_mfma_f32_16x16x32_bf16 v[114:117], v[178:181], v[186:189], v[114:117]
	v_mfma_f32_16x16x32_bf16 v[102:105], v[170:173], v[194:197], v[102:105]
	v_mfma_f32_16x16x32_bf16 v[98:101], v[178:181], v[194:197], v[98:101]
	v_mfma_f32_16x16x32_bf16 v[86:89], v[170:173], v[202:205], v[86:89]
	v_mfma_f32_16x16x32_bf16 v[82:85], v[178:181], v[202:205], v[82:85]
	v_mfma_f32_16x16x32_bf16 v[70:73], v[170:173], v[224:227], v[70:73]
	v_mfma_f32_16x16x32_bf16 v[66:69], v[178:181], v[224:227], v[66:69]
	s_setprio 0
	s_barrier
	s_add_i32 s64, s64, s71
	v_lshl_add_u64 v[210:211], s[56:57], 0, v[142:143]
	s_mov_b32 m0, s64
	ds_read_b128 v[182:185], v169 offset:16384
	ds_read_b128 v[186:189], v169 offset:17408
	ds_read_b128 v[190:193], v169 offset:18432
	ds_read_b128 v[194:197], v169 offset:19456
	ds_read_b128 v[198:201], v169 offset:20480
	ds_read_b128 v[202:205], v169 offset:21504
	ds_read_b128 v[206:209], v169 offset:22528
	ds_read_b128 v[224:227], v169 offset:23552
	global_load_lds_dwordx4 v[210:211], off
	s_add_i32 m0, s64, 0x2000
	s_add_u32 s64, s56, 0x40000
	v_lshl_add_u64 v[228:229], s[56:57], 0, v[138:139]
	s_addc_u32 s65, s57, 0
	s_add_i32 s86, s86, s71
	global_load_lds_dwordx4 v[228:229], off
	v_lshl_add_u64 v[230:231], s[64:65], 0, v[142:143]
	s_mov_b32 m0, s86
	v_lshl_add_u64 v[232:233], s[68:69], 0, v[140:141]
	global_load_lds_dwordx4 v[230:231], off
	v_lshl_add_u64 v[230:231], s[64:65], 0, v[138:139]
	s_add_i32 m0, s86, 0x2000
	s_nop 0
	global_load_lds_dwordx4 v[230:231], off
	v_lshl_add_u64 v[230:231], s[68:69], 0, v[144:145]
	s_mov_b32 m0, s21
	s_nop 0
	global_load_lds_dwordx4 v[230:231], off
	s_mov_b32 m0, s73
	s_nop 0
	global_load_lds_dwordx4 v[232:233], off
	s_waitcnt vmcnt(8)
	s_waitcnt lgkmcnt(0)
	s_setprio 3
	s_barrier
	s_waitcnt lgkmcnt(0)
	v_mfma_f32_16x16x32_bf16 v[62:65], v[134:137], v[182:185], v[62:65]
	v_mfma_f32_16x16x32_bf16 v[58:61], v[154:157], v[182:185], v[58:61]
	v_mfma_f32_16x16x32_bf16 v[46:49], v[134:137], v[190:193], v[46:49]
	v_mfma_f32_16x16x32_bf16 v[42:45], v[154:157], v[190:193], v[42:45]
	v_mfma_f32_16x16x32_bf16 v[30:33], v[134:137], v[198:201], v[30:33]
	v_mfma_f32_16x16x32_bf16 v[26:29], v[154:157], v[198:201], v[26:29]
	v_mfma_f32_16x16x32_bf16 v[14:17], v[134:137], v[206:209], v[14:17]
	v_mfma_f32_16x16x32_bf16 v[10:13], v[154:157], v[206:209], v[10:13]
	v_mfma_f32_16x16x32_bf16 v[62:65], v[150:153], v[186:189], v[62:65]
	v_mfma_f32_16x16x32_bf16 v[58:61], v[158:161], v[186:189], v[58:61]
	v_mfma_f32_16x16x32_bf16 v[46:49], v[150:153], v[194:197], v[46:49]
	v_mfma_f32_16x16x32_bf16 v[42:45], v[158:161], v[194:197], v[42:45]
	v_mfma_f32_16x16x32_bf16 v[30:33], v[150:153], v[202:205], v[30:33]
	v_mfma_f32_16x16x32_bf16 v[26:29], v[158:161], v[202:205], v[26:29]
	v_mfma_f32_16x16x32_bf16 v[14:17], v[150:153], v[224:227], v[14:17]
	v_mfma_f32_16x16x32_bf16 v[10:13], v[158:161], v[224:227], v[10:13]
	v_mfma_f32_16x16x32_bf16 v[54:57], v[162:165], v[182:185], v[54:57]
	v_mfma_f32_16x16x32_bf16 v[50:53], v[174:177], v[182:185], v[50:53]
	v_mfma_f32_16x16x32_bf16 v[38:41], v[162:165], v[190:193], v[38:41]
	v_mfma_f32_16x16x32_bf16 v[34:37], v[174:177], v[190:193], v[34:37]
	v_mfma_f32_16x16x32_bf16 v[22:25], v[162:165], v[198:201], v[22:25]
	v_mfma_f32_16x16x32_bf16 v[18:21], v[174:177], v[198:201], v[18:21]
	v_mfma_f32_16x16x32_bf16 v[6:9], v[162:165], v[206:209], v[6:9]
	v_mfma_f32_16x16x32_bf16 v[2:5], v[174:177], v[206:209], v[2:5]
	v_mfma_f32_16x16x32_bf16 v[54:57], v[170:173], v[186:189], v[54:57]
	v_mfma_f32_16x16x32_bf16 v[50:53], v[178:181], v[186:189], v[50:53]
	v_mfma_f32_16x16x32_bf16 v[38:41], v[170:173], v[194:197], v[38:41]
	v_mfma_f32_16x16x32_bf16 v[34:37], v[178:181], v[194:197], v[34:37]
	v_mfma_f32_16x16x32_bf16 v[22:25], v[170:173], v[202:205], v[22:25]
	v_mfma_f32_16x16x32_bf16 v[18:21], v[178:181], v[202:205], v[18:21]
	v_mfma_f32_16x16x32_bf16 v[6:9], v[170:173], v[224:227], v[6:9]
	v_mfma_f32_16x16x32_bf16 v[2:5], v[178:181], v[224:227], v[2:5]
	s_setprio 0
	s_barrier
	s_add_i32 s86, 0, 0x18000
	v_add_u32_e32 v0, s86, v167
	s_add_i32 s87, 0, 0x1c000
	ds_read_b128 v[134:137], v0
	ds_read_b128 v[150:153], v0 offset:1024
	ds_read_b128 v[154:157], v0 offset:2048
	ds_read_b128 v[158:161], v0 offset:3072
	v_add_u32_e32 v0, s87, v167
	ds_read_b128 v[162:165], v0
	ds_read_b128 v[170:173], v0 offset:1024
	ds_read_b128 v[174:177], v0 offset:2048
	ds_read_b128 v[178:181], v0 offset:3072
	s_add_u32 s64, s68, 0x40000
	s_addc_u32 s65, s69, 0
	s_mov_b32 m0, s74
	v_lshl_add_u64 v[234:235], s[64:65], 0, v[144:145]
	ds_read_b128 v[182:185], v169 offset:32768
	ds_read_b128 v[186:189], v169 offset:33792
	ds_read_b128 v[190:193], v169 offset:34816
	ds_read_b128 v[194:197], v169 offset:35840
	ds_read_b128 v[198:201], v169 offset:36864
	ds_read_b128 v[202:205], v169 offset:37888
	ds_read_b128 v[206:209], v169 offset:38912
	ds_read_b128 v[224:227], v169 offset:39936
	global_load_lds_dwordx4 v[234:235], off
	v_lshl_add_u64 v[234:235], s[64:65], 0, v[140:141]
	s_mov_b32 m0, s75
	s_nop 0
	global_load_lds_dwordx4 v[234:235], off
	s_waitcnt vmcnt(8)
	s_waitcnt lgkmcnt(0)
	s_setprio 3
	s_barrier
	s_waitcnt lgkmcnt(0)
	v_mfma_f32_16x16x32_bf16 v[126:129], v[134:137], v[182:185], v[126:129]
	v_mfma_f32_16x16x32_bf16 v[122:125], v[154:157], v[182:185], v[122:125]
	v_mfma_f32_16x16x32_bf16 v[110:113], v[134:137], v[190:193], v[110:113]
	v_mfma_f32_16x16x32_bf16 v[106:109], v[154:157], v[190:193], v[106:109]
	v_mfma_f32_16x16x32_bf16 v[94:97], v[134:137], v[198:201], v[94:97]
	v_mfma_f32_16x16x32_bf16 v[90:93], v[154:157], v[198:201], v[90:93]
	v_mfma_f32_16x16x32_bf16 v[78:81], v[134:137], v[206:209], v[78:81]
	v_mfma_f32_16x16x32_bf16 v[74:77], v[154:157], v[206:209], v[74:77]
	v_mfma_f32_16x16x32_bf16 v[126:129], v[150:153], v[186:189], v[126:129]
	v_mfma_f32_16x16x32_bf16 v[122:125], v[158:161], v[186:189], v[122:125]
	v_mfma_f32_16x16x32_bf16 v[110:113], v[150:153], v[194:197], v[110:113]
	v_mfma_f32_16x16x32_bf16 v[106:109], v[158:161], v[194:197], v[106:109]
	v_mfma_f32_16x16x32_bf16 v[94:97], v[150:153], v[202:205], v[94:97]
	v_mfma_f32_16x16x32_bf16 v[90:93], v[158:161], v[202:205], v[90:93]
	v_mfma_f32_16x16x32_bf16 v[78:81], v[150:153], v[224:227], v[78:81]
	v_mfma_f32_16x16x32_bf16 v[74:77], v[158:161], v[224:227], v[74:77]
	v_mfma_f32_16x16x32_bf16 v[118:121], v[162:165], v[182:185], v[118:121]
	v_mfma_f32_16x16x32_bf16 v[114:117], v[174:177], v[182:185], v[114:117]
	v_mfma_f32_16x16x32_bf16 v[102:105], v[162:165], v[190:193], v[102:105]
	v_mfma_f32_16x16x32_bf16 v[98:101], v[174:177], v[190:193], v[98:101]
	v_mfma_f32_16x16x32_bf16 v[86:89], v[162:165], v[198:201], v[86:89]
	v_mfma_f32_16x16x32_bf16 v[82:85], v[174:177], v[198:201], v[82:85]
	v_mfma_f32_16x16x32_bf16 v[70:73], v[162:165], v[206:209], v[70:73]
	v_mfma_f32_16x16x32_bf16 v[66:69], v[174:177], v[206:209], v[66:69]
	v_mfma_f32_16x16x32_bf16 v[118:121], v[170:173], v[186:189], v[118:121]
	v_mfma_f32_16x16x32_bf16 v[114:117], v[178:181], v[186:189], v[114:117]
	v_mfma_f32_16x16x32_bf16 v[102:105], v[170:173], v[194:197], v[102:105]
	v_mfma_f32_16x16x32_bf16 v[98:101], v[178:181], v[194:197], v[98:101]
	v_mfma_f32_16x16x32_bf16 v[86:89], v[170:173], v[202:205], v[86:89]
	v_mfma_f32_16x16x32_bf16 v[82:85], v[178:181], v[202:205], v[82:85]
	v_mfma_f32_16x16x32_bf16 v[70:73], v[170:173], v[224:227], v[70:73]
	v_mfma_f32_16x16x32_bf16 v[66:69], v[178:181], v[224:227], v[66:69]
	s_setprio 0
	s_barrier
	s_add_i32 s64, s86, s71
	v_lshl_add_u64 v[210:211], v[210:211], 0, s[48:49]
	s_mov_b32 m0, s64
	ds_read_b128 v[182:185], v169 offset:49152
	ds_read_b128 v[186:189], v169 offset:50176
	ds_read_b128 v[190:193], v169 offset:51200
	ds_read_b128 v[194:197], v169 offset:52224
	ds_read_b128 v[198:201], v169 offset:53248
	ds_read_b128 v[202:205], v169 offset:54272
	ds_read_b128 v[206:209], v169 offset:55296
	ds_read_b128 v[224:227], v169 offset:56320
	global_load_lds_dwordx4 v[210:211], off
	s_add_i32 m0, s64, 0x2000
	s_add_u32 s56, s56, 0x40080
	v_lshl_add_u64 v[210:211], v[228:229], 0, s[48:49]
	s_addc_u32 s57, s57, 0
	s_add_i32 s64, s87, s71
	global_load_lds_dwordx4 v[210:211], off
	v_lshl_add_u64 v[210:211], s[56:57], 0, v[142:143]
	s_mov_b32 m0, s64
	s_nop 0
	global_load_lds_dwordx4 v[210:211], off
	v_lshl_add_u64 v[210:211], s[56:57], 0, v[138:139]
	s_add_i32 m0, s64, 0x2000
	s_nop 0
	global_load_lds_dwordx4 v[210:211], off
	v_lshl_add_u64 v[210:211], v[230:231], 0, s[48:49]
	s_mov_b32 m0, s80
	s_nop 0
	global_load_lds_dwordx4 v[210:211], off
	v_lshl_add_u64 v[210:211], v[232:233], 0, s[48:49]
	s_mov_b32 m0, s81
	s_nop 0
	global_load_lds_dwordx4 v[210:211], off
	s_waitcnt vmcnt(8)
	s_waitcnt lgkmcnt(0)
	s_setprio 3
	s_barrier
	s_waitcnt lgkmcnt(0)
	v_mfma_f32_16x16x32_bf16 v[62:65], v[134:137], v[182:185], v[62:65]
	v_mfma_f32_16x16x32_bf16 v[58:61], v[154:157], v[182:185], v[58:61]
	v_mfma_f32_16x16x32_bf16 v[46:49], v[134:137], v[190:193], v[46:49]
	v_mfma_f32_16x16x32_bf16 v[42:45], v[154:157], v[190:193], v[42:45]
	v_mfma_f32_16x16x32_bf16 v[30:33], v[134:137], v[198:201], v[30:33]
	v_mfma_f32_16x16x32_bf16 v[26:29], v[154:157], v[198:201], v[26:29]
	v_mfma_f32_16x16x32_bf16 v[14:17], v[134:137], v[206:209], v[14:17]
	v_mfma_f32_16x16x32_bf16 v[10:13], v[154:157], v[206:209], v[10:13]
	v_mfma_f32_16x16x32_bf16 v[62:65], v[150:153], v[186:189], v[62:65]
	v_mfma_f32_16x16x32_bf16 v[58:61], v[158:161], v[186:189], v[58:61]
	v_mfma_f32_16x16x32_bf16 v[46:49], v[150:153], v[194:197], v[46:49]
	v_mfma_f32_16x16x32_bf16 v[42:45], v[158:161], v[194:197], v[42:45]
	v_mfma_f32_16x16x32_bf16 v[30:33], v[150:153], v[202:205], v[30:33]
	v_mfma_f32_16x16x32_bf16 v[26:29], v[158:161], v[202:205], v[26:29]
	v_mfma_f32_16x16x32_bf16 v[14:17], v[150:153], v[224:227], v[14:17]
	v_mfma_f32_16x16x32_bf16 v[10:13], v[158:161], v[224:227], v[10:13]
	v_mfma_f32_16x16x32_bf16 v[54:57], v[162:165], v[182:185], v[54:57]
	v_mfma_f32_16x16x32_bf16 v[50:53], v[174:177], v[182:185], v[50:53]
	v_mfma_f32_16x16x32_bf16 v[38:41], v[162:165], v[190:193], v[38:41]
	v_mfma_f32_16x16x32_bf16 v[34:37], v[174:177], v[190:193], v[34:37]
	v_mfma_f32_16x16x32_bf16 v[22:25], v[162:165], v[198:201], v[22:25]
	v_mfma_f32_16x16x32_bf16 v[18:21], v[174:177], v[198:201], v[18:21]
	v_mfma_f32_16x16x32_bf16 v[6:9], v[162:165], v[206:209], v[6:9]
	v_mfma_f32_16x16x32_bf16 v[2:5], v[174:177], v[206:209], v[2:5]
	v_mfma_f32_16x16x32_bf16 v[54:57], v[170:173], v[186:189], v[54:57]
	v_mfma_f32_16x16x32_bf16 v[50:53], v[178:181], v[186:189], v[50:53]
	v_mfma_f32_16x16x32_bf16 v[38:41], v[170:173], v[194:197], v[38:41]
	v_mfma_f32_16x16x32_bf16 v[34:37], v[178:181], v[194:197], v[34:37]
	v_mfma_f32_16x16x32_bf16 v[22:25], v[170:173], v[202:205], v[22:25]
	v_mfma_f32_16x16x32_bf16 v[18:21], v[178:181], v[202:205], v[18:21]
	v_mfma_f32_16x16x32_bf16 v[6:9], v[170:173], v[224:227], v[6:9]
	v_mfma_f32_16x16x32_bf16 v[2:5], v[178:181], v[224:227], v[2:5]
	s_setprio 0
	s_barrier
	s_add_i32 s85, s85, 2
	s_add_u32 s52, s52, 0x100
	s_addc_u32 s53, s53, 0
	s_add_u32 s31, s31, 0x100
	s_addc_u32 s84, s84, 0
	s_cmp_gt_u32 s85, 13
	s_cbranch_scc0 .LBB0_1459
	s_and_b64 vcc, exec, s[6:7]
	s_cbranch_vccz .LBB0_1462
	s_barrier

.LBB0_1532:
	s_ashr_i32 s17, s16, 31
	s_lshl_b64 s[56:57], s[16:17], 18
	s_add_u32 s56, s37, s56
	s_addc_u32 s57, s60, s57
	s_and_b64 s[6:7], s[6:7], exec
	s_cselect_b32 s17, s57, s69
	s_cselect_b32 s19, s56, s68
	s_add_u32 s6, s70, 0x20080
	s_addc_u32 s7, s71, 0
	s_add_u32 s80, s68, 0x100
	s_addc_u32 s81, s69, 0
	s_mov_b32 s82, -2
	s_add_u32 s64, s6, 0xfffe0080
	s_addc_u32 s65, s7, -1
	s_add_i32 s83, 0, 0x10000
	s_cmp_eq_u32 s82, 4
	s_cselect_b32 s71, s53, s65
	s_cselect_b32 s70, s52, s64
	v_add_u32_e32 v144, s83, v147
	s_cselect_b32 s69, s17, s81
	s_cselect_b32 s68, s19, s80
	s_add_i32 s84, 0, 0x14000
	ds_read_b128 v[150:153], v144
	ds_read_b128 v[154:157], v144 offset:1024
	ds_read_b128 v[158:161], v144 offset:2048
	ds_read_b128 v[162:165], v144 offset:3072
	v_add_u32_e32 v144, s84, v147
	ds_read_b128 v[166:169], v144
	ds_read_b128 v[170:173], v144 offset:1024
	ds_read_b128 v[174:177], v144 offset:2048
	ds_read_b128 v[178:181], v144 offset:3072
	v_lshl_add_u64 v[144:145], s[6:7], 0, v[140:141]
	s_add_i32 m0, s21, 0xc000
	ds_read_b128 v[182:185], v149
	ds_read_b128 v[186:189], v149 offset:1024
	ds_read_b128 v[190:193], v149 offset:2048
	ds_read_b128 v[194:197], v149 offset:3072
	ds_read_b128 v[198:201], v149 offset:4096
	ds_read_b128 v[202:205], v149 offset:5120
	ds_read_b128 v[206:209], v149 offset:6144
	ds_read_b128 v[224:227], v149 offset:7168
	global_load_lds_dwordx4 v[144:145], off
	v_lshl_add_u64 v[144:145], s[6:7], 0, v[142:143]
	s_add_i32 m0, s21, 0xe000
	s_nop 0
	global_load_lds_dwordx4 v[144:145], off
	s_waitcnt vmcnt(8)
	s_waitcnt lgkmcnt(0)
	s_setprio 3
	s_barrier
	s_waitcnt lgkmcnt(0)
	v_mfma_f32_16x16x32_bf16 v[126:129], v[150:153], v[182:185], 0
	v_mfma_f32_16x16x32_bf16 v[122:125], v[158:161], v[182:185], 0
	v_mfma_f32_16x16x32_bf16 v[118:121], v[150:153], v[190:193], 0
	v_mfma_f32_16x16x32_bf16 v[110:113], v[158:161], v[190:193], 0
	v_mfma_f32_16x16x32_bf16 v[102:105], v[150:153], v[198:201], 0
	v_mfma_f32_16x16x32_bf16 v[94:97], v[158:161], v[198:201], 0
	v_mfma_f32_16x16x32_bf16 v[86:89], v[150:153], v[206:209], 0
	v_mfma_f32_16x16x32_bf16 v[78:81], v[158:161], v[206:209], 0
	v_mfma_f32_16x16x32_bf16 v[126:129], v[154:157], v[186:189], v[126:129]
	v_mfma_f32_16x16x32_bf16 v[122:125], v[162:165], v[186:189], v[122:125]
	v_mfma_f32_16x16x32_bf16 v[118:121], v[154:157], v[194:197], v[118:121]
	v_mfma_f32_16x16x32_bf16 v[110:113], v[162:165], v[194:197], v[110:113]
	v_mfma_f32_16x16x32_bf16 v[102:105], v[154:157], v[202:205], v[102:105]
	v_mfma_f32_16x16x32_bf16 v[94:97], v[162:165], v[202:205], v[94:97]
	v_mfma_f32_16x16x32_bf16 v[86:89], v[154:157], v[224:227], v[86:89]
	v_mfma_f32_16x16x32_bf16 v[78:81], v[162:165], v[224:227], v[78:81]
	v_mfma_f32_16x16x32_bf16 v[114:117], v[166:169], v[182:185], 0
	v_mfma_f32_16x16x32_bf16 v[106:109], v[174:177], v[182:185], 0
	v_mfma_f32_16x16x32_bf16 v[98:101], v[166:169], v[190:193], 0
	v_mfma_f32_16x16x32_bf16 v[90:93], v[174:177], v[190:193], 0
	v_mfma_f32_16x16x32_bf16 v[82:85], v[166:169], v[198:201], 0
	v_mfma_f32_16x16x32_bf16 v[74:77], v[174:177], v[198:201], 0
	v_mfma_f32_16x16x32_bf16 v[70:73], v[166:169], v[206:209], 0
	v_mfma_f32_16x16x32_bf16 v[66:69], v[174:177], v[206:209], 0
	v_mfma_f32_16x16x32_bf16 v[114:117], v[170:173], v[186:189], v[114:117]
	v_mfma_f32_16x16x32_bf16 v[106:109], v[178:181], v[186:189], v[106:109]
	v_mfma_f32_16x16x32_bf16 v[98:101], v[170:173], v[194:197], v[98:101]
	v_mfma_f32_16x16x32_bf16 v[90:93], v[178:181], v[194:197], v[90:93]
	v_mfma_f32_16x16x32_bf16 v[82:85], v[170:173], v[202:205], v[82:85]
	v_mfma_f32_16x16x32_bf16 v[74:77], v[178:181], v[202:205], v[74:77]
	v_mfma_f32_16x16x32_bf16 v[70:73], v[170:173], v[224:227], v[70:73]
	v_mfma_f32_16x16x32_bf16 v[66:69], v[178:181], v[224:227], v[66:69]
	s_setprio 0
	s_barrier
	s_add_i32 s64, s83, s63
	v_lshl_add_u64 v[144:145], s[68:69], 0, v[0:1]
	s_mov_b32 m0, s64
	ds_read_b128 v[182:185], v149 offset:16384
	ds_read_b128 v[186:189], v149 offset:17408
	ds_read_b128 v[190:193], v149 offset:18432
	ds_read_b128 v[194:197], v149 offset:19456
	ds_read_b128 v[198:201], v149 offset:20480
	ds_read_b128 v[202:205], v149 offset:21504
	ds_read_b128 v[206:209], v149 offset:22528
	ds_read_b128 v[224:227], v149 offset:23552
	global_load_lds_dwordx4 v[144:145], off
	s_add_i32 m0, s64, 0x2000
	s_add_u32 s64, s68, 0x20000
	v_lshl_add_u64 v[210:211], s[68:69], 0, v[134:135]
	s_addc_u32 s65, s69, 0
	s_add_i32 s83, s84, s63
	global_load_lds_dwordx4 v[210:211], off
	v_lshl_add_u64 v[220:221], s[64:65], 0, v[0:1]
	s_mov_b32 m0, s83
	v_lshl_add_u64 v[228:229], s[70:71], 0, v[136:137]
	global_load_lds_dwordx4 v[220:221], off
	v_lshl_add_u64 v[220:221], s[64:65], 0, v[134:135]
	s_add_i32 m0, s83, 0x2000
	s_nop 0
	global_load_lds_dwordx4 v[220:221], off
	v_lshl_add_u64 v[220:221], s[70:71], 0, v[138:139]
	s_mov_b32 m0, s21
	s_nop 0
	global_load_lds_dwordx4 v[220:221], off
	s_mov_b32 m0, s27
	s_nop 0
	global_load_lds_dwordx4 v[228:229], off
	s_waitcnt vmcnt(8)
	s_waitcnt lgkmcnt(0)
	s_setprio 3
	s_barrier
	s_waitcnt lgkmcnt(0)
	v_mfma_f32_16x16x32_bf16 v[62:65], v[150:153], v[182:185], 0
	v_mfma_f32_16x16x32_bf16 v[58:61], v[158:161], v[182:185], 0
	v_mfma_f32_16x16x32_bf16 v[54:57], v[150:153], v[190:193], 0
	v_mfma_f32_16x16x32_bf16 v[46:49], v[158:161], v[190:193], 0
	v_mfma_f32_16x16x32_bf16 v[38:41], v[150:153], v[198:201], 0
	v_mfma_f32_16x16x32_bf16 v[30:33], v[158:161], v[198:201], 0
	v_mfma_f32_16x16x32_bf16 v[22:25], v[150:153], v[206:209], 0
	v_mfma_f32_16x16x32_bf16 v[14:17], v[158:161], v[206:209], 0
	v_mfma_f32_16x16x32_bf16 v[62:65], v[154:157], v[186:189], v[62:65]
	v_mfma_f32_16x16x32_bf16 v[58:61], v[162:165], v[186:189], v[58:61]
	v_mfma_f32_16x16x32_bf16 v[54:57], v[154:157], v[194:197], v[54:57]
	v_mfma_f32_16x16x32_bf16 v[46:49], v[162:165], v[194:197], v[46:49]
	v_mfma_f32_16x16x32_bf16 v[38:41], v[154:157], v[202:205], v[38:41]
	v_mfma_f32_16x16x32_bf16 v[30:33], v[162:165], v[202:205], v[30:33]
	v_mfma_f32_16x16x32_bf16 v[22:25], v[154:157], v[224:227], v[22:25]
	v_mfma_f32_16x16x32_bf16 v[14:17], v[162:165], v[224:227], v[14:17]
	v_mfma_f32_16x16x32_bf16 v[50:53], v[166:169], v[182:185], 0
	v_mfma_f32_16x16x32_bf16 v[42:45], v[174:177], v[182:185], 0
	v_mfma_f32_16x16x32_bf16 v[34:37], v[166:169], v[190:193], 0
	v_mfma_f32_16x16x32_bf16 v[26:29], v[174:177], v[190:193], 0
	v_mfma_f32_16x16x32_bf16 v[18:21], v[166:169], v[198:201], 0
	v_mfma_f32_16x16x32_bf16 v[10:13], v[174:177], v[198:201], 0
	v_mfma_f32_16x16x32_bf16 v[6:9], v[166:169], v[206:209], 0
	v_mfma_f32_16x16x32_bf16 v[2:5], v[174:177], v[206:209], 0
	v_mfma_f32_16x16x32_bf16 v[50:53], v[170:173], v[186:189], v[50:53]
	v_mfma_f32_16x16x32_bf16 v[42:45], v[178:181], v[186:189], v[42:45]
	v_mfma_f32_16x16x32_bf16 v[34:37], v[170:173], v[194:197], v[34:37]
	v_mfma_f32_16x16x32_bf16 v[26:29], v[178:181], v[194:197], v[26:29]
	v_mfma_f32_16x16x32_bf16 v[18:21], v[170:173], v[202:205], v[18:21]
	v_mfma_f32_16x16x32_bf16 v[10:13], v[178:181], v[202:205], v[10:13]
	v_mfma_f32_16x16x32_bf16 v[6:9], v[170:173], v[224:227], v[6:9]
	v_mfma_f32_16x16x32_bf16 v[2:5], v[178:181], v[224:227], v[2:5]
	s_setprio 0
	s_barrier
	s_add_i32 s83, 0, 0x18000
	s_add_i32 s84, 0, 0x1c000
	v_add_u32_e32 v162, s83, v147
	v_add_u32_e32 v178, s84, v147
	ds_read_b128 v[150:153], v162
	ds_read_b128 v[154:157], v162 offset:1024
	ds_read_b128 v[158:161], v162 offset:2048
	ds_read_b128 v[162:165], v162 offset:3072
	ds_read_b128 v[166:169], v178
	ds_read_b128 v[170:173], v178 offset:1024
	ds_read_b128 v[174:177], v178 offset:2048
	ds_read_b128 v[178:181], v178 offset:3072
	s_add_u32 s64, s70, 0x20000
	s_addc_u32 s65, s71, 0
	s_mov_b32 m0, s72
	v_lshl_add_u64 v[230:231], s[64:65], 0, v[138:139]
	ds_read_b128 v[182:185], v149 offset:32768
	ds_read_b128 v[186:189], v149 offset:33792
	ds_read_b128 v[190:193], v149 offset:34816
	ds_read_b128 v[194:197], v149 offset:35840
	ds_read_b128 v[198:201], v149 offset:36864
	ds_read_b128 v[202:205], v149 offset:37888
	ds_read_b128 v[206:209], v149 offset:38912
	ds_read_b128 v[224:227], v149 offset:39936
	global_load_lds_dwordx4 v[230:231], off
	v_lshl_add_u64 v[230:231], s[64:65], 0, v[136:137]
	s_mov_b32 m0, s73
	s_nop 0
	global_load_lds_dwordx4 v[230:231], off
	s_waitcnt vmcnt(8)
	s_waitcnt lgkmcnt(0)
	s_setprio 3
	s_barrier
	s_waitcnt lgkmcnt(0)
	v_mfma_f32_16x16x32_bf16 v[126:129], v[150:153], v[182:185], v[126:129]
	v_mfma_f32_16x16x32_bf16 v[122:125], v[158:161], v[182:185], v[122:125]
	v_mfma_f32_16x16x32_bf16 v[118:121], v[150:153], v[190:193], v[118:121]
	v_mfma_f32_16x16x32_bf16 v[110:113], v[158:161], v[190:193], v[110:113]
	v_mfma_f32_16x16x32_bf16 v[102:105], v[150:153], v[198:201], v[102:105]
	v_mfma_f32_16x16x32_bf16 v[94:97], v[158:161], v[198:201], v[94:97]
	v_mfma_f32_16x16x32_bf16 v[86:89], v[150:153], v[206:209], v[86:89]
	v_mfma_f32_16x16x32_bf16 v[78:81], v[158:161], v[206:209], v[78:81]
	v_mfma_f32_16x16x32_bf16 v[126:129], v[154:157], v[186:189], v[126:129]
	v_mfma_f32_16x16x32_bf16 v[122:125], v[162:165], v[186:189], v[122:125]
	v_mfma_f32_16x16x32_bf16 v[118:121], v[154:157], v[194:197], v[118:121]
	v_mfma_f32_16x16x32_bf16 v[110:113], v[162:165], v[194:197], v[110:113]
	v_mfma_f32_16x16x32_bf16 v[102:105], v[154:157], v[202:205], v[102:105]
	v_mfma_f32_16x16x32_bf16 v[94:97], v[162:165], v[202:205], v[94:97]
	v_mfma_f32_16x16x32_bf16 v[86:89], v[154:157], v[224:227], v[86:89]
	v_mfma_f32_16x16x32_bf16 v[78:81], v[162:165], v[224:227], v[78:81]
	v_mfma_f32_16x16x32_bf16 v[114:117], v[166:169], v[182:185], v[114:117]
	v_mfma_f32_16x16x32_bf16 v[106:109], v[174:177], v[182:185], v[106:109]
	v_mfma_f32_16x16x32_bf16 v[98:101], v[166:169], v[190:193], v[98:101]
	v_mfma_f32_16x16x32_bf16 v[90:93], v[174:177], v[190:193], v[90:93]
	v_mfma_f32_16x16x32_bf16 v[82:85], v[166:169], v[198:201], v[82:85]
	v_mfma_f32_16x16x32_bf16 v[74:77], v[174:177], v[198:201], v[74:77]
	v_mfma_f32_16x16x32_bf16 v[70:73], v[166:169], v[206:209], v[70:73]
	v_mfma_f32_16x16x32_bf16 v[66:69], v[174:177], v[206:209], v[66:69]
	v_mfma_f32_16x16x32_bf16 v[114:117], v[170:173], v[186:189], v[114:117]
	v_mfma_f32_16x16x32_bf16 v[106:109], v[178:181], v[186:189], v[106:109]
	v_mfma_f32_16x16x32_bf16 v[98:101], v[170:173], v[194:197], v[98:101]
	v_mfma_f32_16x16x32_bf16 v[90:93], v[178:181], v[194:197], v[90:93]
	v_mfma_f32_16x16x32_bf16 v[82:85], v[170:173], v[202:205], v[82:85]
	v_mfma_f32_16x16x32_bf16 v[74:77], v[178:181], v[202:205], v[74:77]
	v_mfma_f32_16x16x32_bf16 v[70:73], v[170:173], v[224:227], v[70:73]
	v_mfma_f32_16x16x32_bf16 v[66:69], v[178:181], v[224:227], v[66:69]
	s_setprio 0
	s_barrier
	s_add_i32 s64, s83, s63
	v_lshl_add_u64 v[144:145], v[144:145], 0, s[48:49]
	s_mov_b32 m0, s64
	ds_read_b128 v[182:185], v149 offset:49152
	ds_read_b128 v[186:189], v149 offset:50176
	ds_read_b128 v[190:193], v149 offset:51200
	ds_read_b128 v[194:197], v149 offset:52224
	ds_read_b128 v[198:201], v149 offset:53248
	ds_read_b128 v[202:205], v149 offset:54272
	ds_read_b128 v[206:209], v149 offset:55296
	ds_read_b128 v[224:227], v149 offset:56320
	global_load_lds_dwordx4 v[144:145], off
	s_add_i32 m0, s64, 0x2000
	s_add_u32 s64, s68, 0x20080
	v_lshl_add_u64 v[144:145], v[210:211], 0, s[48:49]
	s_addc_u32 s65, s69, 0
	s_add_i32 s68, s84, s63
	global_load_lds_dwordx4 v[144:145], off
	v_lshl_add_u64 v[144:145], s[64:65], 0, v[0:1]
	s_mov_b32 m0, s68
	s_nop 0
	global_load_lds_dwordx4 v[144:145], off
	v_lshl_add_u64 v[144:145], s[64:65], 0, v[134:135]
	s_add_i32 m0, s68, 0x2000
	s_nop 0
	global_load_lds_dwordx4 v[144:145], off
	v_lshl_add_u64 v[144:145], v[220:221], 0, s[48:49]
	s_mov_b32 m0, s74
	s_nop 0
	global_load_lds_dwordx4 v[144:145], off
	v_lshl_add_u64 v[144:145], v[228:229], 0, s[48:49]
	s_mov_b32 m0, s75
	s_nop 0
	global_load_lds_dwordx4 v[144:145], off
	s_waitcnt vmcnt(8)
	s_waitcnt lgkmcnt(0)
	s_setprio 3
	s_barrier
	s_waitcnt lgkmcnt(0)
	v_mfma_f32_16x16x32_bf16 v[62:65], v[150:153], v[182:185], v[62:65]
	v_mfma_f32_16x16x32_bf16 v[58:61], v[158:161], v[182:185], v[58:61]
	v_mfma_f32_16x16x32_bf16 v[54:57], v[150:153], v[190:193], v[54:57]
	v_mfma_f32_16x16x32_bf16 v[46:49], v[158:161], v[190:193], v[46:49]
	v_mfma_f32_16x16x32_bf16 v[38:41], v[150:153], v[198:201], v[38:41]
	v_mfma_f32_16x16x32_bf16 v[30:33], v[158:161], v[198:201], v[30:33]
	v_mfma_f32_16x16x32_bf16 v[22:25], v[150:153], v[206:209], v[22:25]
	v_mfma_f32_16x16x32_bf16 v[14:17], v[158:161], v[206:209], v[14:17]
	v_mfma_f32_16x16x32_bf16 v[62:65], v[154:157], v[186:189], v[62:65]
	v_mfma_f32_16x16x32_bf16 v[58:61], v[162:165], v[186:189], v[58:61]
	v_mfma_f32_16x16x32_bf16 v[54:57], v[154:157], v[194:197], v[54:57]
	v_mfma_f32_16x16x32_bf16 v[46:49], v[162:165], v[194:197], v[46:49]
	v_mfma_f32_16x16x32_bf16 v[38:41], v[154:157], v[202:205], v[38:41]
	v_mfma_f32_16x16x32_bf16 v[30:33], v[162:165], v[202:205], v[30:33]
	v_mfma_f32_16x16x32_bf16 v[22:25], v[154:157], v[224:227], v[22:25]
	v_mfma_f32_16x16x32_bf16 v[14:17], v[162:165], v[224:227], v[14:17]
	v_mfma_f32_16x16x32_bf16 v[50:53], v[166:169], v[182:185], v[50:53]
	v_mfma_f32_16x16x32_bf16 v[42:45], v[174:177], v[182:185], v[42:45]
	v_mfma_f32_16x16x32_bf16 v[34:37], v[166:169], v[190:193], v[34:37]
	v_mfma_f32_16x16x32_bf16 v[26:29], v[174:177], v[190:193], v[26:29]
	v_mfma_f32_16x16x32_bf16 v[18:21], v[166:169], v[198:201], v[18:21]
	v_mfma_f32_16x16x32_bf16 v[10:13], v[174:177], v[198:201], v[10:13]
	v_mfma_f32_16x16x32_bf16 v[6:9], v[166:169], v[206:209], v[6:9]
	v_mfma_f32_16x16x32_bf16 v[2:5], v[174:177], v[206:209], v[2:5]
	v_mfma_f32_16x16x32_bf16 v[50:53], v[170:173], v[186:189], v[50:53]
	v_mfma_f32_16x16x32_bf16 v[42:45], v[178:181], v[186:189], v[42:45]
	v_mfma_f32_16x16x32_bf16 v[34:37], v[170:173], v[194:197], v[34:37]
	v_mfma_f32_16x16x32_bf16 v[26:29], v[178:181], v[194:197], v[26:29]
	v_mfma_f32_16x16x32_bf16 v[18:21], v[170:173], v[202:205], v[18:21]
	v_mfma_f32_16x16x32_bf16 v[10:13], v[178:181], v[202:205], v[10:13]
	v_mfma_f32_16x16x32_bf16 v[6:9], v[170:173], v[224:227], v[6:9]
	v_mfma_f32_16x16x32_bf16 v[2:5], v[178:181], v[224:227], v[2:5]
	s_setprio 0
	s_barrier
	s_add_i32 s82, s82, 2
	s_add_u32 s6, s6, 0x100
	s_addc_u32 s7, s7, 0
	s_add_u32 s80, s80, 0x100
	s_addc_u32 s81, s81, 0
.LBB0_1533:
	s_add_u32 s64, s6, 0xfffe0080
	s_addc_u32 s65, s7, -1
	s_add_i32 s83, 0, 0x10000
	s_cmp_eq_u32 s82, 4
	s_cselect_b32 s71, s53, s65
	s_cselect_b32 s70, s52, s64
	v_add_u32_e32 v144, s83, v147
	s_cselect_b32 s69, s17, s81
	s_cselect_b32 s68, s19, s80
	s_add_i32 s84, 0, 0x14000
	ds_read_b128 v[150:153], v144
	ds_read_b128 v[154:157], v144 offset:1024
	ds_read_b128 v[158:161], v144 offset:2048
	ds_read_b128 v[162:165], v144 offset:3072
	v_add_u32_e32 v144, s84, v147
	ds_read_b128 v[166:169], v144
	ds_read_b128 v[170:173], v144 offset:1024
	ds_read_b128 v[174:177], v144 offset:2048
	ds_read_b128 v[178:181], v144 offset:3072
	v_lshl_add_u64 v[144:145], s[6:7], 0, v[140:141]
	s_add_i32 m0, s21, 0xc000
	ds_read_b128 v[182:185], v149
	ds_read_b128 v[186:189], v149 offset:1024
	ds_read_b128 v[190:193], v149 offset:2048
	ds_read_b128 v[194:197], v149 offset:3072
	ds_read_b128 v[198:201], v149 offset:4096
	ds_read_b128 v[202:205], v149 offset:5120
	ds_read_b128 v[206:209], v149 offset:6144
	ds_read_b128 v[224:227], v149 offset:7168
	global_load_lds_dwordx4 v[144:145], off
	v_lshl_add_u64 v[144:145], s[6:7], 0, v[142:143]
	s_add_i32 m0, s21, 0xe000
	s_nop 0
	global_load_lds_dwordx4 v[144:145], off
	s_waitcnt vmcnt(8)
	s_waitcnt lgkmcnt(0)
	s_setprio 3
	s_barrier
	s_waitcnt lgkmcnt(0)
	v_mfma_f32_16x16x32_bf16 v[126:129], v[150:153], v[182:185], v[126:129]
	v_mfma_f32_16x16x32_bf16 v[122:125], v[158:161], v[182:185], v[122:125]
	v_mfma_f32_16x16x32_bf16 v[118:121], v[150:153], v[190:193], v[118:121]
	v_mfma_f32_16x16x32_bf16 v[110:113], v[158:161], v[190:193], v[110:113]
	v_mfma_f32_16x16x32_bf16 v[102:105], v[150:153], v[198:201], v[102:105]
	v_mfma_f32_16x16x32_bf16 v[94:97], v[158:161], v[198:201], v[94:97]
	v_mfma_f32_16x16x32_bf16 v[86:89], v[150:153], v[206:209], v[86:89]
	v_mfma_f32_16x16x32_bf16 v[78:81], v[158:161], v[206:209], v[78:81]
	v_mfma_f32_16x16x32_bf16 v[126:129], v[154:157], v[186:189], v[126:129]
	v_mfma_f32_16x16x32_bf16 v[122:125], v[162:165], v[186:189], v[122:125]
	v_mfma_f32_16x16x32_bf16 v[118:121], v[154:157], v[194:197], v[118:121]
	v_mfma_f32_16x16x32_bf16 v[110:113], v[162:165], v[194:197], v[110:113]
	v_mfma_f32_16x16x32_bf16 v[102:105], v[154:157], v[202:205], v[102:105]
	v_mfma_f32_16x16x32_bf16 v[94:97], v[162:165], v[202:205], v[94:97]
	v_mfma_f32_16x16x32_bf16 v[86:89], v[154:157], v[224:227], v[86:89]
	v_mfma_f32_16x16x32_bf16 v[78:81], v[162:165], v[224:227], v[78:81]
	v_mfma_f32_16x16x32_bf16 v[114:117], v[166:169], v[182:185], v[114:117]
	v_mfma_f32_16x16x32_bf16 v[106:109], v[174:177], v[182:185], v[106:109]
	v_mfma_f32_16x16x32_bf16 v[98:101], v[166:169], v[190:193], v[98:101]
	v_mfma_f32_16x16x32_bf16 v[90:93], v[174:177], v[190:193], v[90:93]
	v_mfma_f32_16x16x32_bf16 v[82:85], v[166:169], v[198:201], v[82:85]
	v_mfma_f32_16x16x32_bf16 v[74:77], v[174:177], v[198:201], v[74:77]
	v_mfma_f32_16x16x32_bf16 v[70:73], v[166:169], v[206:209], v[70:73]
	v_mfma_f32_16x16x32_bf16 v[66:69], v[174:177], v[206:209], v[66:69]
	v_mfma_f32_16x16x32_bf16 v[114:117], v[170:173], v[186:189], v[114:117]
	v_mfma_f32_16x16x32_bf16 v[106:109], v[178:181], v[186:189], v[106:109]
	v_mfma_f32_16x16x32_bf16 v[98:101], v[170:173], v[194:197], v[98:101]
	v_mfma_f32_16x16x32_bf16 v[90:93], v[178:181], v[194:197], v[90:93]
	v_mfma_f32_16x16x32_bf16 v[82:85], v[170:173], v[202:205], v[82:85]
	v_mfma_f32_16x16x32_bf16 v[74:77], v[178:181], v[202:205], v[74:77]
	v_mfma_f32_16x16x32_bf16 v[70:73], v[170:173], v[224:227], v[70:73]
	v_mfma_f32_16x16x32_bf16 v[66:69], v[178:181], v[224:227], v[66:69]
	s_setprio 0
	s_barrier
	s_add_i32 s64, s83, s63
	v_lshl_add_u64 v[144:145], s[68:69], 0, v[0:1]
	s_mov_b32 m0, s64
	ds_read_b128 v[182:185], v149 offset:16384
	ds_read_b128 v[186:189], v149 offset:17408
	ds_read_b128 v[190:193], v149 offset:18432
	ds_read_b128 v[194:197], v149 offset:19456
	ds_read_b128 v[198:201], v149 offset:20480
	ds_read_b128 v[202:205], v149 offset:21504
	ds_read_b128 v[206:209], v149 offset:22528
	ds_read_b128 v[224:227], v149 offset:23552
	global_load_lds_dwordx4 v[144:145], off
	s_add_i32 m0, s64, 0x2000
	s_add_u32 s64, s68, 0x20000
	v_lshl_add_u64 v[210:211], s[68:69], 0, v[134:135]
	s_addc_u32 s65, s69, 0
	s_add_i32 s83, s84, s63
	global_load_lds_dwordx4 v[210:211], off
	v_lshl_add_u64 v[220:221], s[64:65], 0, v[0:1]
	s_mov_b32 m0, s83
	v_lshl_add_u64 v[228:229], s[70:71], 0, v[136:137]
	global_load_lds_dwordx4 v[220:221], off
	v_lshl_add_u64 v[220:221], s[64:65], 0, v[134:135]
	s_add_i32 m0, s83, 0x2000
	s_nop 0
	global_load_lds_dwordx4 v[220:221], off
	v_lshl_add_u64 v[220:221], s[70:71], 0, v[138:139]
	s_mov_b32 m0, s21
	s_nop 0
	global_load_lds_dwordx4 v[220:221], off
	s_mov_b32 m0, s27
	s_nop 0
	global_load_lds_dwordx4 v[228:229], off
	s_waitcnt vmcnt(8)
	s_waitcnt lgkmcnt(0)
	s_setprio 3
	s_barrier
	s_waitcnt lgkmcnt(0)
	v_mfma_f32_16x16x32_bf16 v[62:65], v[150:153], v[182:185], v[62:65]
	v_mfma_f32_16x16x32_bf16 v[58:61], v[158:161], v[182:185], v[58:61]
	v_mfma_f32_16x16x32_bf16 v[54:57], v[150:153], v[190:193], v[54:57]
	v_mfma_f32_16x16x32_bf16 v[46:49], v[158:161], v[190:193], v[46:49]
	v_mfma_f32_16x16x32_bf16 v[38:41], v[150:153], v[198:201], v[38:41]
	v_mfma_f32_16x16x32_bf16 v[30:33], v[158:161], v[198:201], v[30:33]
	v_mfma_f32_16x16x32_bf16 v[22:25], v[150:153], v[206:209], v[22:25]
	v_mfma_f32_16x16x32_bf16 v[14:17], v[158:161], v[206:209], v[14:17]
	v_mfma_f32_16x16x32_bf16 v[62:65], v[154:157], v[186:189], v[62:65]
	v_mfma_f32_16x16x32_bf16 v[58:61], v[162:165], v[186:189], v[58:61]
	v_mfma_f32_16x16x32_bf16 v[54:57], v[154:157], v[194:197], v[54:57]
	v_mfma_f32_16x16x32_bf16 v[46:49], v[162:165], v[194:197], v[46:49]
	v_mfma_f32_16x16x32_bf16 v[38:41], v[154:157], v[202:205], v[38:41]
	v_mfma_f32_16x16x32_bf16 v[30:33], v[162:165], v[202:205], v[30:33]
	v_mfma_f32_16x16x32_bf16 v[22:25], v[154:157], v[224:227], v[22:25]
	v_mfma_f32_16x16x32_bf16 v[14:17], v[162:165], v[224:227], v[14:17]
	v_mfma_f32_16x16x32_bf16 v[50:53], v[166:169], v[182:185], v[50:53]
	v_mfma_f32_16x16x32_bf16 v[42:45], v[174:177], v[182:185], v[42:45]
	v_mfma_f32_16x16x32_bf16 v[34:37], v[166:169], v[190:193], v[34:37]
	v_mfma_f32_16x16x32_bf16 v[26:29], v[174:177], v[190:193], v[26:29]
	v_mfma_f32_16x16x32_bf16 v[18:21], v[166:169], v[198:201], v[18:21]
	v_mfma_f32_16x16x32_bf16 v[10:13], v[174:177], v[198:201], v[10:13]
	v_mfma_f32_16x16x32_bf16 v[6:9], v[166:169], v[206:209], v[6:9]
	v_mfma_f32_16x16x32_bf16 v[2:5], v[174:177], v[206:209], v[2:5]
	v_mfma_f32_16x16x32_bf16 v[50:53], v[170:173], v[186:189], v[50:53]
	v_mfma_f32_16x16x32_bf16 v[42:45], v[178:181], v[186:189], v[42:45]
	v_mfma_f32_16x16x32_bf16 v[34:37], v[170:173], v[194:197], v[34:37]
	v_mfma_f32_16x16x32_bf16 v[26:29], v[178:181], v[194:197], v[26:29]
	v_mfma_f32_16x16x32_bf16 v[18:21], v[170:173], v[202:205], v[18:21]
	v_mfma_f32_16x16x32_bf16 v[10:13], v[178:181], v[202:205], v[10:13]
	v_mfma_f32_16x16x32_bf16 v[6:9], v[170:173], v[224:227], v[6:9]
	v_mfma_f32_16x16x32_bf16 v[2:5], v[178:181], v[224:227], v[2:5]
	s_setprio 0
	s_barrier
	s_add_i32 s83, 0, 0x18000
	s_add_i32 s84, 0, 0x1c000
	v_add_u32_e32 v162, s83, v147
	v_add_u32_e32 v178, s84, v147
	ds_read_b128 v[150:153], v162
	ds_read_b128 v[154:157], v162 offset:1024
	ds_read_b128 v[158:161], v162 offset:2048
	ds_read_b128 v[162:165], v162 offset:3072
	ds_read_b128 v[166:169], v178
	ds_read_b128 v[170:173], v178 offset:1024
	ds_read_b128 v[174:177], v178 offset:2048
	ds_read_b128 v[178:181], v178 offset:3072
	s_add_u32 s64, s70, 0x20000
	s_addc_u32 s65, s71, 0
	s_mov_b32 m0, s72
	v_lshl_add_u64 v[230:231], s[64:65], 0, v[138:139]
	ds_read_b128 v[182:185], v149 offset:32768
	ds_read_b128 v[186:189], v149 offset:33792
	ds_read_b128 v[190:193], v149 offset:34816
	ds_read_b128 v[194:197], v149 offset:35840
	ds_read_b128 v[198:201], v149 offset:36864
	ds_read_b128 v[202:205], v149 offset:37888
	ds_read_b128 v[206:209], v149 offset:38912
	ds_read_b128 v[224:227], v149 offset:39936
	global_load_lds_dwordx4 v[230:231], off
	v_lshl_add_u64 v[230:231], s[64:65], 0, v[136:137]
	s_mov_b32 m0, s73
	s_nop 0
	global_load_lds_dwordx4 v[230:231], off
	s_waitcnt vmcnt(8)
	s_waitcnt lgkmcnt(0)
	s_setprio 3
	s_barrier
	s_waitcnt lgkmcnt(0)
	v_mfma_f32_16x16x32_bf16 v[126:129], v[150:153], v[182:185], v[126:129]
	v_mfma_f32_16x16x32_bf16 v[122:125], v[158:161], v[182:185], v[122:125]
	v_mfma_f32_16x16x32_bf16 v[118:121], v[150:153], v[190:193], v[118:121]
	v_mfma_f32_16x16x32_bf16 v[110:113], v[158:161], v[190:193], v[110:113]
	v_mfma_f32_16x16x32_bf16 v[102:105], v[150:153], v[198:201], v[102:105]
	v_mfma_f32_16x16x32_bf16 v[94:97], v[158:161], v[198:201], v[94:97]
	v_mfma_f32_16x16x32_bf16 v[86:89], v[150:153], v[206:209], v[86:89]
	v_mfma_f32_16x16x32_bf16 v[78:81], v[158:161], v[206:209], v[78:81]
	v_mfma_f32_16x16x32_bf16 v[126:129], v[154:157], v[186:189], v[126:129]
	v_mfma_f32_16x16x32_bf16 v[122:125], v[162:165], v[186:189], v[122:125]
	v_mfma_f32_16x16x32_bf16 v[118:121], v[154:157], v[194:197], v[118:121]
	v_mfma_f32_16x16x32_bf16 v[110:113], v[162:165], v[194:197], v[110:113]
	v_mfma_f32_16x16x32_bf16 v[102:105], v[154:157], v[202:205], v[102:105]
	v_mfma_f32_16x16x32_bf16 v[94:97], v[162:165], v[202:205], v[94:97]
	v_mfma_f32_16x16x32_bf16 v[86:89], v[154:157], v[224:227], v[86:89]
	v_mfma_f32_16x16x32_bf16 v[78:81], v[162:165], v[224:227], v[78:81]
	v_mfma_f32_16x16x32_bf16 v[114:117], v[166:169], v[182:185], v[114:117]
	v_mfma_f32_16x16x32_bf16 v[106:109], v[174:177], v[182:185], v[106:109]
	v_mfma_f32_16x16x32_bf16 v[98:101], v[166:169], v[190:193], v[98:101]
	v_mfma_f32_16x16x32_bf16 v[90:93], v[174:177], v[190:193], v[90:93]
	v_mfma_f32_16x16x32_bf16 v[82:85], v[166:169], v[198:201], v[82:85]
	v_mfma_f32_16x16x32_bf16 v[74:77], v[174:177], v[198:201], v[74:77]
	v_mfma_f32_16x16x32_bf16 v[70:73], v[166:169], v[206:209], v[70:73]
	v_mfma_f32_16x16x32_bf16 v[66:69], v[174:177], v[206:209], v[66:69]
	v_mfma_f32_16x16x32_bf16 v[114:117], v[170:173], v[186:189], v[114:117]
	v_mfma_f32_16x16x32_bf16 v[106:109], v[178:181], v[186:189], v[106:109]
	v_mfma_f32_16x16x32_bf16 v[98:101], v[170:173], v[194:197], v[98:101]
	v_mfma_f32_16x16x32_bf16 v[90:93], v[178:181], v[194:197], v[90:93]
	v_mfma_f32_16x16x32_bf16 v[82:85], v[170:173], v[202:205], v[82:85]
	v_mfma_f32_16x16x32_bf16 v[74:77], v[178:181], v[202:205], v[74:77]
	v_mfma_f32_16x16x32_bf16 v[70:73], v[170:173], v[224:227], v[70:73]
	v_mfma_f32_16x16x32_bf16 v[66:69], v[178:181], v[224:227], v[66:69]
	s_setprio 0
	s_barrier
	s_add_i32 s64, s83, s63
	v_lshl_add_u64 v[144:145], v[144:145], 0, s[48:49]
	s_mov_b32 m0, s64
	ds_read_b128 v[182:185], v149 offset:49152
	ds_read_b128 v[186:189], v149 offset:50176
	ds_read_b128 v[190:193], v149 offset:51200
	ds_read_b128 v[194:197], v149 offset:52224
	ds_read_b128 v[198:201], v149 offset:53248
	ds_read_b128 v[202:205], v149 offset:54272
	ds_read_b128 v[206:209], v149 offset:55296
	ds_read_b128 v[224:227], v149 offset:56320
	global_load_lds_dwordx4 v[144:145], off
	s_add_i32 m0, s64, 0x2000
	s_add_u32 s64, s68, 0x20080
	v_lshl_add_u64 v[144:145], v[210:211], 0, s[48:49]
	s_addc_u32 s65, s69, 0
	s_add_i32 s68, s84, s63
	global_load_lds_dwordx4 v[144:145], off
	v_lshl_add_u64 v[144:145], s[64:65], 0, v[0:1]
	s_mov_b32 m0, s68
	s_nop 0
	global_load_lds_dwordx4 v[144:145], off
	v_lshl_add_u64 v[144:145], s[64:65], 0, v[134:135]
	s_add_i32 m0, s68, 0x2000
	s_nop 0
	global_load_lds_dwordx4 v[144:145], off
	v_lshl_add_u64 v[144:145], v[220:221], 0, s[48:49]
	s_mov_b32 m0, s74
	s_nop 0
	global_load_lds_dwordx4 v[144:145], off
	v_lshl_add_u64 v[144:145], v[228:229], 0, s[48:49]
	s_mov_b32 m0, s75
	s_nop 0
	global_load_lds_dwordx4 v[144:145], off
	s_waitcnt vmcnt(8)
	s_waitcnt lgkmcnt(0)
	s_setprio 3
	s_barrier
	s_waitcnt lgkmcnt(0)
	v_mfma_f32_16x16x32_bf16 v[62:65], v[150:153], v[182:185], v[62:65]
	v_mfma_f32_16x16x32_bf16 v[58:61], v[158:161], v[182:185], v[58:61]
	v_mfma_f32_16x16x32_bf16 v[54:57], v[150:153], v[190:193], v[54:57]
	v_mfma_f32_16x16x32_bf16 v[46:49], v[158:161], v[190:193], v[46:49]
	v_mfma_f32_16x16x32_bf16 v[38:41], v[150:153], v[198:201], v[38:41]
	v_mfma_f32_16x16x32_bf16 v[30:33], v[158:161], v[198:201], v[30:33]
	v_mfma_f32_16x16x32_bf16 v[22:25], v[150:153], v[206:209], v[22:25]
	v_mfma_f32_16x16x32_bf16 v[14:17], v[158:161], v[206:209], v[14:17]
	v_mfma_f32_16x16x32_bf16 v[62:65], v[154:157], v[186:189], v[62:65]
	v_mfma_f32_16x16x32_bf16 v[58:61], v[162:165], v[186:189], v[58:61]
	v_mfma_f32_16x16x32_bf16 v[54:57], v[154:157], v[194:197], v[54:57]
	v_mfma_f32_16x16x32_bf16 v[46:49], v[162:165], v[194:197], v[46:49]
	v_mfma_f32_16x16x32_bf16 v[38:41], v[154:157], v[202:205], v[38:41]
	v_mfma_f32_16x16x32_bf16 v[30:33], v[162:165], v[202:205], v[30:33]
	v_mfma_f32_16x16x32_bf16 v[22:25], v[154:157], v[224:227], v[22:25]
	v_mfma_f32_16x16x32_bf16 v[14:17], v[162:165], v[224:227], v[14:17]
	v_mfma_f32_16x16x32_bf16 v[50:53], v[166:169], v[182:185], v[50:53]
	v_mfma_f32_16x16x32_bf16 v[42:45], v[174:177], v[182:185], v[42:45]
	v_mfma_f32_16x16x32_bf16 v[34:37], v[166:169], v[190:193], v[34:37]
	v_mfma_f32_16x16x32_bf16 v[26:29], v[174:177], v[190:193], v[26:29]
	v_mfma_f32_16x16x32_bf16 v[18:21], v[166:169], v[198:201], v[18:21]
	v_mfma_f32_16x16x32_bf16 v[10:13], v[174:177], v[198:201], v[10:13]
	v_mfma_f32_16x16x32_bf16 v[6:9], v[166:169], v[206:209], v[6:9]
	v_mfma_f32_16x16x32_bf16 v[2:5], v[174:177], v[206:209], v[2:5]
	v_mfma_f32_16x16x32_bf16 v[50:53], v[170:173], v[186:189], v[50:53]
	v_mfma_f32_16x16x32_bf16 v[42:45], v[178:181], v[186:189], v[42:45]
	v_mfma_f32_16x16x32_bf16 v[34:37], v[170:173], v[194:197], v[34:37]
	v_mfma_f32_16x16x32_bf16 v[26:29], v[178:181], v[194:197], v[26:29]
	v_mfma_f32_16x16x32_bf16 v[18:21], v[170:173], v[202:205], v[18:21]
	v_mfma_f32_16x16x32_bf16 v[10:13], v[178:181], v[202:205], v[10:13]
	v_mfma_f32_16x16x32_bf16 v[6:9], v[170:173], v[224:227], v[6:9]
	v_mfma_f32_16x16x32_bf16 v[2:5], v[178:181], v[224:227], v[2:5]
	s_setprio 0
	s_barrier
	s_add_i32 s82, s82, 2
	s_add_u32 s6, s6, 0x100
	s_addc_u32 s7, s7, 0
	s_add_u32 s80, s80, 0x100
	s_addc_u32 s81, s81, 0
	s_cmp_gt_u32 s82, 5
	s_cbranch_scc0 .LBB0_1533
	s_and_b64 vcc, exec, s[12:13]
	s_cbranch_vccnz .LBB0_1537
	s_cmp_gt_i32 s20, 15
	s_cbranch_scc0 .LBB0_1538

.LBB0_1602:
	s_ashr_i32 s13, s16, 3
	s_add_i32 s13, s16, s13
	s_and_b64 s[18:19], s[66:67], s[4:5]
	s_add_i32 s13, s13, 1
	s_and_b64 s[18:19], s[18:19], exec
	s_cselect_b32 s16, s13, s16
	s_ashr_i32 s17, s16, 31
	s_lshl_b64 s[18:19], s[16:17], 19
	s_add_u32 s18, s37, s18
	s_addc_u32 s19, s60, s19
	s_and_b64 s[20:21], s[4:5], exec
	s_cselect_b32 s17, s19, s57
	s_cselect_b32 s27, s18, s56
	s_ashr_i32 s13, s12, 31
	s_lshl_b64 s[20:21], s[12:13], 19
	s_add_u32 s20, s63, s20
	s_addc_u32 s21, s72, s21
	s_and_b64 s[30:31], s[4:5], exec
	s_cselect_b32 s13, s21, s69
	s_cselect_b32 s30, s20, s68
	s_add_u32 s56, s56, 0x40080
	s_addc_u32 s57, s57, 0
	s_add_u32 s31, s68, 0x100
	s_addc_u32 s85, s69, 0
	s_mov_b32 s86, -2
	s_add_u32 s64, s56, 0xfffc0080
	s_addc_u32 s65, s57, -1
	s_add_i32 s87, 0, 0x10000
	s_cmp_eq_u32 s86, 12
	s_cselect_b32 s71, s17, s65
	s_cselect_b32 s70, s27, s64
	v_add_u32_e32 v144, s87, v147
	s_cselect_b32 s69, s13, s85
	s_cselect_b32 s68, s30, s31
	s_add_i32 s88, 0, 0x14000
	ds_read_b128 v[140:143], v144
	ds_read_b128 v[150:153], v144 offset:1024
	ds_read_b128 v[154:157], v144 offset:2048
	ds_read_b128 v[158:161], v144 offset:3072
	v_add_u32_e32 v144, s88, v147
	ds_read_b128 v[162:165], v144
	ds_read_b128 v[166:169], v144 offset:1024
	ds_read_b128 v[170:173], v144 offset:2048
	ds_read_b128 v[174:177], v144 offset:3072
	v_lshl_add_u64 v[144:145], s[56:57], 0, v[136:137]
	s_add_i32 m0, s53, 0xc000
	ds_read_b128 v[178:181], v149
	ds_read_b128 v[182:185], v149 offset:1024
	ds_read_b128 v[186:189], v149 offset:2048
	ds_read_b128 v[190:193], v149 offset:3072
	ds_read_b128 v[194:197], v149 offset:4096
	ds_read_b128 v[198:201], v149 offset:5120
	ds_read_b128 v[202:205], v149 offset:6144
	ds_read_b128 v[206:209], v149 offset:7168
	global_load_lds_dwordx4 v[144:145], off
	v_lshl_add_u64 v[144:145], s[56:57], 0, v[138:139]
	s_add_i32 m0, s53, 0xe000
	s_nop 0
	global_load_lds_dwordx4 v[144:145], off
	s_waitcnt vmcnt(8)
	s_waitcnt lgkmcnt(0)
	s_setprio 3
	s_barrier
	s_waitcnt lgkmcnt(0)
	v_mfma_f32_16x16x32_bf16 v[126:129], v[140:143], v[178:181], 0
	v_mfma_f32_16x16x32_bf16 v[122:125], v[154:157], v[178:181], 0
	v_mfma_f32_16x16x32_bf16 v[110:113], v[140:143], v[186:189], 0
	v_mfma_f32_16x16x32_bf16 v[106:109], v[154:157], v[186:189], 0
	v_mfma_f32_16x16x32_bf16 v[94:97], v[140:143], v[194:197], 0
	v_mfma_f32_16x16x32_bf16 v[90:93], v[154:157], v[194:197], 0
	v_mfma_f32_16x16x32_bf16 v[78:81], v[140:143], v[202:205], 0
	v_mfma_f32_16x16x32_bf16 v[74:77], v[154:157], v[202:205], 0
	v_mfma_f32_16x16x32_bf16 v[126:129], v[150:153], v[182:185], v[126:129]
	v_mfma_f32_16x16x32_bf16 v[122:125], v[158:161], v[182:185], v[122:125]
	v_mfma_f32_16x16x32_bf16 v[110:113], v[150:153], v[190:193], v[110:113]
	v_mfma_f32_16x16x32_bf16 v[106:109], v[158:161], v[190:193], v[106:109]
	v_mfma_f32_16x16x32_bf16 v[94:97], v[150:153], v[198:201], v[94:97]
	v_mfma_f32_16x16x32_bf16 v[90:93], v[158:161], v[198:201], v[90:93]
	v_mfma_f32_16x16x32_bf16 v[78:81], v[150:153], v[206:209], v[78:81]
	v_mfma_f32_16x16x32_bf16 v[74:77], v[158:161], v[206:209], v[74:77]
	v_mfma_f32_16x16x32_bf16 v[118:121], v[162:165], v[178:181], 0
	v_mfma_f32_16x16x32_bf16 v[114:117], v[170:173], v[178:181], 0
	v_mfma_f32_16x16x32_bf16 v[102:105], v[162:165], v[186:189], 0
	v_mfma_f32_16x16x32_bf16 v[98:101], v[170:173], v[186:189], 0
	v_mfma_f32_16x16x32_bf16 v[86:89], v[162:165], v[194:197], 0
	v_mfma_f32_16x16x32_bf16 v[82:85], v[170:173], v[194:197], 0
	v_mfma_f32_16x16x32_bf16 v[70:73], v[162:165], v[202:205], 0
	v_mfma_f32_16x16x32_bf16 v[66:69], v[170:173], v[202:205], 0
	v_mfma_f32_16x16x32_bf16 v[118:121], v[166:169], v[182:185], v[118:121]
	v_mfma_f32_16x16x32_bf16 v[114:117], v[174:177], v[182:185], v[114:117]
	v_mfma_f32_16x16x32_bf16 v[102:105], v[166:169], v[190:193], v[102:105]
	v_mfma_f32_16x16x32_bf16 v[98:101], v[174:177], v[190:193], v[98:101]
	v_mfma_f32_16x16x32_bf16 v[86:89], v[166:169], v[198:201], v[86:89]
	v_mfma_f32_16x16x32_bf16 v[82:85], v[174:177], v[198:201], v[82:85]
	v_mfma_f32_16x16x32_bf16 v[70:73], v[166:169], v[206:209], v[70:73]
	v_mfma_f32_16x16x32_bf16 v[66:69], v[174:177], v[206:209], v[66:69]
	s_setprio 0
	s_barrier
	s_add_i32 s64, s87, s73
	v_lshl_add_u64 v[144:145], s[68:69], 0, v[0:1]
	s_mov_b32 m0, s64
	ds_read_b128 v[178:181], v149 offset:16384
	ds_read_b128 v[182:185], v149 offset:17408
	ds_read_b128 v[186:189], v149 offset:18432
	ds_read_b128 v[190:193], v149 offset:19456
	ds_read_b128 v[194:197], v149 offset:20480
	ds_read_b128 v[198:201], v149 offset:21504
	ds_read_b128 v[202:205], v149 offset:22528
	ds_read_b128 v[206:209], v149 offset:23552
	global_load_lds_dwordx4 v[144:145], off
	s_add_i32 m0, s64, 0x2000
	s_add_u32 s64, s68, 0x40000
	v_lshl_add_u64 v[210:211], s[68:69], 0, v[134:135]
	s_addc_u32 s65, s69, 0
	s_add_i32 s87, s88, s73
	global_load_lds_dwordx4 v[210:211], off
	v_lshl_add_u64 v[220:221], s[64:65], 0, v[0:1]
	s_mov_b32 m0, s87
	v_lshl_add_u64 v[224:225], s[70:71], 0, v[134:135]
	global_load_lds_dwordx4 v[220:221], off
	v_lshl_add_u64 v[220:221], s[64:65], 0, v[134:135]
	s_add_i32 m0, s87, 0x2000
	s_nop 0
	global_load_lds_dwordx4 v[220:221], off
	v_lshl_add_u64 v[220:221], s[70:71], 0, v[0:1]
	s_mov_b32 m0, s53
	s_nop 0
	global_load_lds_dwordx4 v[220:221], off
	s_mov_b32 m0, s78
	s_nop 0
	global_load_lds_dwordx4 v[224:225], off
	s_waitcnt vmcnt(8)
	s_waitcnt lgkmcnt(0)
	s_setprio 3
	s_barrier
	s_waitcnt lgkmcnt(0)
	v_mfma_f32_16x16x32_bf16 v[62:65], v[140:143], v[178:181], 0
	v_mfma_f32_16x16x32_bf16 v[58:61], v[154:157], v[178:181], 0
	v_mfma_f32_16x16x32_bf16 v[46:49], v[140:143], v[186:189], 0
	v_mfma_f32_16x16x32_bf16 v[42:45], v[154:157], v[186:189], 0
	v_mfma_f32_16x16x32_bf16 v[30:33], v[140:143], v[194:197], 0
	v_mfma_f32_16x16x32_bf16 v[26:29], v[154:157], v[194:197], 0
	v_mfma_f32_16x16x32_bf16 v[14:17], v[140:143], v[202:205], 0
	v_mfma_f32_16x16x32_bf16 v[10:13], v[154:157], v[202:205], 0
	v_mfma_f32_16x16x32_bf16 v[62:65], v[150:153], v[182:185], v[62:65]
	v_mfma_f32_16x16x32_bf16 v[58:61], v[158:161], v[182:185], v[58:61]
	v_mfma_f32_16x16x32_bf16 v[46:49], v[150:153], v[190:193], v[46:49]
	v_mfma_f32_16x16x32_bf16 v[42:45], v[158:161], v[190:193], v[42:45]
	v_mfma_f32_16x16x32_bf16 v[30:33], v[150:153], v[198:201], v[30:33]
	v_mfma_f32_16x16x32_bf16 v[26:29], v[158:161], v[198:201], v[26:29]
	v_mfma_f32_16x16x32_bf16 v[14:17], v[150:153], v[206:209], v[14:17]
	v_mfma_f32_16x16x32_bf16 v[10:13], v[158:161], v[206:209], v[10:13]
	v_mfma_f32_16x16x32_bf16 v[54:57], v[162:165], v[178:181], 0
	v_mfma_f32_16x16x32_bf16 v[50:53], v[170:173], v[178:181], 0
	v_mfma_f32_16x16x32_bf16 v[38:41], v[162:165], v[186:189], 0
	v_mfma_f32_16x16x32_bf16 v[34:37], v[170:173], v[186:189], 0
	v_mfma_f32_16x16x32_bf16 v[22:25], v[162:165], v[194:197], 0
	v_mfma_f32_16x16x32_bf16 v[18:21], v[170:173], v[194:197], 0
	v_mfma_f32_16x16x32_bf16 v[6:9], v[162:165], v[202:205], 0
	v_mfma_f32_16x16x32_bf16 v[2:5], v[170:173], v[202:205], 0
	v_mfma_f32_16x16x32_bf16 v[54:57], v[166:169], v[182:185], v[54:57]
	v_mfma_f32_16x16x32_bf16 v[50:53], v[174:177], v[182:185], v[50:53]
	v_mfma_f32_16x16x32_bf16 v[38:41], v[166:169], v[190:193], v[38:41]
	v_mfma_f32_16x16x32_bf16 v[34:37], v[174:177], v[190:193], v[34:37]
	v_mfma_f32_16x16x32_bf16 v[22:25], v[166:169], v[198:201], v[22:25]
	v_mfma_f32_16x16x32_bf16 v[18:21], v[174:177], v[198:201], v[18:21]
	v_mfma_f32_16x16x32_bf16 v[6:9], v[166:169], v[206:209], v[6:9]
	v_mfma_f32_16x16x32_bf16 v[2:5], v[174:177], v[206:209], v[2:5]
	s_setprio 0
	s_barrier
	s_add_i32 s87, 0, 0x18000
	s_add_i32 s88, 0, 0x1c000
	v_add_u32_e32 v158, s87, v147
	v_add_u32_e32 v174, s88, v147
	ds_read_b128 v[140:143], v158
	ds_read_b128 v[150:153], v158 offset:1024
	ds_read_b128 v[154:157], v158 offset:2048
	ds_read_b128 v[158:161], v158 offset:3072
	ds_read_b128 v[162:165], v174
	ds_read_b128 v[166:169], v174 offset:1024
	ds_read_b128 v[170:173], v174 offset:2048
	ds_read_b128 v[174:177], v174 offset:3072
	s_add_u32 s64, s70, 0x40000
	s_addc_u32 s65, s71, 0
	s_mov_b32 m0, s79
	v_lshl_add_u64 v[226:227], s[64:65], 0, v[0:1]
	ds_read_b128 v[178:181], v149 offset:32768
	ds_read_b128 v[182:185], v149 offset:33792
	ds_read_b128 v[186:189], v149 offset:34816
	ds_read_b128 v[190:193], v149 offset:35840
	ds_read_b128 v[194:197], v149 offset:36864
	ds_read_b128 v[198:201], v149 offset:37888
	ds_read_b128 v[202:205], v149 offset:38912
	ds_read_b128 v[206:209], v149 offset:39936
	global_load_lds_dwordx4 v[226:227], off
	v_lshl_add_u64 v[226:227], s[64:65], 0, v[134:135]
	s_mov_b32 m0, s80
	s_nop 0
	global_load_lds_dwordx4 v[226:227], off
	s_waitcnt vmcnt(8)
	s_waitcnt lgkmcnt(0)
	s_setprio 3
	s_barrier
	s_waitcnt lgkmcnt(0)
	v_mfma_f32_16x16x32_bf16 v[126:129], v[140:143], v[178:181], v[126:129]
	v_mfma_f32_16x16x32_bf16 v[122:125], v[154:157], v[178:181], v[122:125]
	v_mfma_f32_16x16x32_bf16 v[110:113], v[140:143], v[186:189], v[110:113]
	v_mfma_f32_16x16x32_bf16 v[106:109], v[154:157], v[186:189], v[106:109]
	v_mfma_f32_16x16x32_bf16 v[94:97], v[140:143], v[194:197], v[94:97]
	v_mfma_f32_16x16x32_bf16 v[90:93], v[154:157], v[194:197], v[90:93]
	v_mfma_f32_16x16x32_bf16 v[78:81], v[140:143], v[202:205], v[78:81]
	v_mfma_f32_16x16x32_bf16 v[74:77], v[154:157], v[202:205], v[74:77]
	v_mfma_f32_16x16x32_bf16 v[126:129], v[150:153], v[182:185], v[126:129]
	v_mfma_f32_16x16x32_bf16 v[122:125], v[158:161], v[182:185], v[122:125]
	v_mfma_f32_16x16x32_bf16 v[110:113], v[150:153], v[190:193], v[110:113]
	v_mfma_f32_16x16x32_bf16 v[106:109], v[158:161], v[190:193], v[106:109]
	v_mfma_f32_16x16x32_bf16 v[94:97], v[150:153], v[198:201], v[94:97]
	v_mfma_f32_16x16x32_bf16 v[90:93], v[158:161], v[198:201], v[90:93]
	v_mfma_f32_16x16x32_bf16 v[78:81], v[150:153], v[206:209], v[78:81]
	v_mfma_f32_16x16x32_bf16 v[74:77], v[158:161], v[206:209], v[74:77]
	v_mfma_f32_16x16x32_bf16 v[118:121], v[162:165], v[178:181], v[118:121]
	v_mfma_f32_16x16x32_bf16 v[114:117], v[170:173], v[178:181], v[114:117]
	v_mfma_f32_16x16x32_bf16 v[102:105], v[162:165], v[186:189], v[102:105]
	v_mfma_f32_16x16x32_bf16 v[98:101], v[170:173], v[186:189], v[98:101]
	v_mfma_f32_16x16x32_bf16 v[86:89], v[162:165], v[194:197], v[86:89]
	v_mfma_f32_16x16x32_bf16 v[82:85], v[170:173], v[194:197], v[82:85]
	v_mfma_f32_16x16x32_bf16 v[70:73], v[162:165], v[202:205], v[70:73]
	v_mfma_f32_16x16x32_bf16 v[66:69], v[170:173], v[202:205], v[66:69]
	v_mfma_f32_16x16x32_bf16 v[118:121], v[166:169], v[182:185], v[118:121]
	v_mfma_f32_16x16x32_bf16 v[114:117], v[174:177], v[182:185], v[114:117]
	v_mfma_f32_16x16x32_bf16 v[102:105], v[166:169], v[190:193], v[102:105]
	v_mfma_f32_16x16x32_bf16 v[98:101], v[174:177], v[190:193], v[98:101]
	v_mfma_f32_16x16x32_bf16 v[86:89], v[166:169], v[198:201], v[86:89]
	v_mfma_f32_16x16x32_bf16 v[82:85], v[174:177], v[198:201], v[82:85]
	v_mfma_f32_16x16x32_bf16 v[70:73], v[166:169], v[206:209], v[70:73]
	v_mfma_f32_16x16x32_bf16 v[66:69], v[174:177], v[206:209], v[66:69]
	s_setprio 0
	s_barrier
	s_add_i32 s64, s87, s73
	v_lshl_add_u64 v[144:145], v[144:145], 0, s[48:49]
	s_mov_b32 m0, s64
	ds_read_b128 v[178:181], v149 offset:49152
	ds_read_b128 v[182:185], v149 offset:50176
	ds_read_b128 v[186:189], v149 offset:51200
	ds_read_b128 v[190:193], v149 offset:52224
	ds_read_b128 v[194:197], v149 offset:53248
	ds_read_b128 v[198:201], v149 offset:54272
	ds_read_b128 v[202:205], v149 offset:55296
	ds_read_b128 v[206:209], v149 offset:56320
	global_load_lds_dwordx4 v[144:145], off
	s_add_i32 m0, s64, 0x2000
	s_add_u32 s64, s68, 0x40080
	v_lshl_add_u64 v[144:145], v[210:211], 0, s[48:49]
	s_addc_u32 s65, s69, 0
	s_add_i32 s68, s88, s73
	global_load_lds_dwordx4 v[144:145], off
	v_lshl_add_u64 v[144:145], s[64:65], 0, v[0:1]
	s_mov_b32 m0, s68
	s_nop 0
	global_load_lds_dwordx4 v[144:145], off
	v_lshl_add_u64 v[144:145], s[64:65], 0, v[134:135]
	s_add_i32 m0, s68, 0x2000
	s_nop 0
	global_load_lds_dwordx4 v[144:145], off
	v_lshl_add_u64 v[144:145], v[220:221], 0, s[48:49]
	s_mov_b32 m0, s81
	s_nop 0
	global_load_lds_dwordx4 v[144:145], off
	v_lshl_add_u64 v[144:145], v[224:225], 0, s[48:49]
	s_mov_b32 m0, s82
	s_nop 0
	global_load_lds_dwordx4 v[144:145], off
	s_waitcnt vmcnt(8)
	s_waitcnt lgkmcnt(0)
	s_setprio 3
	s_barrier
	s_waitcnt lgkmcnt(0)
	v_mfma_f32_16x16x32_bf16 v[62:65], v[140:143], v[178:181], v[62:65]
	v_mfma_f32_16x16x32_bf16 v[58:61], v[154:157], v[178:181], v[58:61]
	v_mfma_f32_16x16x32_bf16 v[46:49], v[140:143], v[186:189], v[46:49]
	v_mfma_f32_16x16x32_bf16 v[42:45], v[154:157], v[186:189], v[42:45]
	v_mfma_f32_16x16x32_bf16 v[30:33], v[140:143], v[194:197], v[30:33]
	v_mfma_f32_16x16x32_bf16 v[26:29], v[154:157], v[194:197], v[26:29]
	v_mfma_f32_16x16x32_bf16 v[14:17], v[140:143], v[202:205], v[14:17]
	v_mfma_f32_16x16x32_bf16 v[10:13], v[154:157], v[202:205], v[10:13]
	v_mfma_f32_16x16x32_bf16 v[62:65], v[150:153], v[182:185], v[62:65]
	v_mfma_f32_16x16x32_bf16 v[58:61], v[158:161], v[182:185], v[58:61]
	v_mfma_f32_16x16x32_bf16 v[46:49], v[150:153], v[190:193], v[46:49]
	v_mfma_f32_16x16x32_bf16 v[42:45], v[158:161], v[190:193], v[42:45]
	v_mfma_f32_16x16x32_bf16 v[30:33], v[150:153], v[198:201], v[30:33]
	v_mfma_f32_16x16x32_bf16 v[26:29], v[158:161], v[198:201], v[26:29]
	v_mfma_f32_16x16x32_bf16 v[14:17], v[150:153], v[206:209], v[14:17]
	v_mfma_f32_16x16x32_bf16 v[10:13], v[158:161], v[206:209], v[10:13]
	v_mfma_f32_16x16x32_bf16 v[54:57], v[162:165], v[178:181], v[54:57]
	v_mfma_f32_16x16x32_bf16 v[50:53], v[170:173], v[178:181], v[50:53]
	v_mfma_f32_16x16x32_bf16 v[38:41], v[162:165], v[186:189], v[38:41]
	v_mfma_f32_16x16x32_bf16 v[34:37], v[170:173], v[186:189], v[34:37]
	v_mfma_f32_16x16x32_bf16 v[22:25], v[162:165], v[194:197], v[22:25]
	v_mfma_f32_16x16x32_bf16 v[18:21], v[170:173], v[194:197], v[18:21]
	v_mfma_f32_16x16x32_bf16 v[6:9], v[162:165], v[202:205], v[6:9]
	v_mfma_f32_16x16x32_bf16 v[2:5], v[170:173], v[202:205], v[2:5]
	v_mfma_f32_16x16x32_bf16 v[54:57], v[166:169], v[182:185], v[54:57]
	v_mfma_f32_16x16x32_bf16 v[50:53], v[174:177], v[182:185], v[50:53]
	v_mfma_f32_16x16x32_bf16 v[38:41], v[166:169], v[190:193], v[38:41]
	v_mfma_f32_16x16x32_bf16 v[34:37], v[174:177], v[190:193], v[34:37]
	v_mfma_f32_16x16x32_bf16 v[22:25], v[166:169], v[198:201], v[22:25]
	v_mfma_f32_16x16x32_bf16 v[18:21], v[174:177], v[198:201], v[18:21]
	v_mfma_f32_16x16x32_bf16 v[6:9], v[166:169], v[206:209], v[6:9]
	v_mfma_f32_16x16x32_bf16 v[2:5], v[174:177], v[206:209], v[2:5]
	s_setprio 0
	s_barrier
	s_add_i32 s86, s86, 2
	s_add_u32 s56, s56, 0x100
	s_addc_u32 s57, s57, 0
	s_add_u32 s31, s31, 0x100
	s_addc_u32 s85, s85, 0
.LBB0_1603:
	s_add_u32 s64, s56, 0xfffc0080
	s_addc_u32 s65, s57, -1
	s_add_i32 s87, 0, 0x10000
	s_cmp_eq_u32 s86, 12
	s_cselect_b32 s71, s17, s65
	s_cselect_b32 s70, s27, s64
	v_add_u32_e32 v144, s87, v147
	s_cselect_b32 s69, s13, s85
	s_cselect_b32 s68, s30, s31
	s_add_i32 s88, 0, 0x14000
	ds_read_b128 v[140:143], v144
	ds_read_b128 v[150:153], v144 offset:1024
	ds_read_b128 v[154:157], v144 offset:2048
	ds_read_b128 v[158:161], v144 offset:3072
	v_add_u32_e32 v144, s88, v147
	ds_read_b128 v[162:165], v144
	ds_read_b128 v[166:169], v144 offset:1024
	ds_read_b128 v[170:173], v144 offset:2048
	ds_read_b128 v[174:177], v144 offset:3072
	v_lshl_add_u64 v[144:145], s[56:57], 0, v[136:137]
	s_add_i32 m0, s53, 0xc000
	ds_read_b128 v[178:181], v149
	ds_read_b128 v[182:185], v149 offset:1024
	ds_read_b128 v[186:189], v149 offset:2048
	ds_read_b128 v[190:193], v149 offset:3072
	ds_read_b128 v[194:197], v149 offset:4096
	ds_read_b128 v[198:201], v149 offset:5120
	ds_read_b128 v[202:205], v149 offset:6144
	ds_read_b128 v[206:209], v149 offset:7168
	global_load_lds_dwordx4 v[144:145], off
	v_lshl_add_u64 v[144:145], s[56:57], 0, v[138:139]
	s_add_i32 m0, s53, 0xe000
	s_nop 0
	global_load_lds_dwordx4 v[144:145], off
	s_waitcnt vmcnt(8)
	s_waitcnt lgkmcnt(0)
	s_setprio 3
	s_barrier
	s_waitcnt lgkmcnt(0)
	v_mfma_f32_16x16x32_bf16 v[126:129], v[140:143], v[178:181], v[126:129]
	v_mfma_f32_16x16x32_bf16 v[122:125], v[154:157], v[178:181], v[122:125]
	v_mfma_f32_16x16x32_bf16 v[110:113], v[140:143], v[186:189], v[110:113]
	v_mfma_f32_16x16x32_bf16 v[106:109], v[154:157], v[186:189], v[106:109]
	v_mfma_f32_16x16x32_bf16 v[94:97], v[140:143], v[194:197], v[94:97]
	v_mfma_f32_16x16x32_bf16 v[90:93], v[154:157], v[194:197], v[90:93]
	v_mfma_f32_16x16x32_bf16 v[78:81], v[140:143], v[202:205], v[78:81]
	v_mfma_f32_16x16x32_bf16 v[74:77], v[154:157], v[202:205], v[74:77]
	v_mfma_f32_16x16x32_bf16 v[126:129], v[150:153], v[182:185], v[126:129]
	v_mfma_f32_16x16x32_bf16 v[122:125], v[158:161], v[182:185], v[122:125]
	v_mfma_f32_16x16x32_bf16 v[110:113], v[150:153], v[190:193], v[110:113]
	v_mfma_f32_16x16x32_bf16 v[106:109], v[158:161], v[190:193], v[106:109]
	v_mfma_f32_16x16x32_bf16 v[94:97], v[150:153], v[198:201], v[94:97]
	v_mfma_f32_16x16x32_bf16 v[90:93], v[158:161], v[198:201], v[90:93]
	v_mfma_f32_16x16x32_bf16 v[78:81], v[150:153], v[206:209], v[78:81]
	v_mfma_f32_16x16x32_bf16 v[74:77], v[158:161], v[206:209], v[74:77]
	v_mfma_f32_16x16x32_bf16 v[118:121], v[162:165], v[178:181], v[118:121]
	v_mfma_f32_16x16x32_bf16 v[114:117], v[170:173], v[178:181], v[114:117]
	v_mfma_f32_16x16x32_bf16 v[102:105], v[162:165], v[186:189], v[102:105]
	v_mfma_f32_16x16x32_bf16 v[98:101], v[170:173], v[186:189], v[98:101]
	v_mfma_f32_16x16x32_bf16 v[86:89], v[162:165], v[194:197], v[86:89]
	v_mfma_f32_16x16x32_bf16 v[82:85], v[170:173], v[194:197], v[82:85]
	v_mfma_f32_16x16x32_bf16 v[70:73], v[162:165], v[202:205], v[70:73]
	v_mfma_f32_16x16x32_bf16 v[66:69], v[170:173], v[202:205], v[66:69]
	v_mfma_f32_16x16x32_bf16 v[118:121], v[166:169], v[182:185], v[118:121]
	v_mfma_f32_16x16x32_bf16 v[114:117], v[174:177], v[182:185], v[114:117]
	v_mfma_f32_16x16x32_bf16 v[102:105], v[166:169], v[190:193], v[102:105]
	v_mfma_f32_16x16x32_bf16 v[98:101], v[174:177], v[190:193], v[98:101]
	v_mfma_f32_16x16x32_bf16 v[86:89], v[166:169], v[198:201], v[86:89]
	v_mfma_f32_16x16x32_bf16 v[82:85], v[174:177], v[198:201], v[82:85]
	v_mfma_f32_16x16x32_bf16 v[70:73], v[166:169], v[206:209], v[70:73]
	v_mfma_f32_16x16x32_bf16 v[66:69], v[174:177], v[206:209], v[66:69]
	s_setprio 0
	s_barrier
	s_add_i32 s64, s87, s73
	v_lshl_add_u64 v[144:145], s[68:69], 0, v[0:1]
	s_mov_b32 m0, s64
	ds_read_b128 v[178:181], v149 offset:16384
	ds_read_b128 v[182:185], v149 offset:17408
	ds_read_b128 v[186:189], v149 offset:18432
	ds_read_b128 v[190:193], v149 offset:19456
	ds_read_b128 v[194:197], v149 offset:20480
	ds_read_b128 v[198:201], v149 offset:21504
	ds_read_b128 v[202:205], v149 offset:22528
	ds_read_b128 v[206:209], v149 offset:23552
	global_load_lds_dwordx4 v[144:145], off
	s_add_i32 m0, s64, 0x2000
	s_add_u32 s64, s68, 0x40000
	v_lshl_add_u64 v[210:211], s[68:69], 0, v[134:135]
	s_addc_u32 s65, s69, 0
	s_add_i32 s87, s88, s73
	global_load_lds_dwordx4 v[210:211], off
	v_lshl_add_u64 v[220:221], s[64:65], 0, v[0:1]
	s_mov_b32 m0, s87
	v_lshl_add_u64 v[224:225], s[70:71], 0, v[134:135]
	global_load_lds_dwordx4 v[220:221], off
	v_lshl_add_u64 v[220:221], s[64:65], 0, v[134:135]
	s_add_i32 m0, s87, 0x2000
	s_nop 0
	global_load_lds_dwordx4 v[220:221], off
	v_lshl_add_u64 v[220:221], s[70:71], 0, v[0:1]
	s_mov_b32 m0, s53
	s_nop 0
	global_load_lds_dwordx4 v[220:221], off
	s_mov_b32 m0, s78
	s_nop 0
	global_load_lds_dwordx4 v[224:225], off
	s_waitcnt vmcnt(8)
	s_waitcnt lgkmcnt(0)
	s_setprio 3
	s_barrier
	s_waitcnt lgkmcnt(0)
	v_mfma_f32_16x16x32_bf16 v[62:65], v[140:143], v[178:181], v[62:65]
	v_mfma_f32_16x16x32_bf16 v[58:61], v[154:157], v[178:181], v[58:61]
	v_mfma_f32_16x16x32_bf16 v[46:49], v[140:143], v[186:189], v[46:49]
	v_mfma_f32_16x16x32_bf16 v[42:45], v[154:157], v[186:189], v[42:45]
	v_mfma_f32_16x16x32_bf16 v[30:33], v[140:143], v[194:197], v[30:33]
	v_mfma_f32_16x16x32_bf16 v[26:29], v[154:157], v[194:197], v[26:29]
	v_mfma_f32_16x16x32_bf16 v[14:17], v[140:143], v[202:205], v[14:17]
	v_mfma_f32_16x16x32_bf16 v[10:13], v[154:157], v[202:205], v[10:13]
	v_mfma_f32_16x16x32_bf16 v[62:65], v[150:153], v[182:185], v[62:65]
	v_mfma_f32_16x16x32_bf16 v[58:61], v[158:161], v[182:185], v[58:61]
	v_mfma_f32_16x16x32_bf16 v[46:49], v[150:153], v[190:193], v[46:49]
	v_mfma_f32_16x16x32_bf16 v[42:45], v[158:161], v[190:193], v[42:45]
	v_mfma_f32_16x16x32_bf16 v[30:33], v[150:153], v[198:201], v[30:33]
	v_mfma_f32_16x16x32_bf16 v[26:29], v[158:161], v[198:201], v[26:29]
	v_mfma_f32_16x16x32_bf16 v[14:17], v[150:153], v[206:209], v[14:17]
	v_mfma_f32_16x16x32_bf16 v[10:13], v[158:161], v[206:209], v[10:13]
	v_mfma_f32_16x16x32_bf16 v[54:57], v[162:165], v[178:181], v[54:57]
	v_mfma_f32_16x16x32_bf16 v[50:53], v[170:173], v[178:181], v[50:53]
	v_mfma_f32_16x16x32_bf16 v[38:41], v[162:165], v[186:189], v[38:41]
	v_mfma_f32_16x16x32_bf16 v[34:37], v[170:173], v[186:189], v[34:37]
	v_mfma_f32_16x16x32_bf16 v[22:25], v[162:165], v[194:197], v[22:25]
	v_mfma_f32_16x16x32_bf16 v[18:21], v[170:173], v[194:197], v[18:21]
	v_mfma_f32_16x16x32_bf16 v[6:9], v[162:165], v[202:205], v[6:9]
	v_mfma_f32_16x16x32_bf16 v[2:5], v[170:173], v[202:205], v[2:5]
	v_mfma_f32_16x16x32_bf16 v[54:57], v[166:169], v[182:185], v[54:57]
	v_mfma_f32_16x16x32_bf16 v[50:53], v[174:177], v[182:185], v[50:53]
	v_mfma_f32_16x16x32_bf16 v[38:41], v[166:169], v[190:193], v[38:41]
	v_mfma_f32_16x16x32_bf16 v[34:37], v[174:177], v[190:193], v[34:37]
	v_mfma_f32_16x16x32_bf16 v[22:25], v[166:169], v[198:201], v[22:25]
	v_mfma_f32_16x16x32_bf16 v[18:21], v[174:177], v[198:201], v[18:21]
	v_mfma_f32_16x16x32_bf16 v[6:9], v[166:169], v[206:209], v[6:9]
	v_mfma_f32_16x16x32_bf16 v[2:5], v[174:177], v[206:209], v[2:5]
	s_setprio 0
	s_barrier
	s_add_i32 s87, 0, 0x18000
	s_add_i32 s88, 0, 0x1c000
	v_add_u32_e32 v158, s87, v147
	v_add_u32_e32 v174, s88, v147
	ds_read_b128 v[140:143], v158
	ds_read_b128 v[150:153], v158 offset:1024
	ds_read_b128 v[154:157], v158 offset:2048
	ds_read_b128 v[158:161], v158 offset:3072
	ds_read_b128 v[162:165], v174
	ds_read_b128 v[166:169], v174 offset:1024
	ds_read_b128 v[170:173], v174 offset:2048
	ds_read_b128 v[174:177], v174 offset:3072
	s_add_u32 s64, s70, 0x40000
	s_addc_u32 s65, s71, 0
	s_mov_b32 m0, s79
	v_lshl_add_u64 v[226:227], s[64:65], 0, v[0:1]
	ds_read_b128 v[178:181], v149 offset:32768
	ds_read_b128 v[182:185], v149 offset:33792
	ds_read_b128 v[186:189], v149 offset:34816
	ds_read_b128 v[190:193], v149 offset:35840
	ds_read_b128 v[194:197], v149 offset:36864
	ds_read_b128 v[198:201], v149 offset:37888
	ds_read_b128 v[202:205], v149 offset:38912
	ds_read_b128 v[206:209], v149 offset:39936
	global_load_lds_dwordx4 v[226:227], off
	v_lshl_add_u64 v[226:227], s[64:65], 0, v[134:135]
	s_mov_b32 m0, s80
	s_nop 0
	global_load_lds_dwordx4 v[226:227], off
	s_waitcnt vmcnt(8)
	s_waitcnt lgkmcnt(0)
	s_setprio 3
	s_barrier
	s_waitcnt lgkmcnt(0)
	v_mfma_f32_16x16x32_bf16 v[126:129], v[140:143], v[178:181], v[126:129]
	v_mfma_f32_16x16x32_bf16 v[122:125], v[154:157], v[178:181], v[122:125]
	v_mfma_f32_16x16x32_bf16 v[110:113], v[140:143], v[186:189], v[110:113]
	v_mfma_f32_16x16x32_bf16 v[106:109], v[154:157], v[186:189], v[106:109]
	v_mfma_f32_16x16x32_bf16 v[94:97], v[140:143], v[194:197], v[94:97]
	v_mfma_f32_16x16x32_bf16 v[90:93], v[154:157], v[194:197], v[90:93]
	v_mfma_f32_16x16x32_bf16 v[78:81], v[140:143], v[202:205], v[78:81]
	v_mfma_f32_16x16x32_bf16 v[74:77], v[154:157], v[202:205], v[74:77]
	v_mfma_f32_16x16x32_bf16 v[126:129], v[150:153], v[182:185], v[126:129]
	v_mfma_f32_16x16x32_bf16 v[122:125], v[158:161], v[182:185], v[122:125]
	v_mfma_f32_16x16x32_bf16 v[110:113], v[150:153], v[190:193], v[110:113]
	v_mfma_f32_16x16x32_bf16 v[106:109], v[158:161], v[190:193], v[106:109]
	v_mfma_f32_16x16x32_bf16 v[94:97], v[150:153], v[198:201], v[94:97]
	v_mfma_f32_16x16x32_bf16 v[90:93], v[158:161], v[198:201], v[90:93]
	v_mfma_f32_16x16x32_bf16 v[78:81], v[150:153], v[206:209], v[78:81]
	v_mfma_f32_16x16x32_bf16 v[74:77], v[158:161], v[206:209], v[74:77]
	v_mfma_f32_16x16x32_bf16 v[118:121], v[162:165], v[178:181], v[118:121]
	v_mfma_f32_16x16x32_bf16 v[114:117], v[170:173], v[178:181], v[114:117]
	v_mfma_f32_16x16x32_bf16 v[102:105], v[162:165], v[186:189], v[102:105]
	v_mfma_f32_16x16x32_bf16 v[98:101], v[170:173], v[186:189], v[98:101]
	v_mfma_f32_16x16x32_bf16 v[86:89], v[162:165], v[194:197], v[86:89]
	v_mfma_f32_16x16x32_bf16 v[82:85], v[170:173], v[194:197], v[82:85]
	v_mfma_f32_16x16x32_bf16 v[70:73], v[162:165], v[202:205], v[70:73]
	v_mfma_f32_16x16x32_bf16 v[66:69], v[170:173], v[202:205], v[66:69]
	v_mfma_f32_16x16x32_bf16 v[118:121], v[166:169], v[182:185], v[118:121]
	v_mfma_f32_16x16x32_bf16 v[114:117], v[174:177], v[182:185], v[114:117]
	v_mfma_f32_16x16x32_bf16 v[102:105], v[166:169], v[190:193], v[102:105]
	v_mfma_f32_16x16x32_bf16 v[98:101], v[174:177], v[190:193], v[98:101]
	v_mfma_f32_16x16x32_bf16 v[86:89], v[166:169], v[198:201], v[86:89]
	v_mfma_f32_16x16x32_bf16 v[82:85], v[174:177], v[198:201], v[82:85]
	v_mfma_f32_16x16x32_bf16 v[70:73], v[166:169], v[206:209], v[70:73]
	v_mfma_f32_16x16x32_bf16 v[66:69], v[174:177], v[206:209], v[66:69]
	s_setprio 0
	s_barrier
	s_add_i32 s64, s87, s73
	v_lshl_add_u64 v[144:145], v[144:145], 0, s[48:49]
	s_mov_b32 m0, s64
	ds_read_b128 v[178:181], v149 offset:49152
	ds_read_b128 v[182:185], v149 offset:50176
	ds_read_b128 v[186:189], v149 offset:51200
	ds_read_b128 v[190:193], v149 offset:52224
	ds_read_b128 v[194:197], v149 offset:53248
	ds_read_b128 v[198:201], v149 offset:54272
	ds_read_b128 v[202:205], v149 offset:55296
	ds_read_b128 v[206:209], v149 offset:56320
	global_load_lds_dwordx4 v[144:145], off
	s_add_i32 m0, s64, 0x2000
	s_add_u32 s64, s68, 0x40080
	v_lshl_add_u64 v[144:145], v[210:211], 0, s[48:49]
	s_addc_u32 s65, s69, 0
	s_add_i32 s68, s88, s73
	global_load_lds_dwordx4 v[144:145], off
	v_lshl_add_u64 v[144:145], s[64:65], 0, v[0:1]
	s_mov_b32 m0, s68
	s_nop 0
	global_load_lds_dwordx4 v[144:145], off
	v_lshl_add_u64 v[144:145], s[64:65], 0, v[134:135]
	s_add_i32 m0, s68, 0x2000
	s_nop 0
	global_load_lds_dwordx4 v[144:145], off
	v_lshl_add_u64 v[144:145], v[220:221], 0, s[48:49]
	s_mov_b32 m0, s81
	s_nop 0
	global_load_lds_dwordx4 v[144:145], off
	v_lshl_add_u64 v[144:145], v[224:225], 0, s[48:49]
	s_mov_b32 m0, s82
	s_nop 0
	global_load_lds_dwordx4 v[144:145], off
	s_waitcnt vmcnt(8)
	s_waitcnt lgkmcnt(0)
	s_setprio 3
	s_barrier
	s_waitcnt lgkmcnt(0)
	v_mfma_f32_16x16x32_bf16 v[62:65], v[140:143], v[178:181], v[62:65]
	v_mfma_f32_16x16x32_bf16 v[58:61], v[154:157], v[178:181], v[58:61]
	v_mfma_f32_16x16x32_bf16 v[46:49], v[140:143], v[186:189], v[46:49]
	v_mfma_f32_16x16x32_bf16 v[42:45], v[154:157], v[186:189], v[42:45]
	v_mfma_f32_16x16x32_bf16 v[30:33], v[140:143], v[194:197], v[30:33]
	v_mfma_f32_16x16x32_bf16 v[26:29], v[154:157], v[194:197], v[26:29]
	v_mfma_f32_16x16x32_bf16 v[14:17], v[140:143], v[202:205], v[14:17]
	v_mfma_f32_16x16x32_bf16 v[10:13], v[154:157], v[202:205], v[10:13]
	v_mfma_f32_16x16x32_bf16 v[62:65], v[150:153], v[182:185], v[62:65]
	v_mfma_f32_16x16x32_bf16 v[58:61], v[158:161], v[182:185], v[58:61]
	v_mfma_f32_16x16x32_bf16 v[46:49], v[150:153], v[190:193], v[46:49]
	v_mfma_f32_16x16x32_bf16 v[42:45], v[158:161], v[190:193], v[42:45]
	v_mfma_f32_16x16x32_bf16 v[30:33], v[150:153], v[198:201], v[30:33]
	v_mfma_f32_16x16x32_bf16 v[26:29], v[158:161], v[198:201], v[26:29]
	v_mfma_f32_16x16x32_bf16 v[14:17], v[150:153], v[206:209], v[14:17]
	v_mfma_f32_16x16x32_bf16 v[10:13], v[158:161], v[206:209], v[10:13]
	v_mfma_f32_16x16x32_bf16 v[54:57], v[162:165], v[178:181], v[54:57]
	v_mfma_f32_16x16x32_bf16 v[50:53], v[170:173], v[178:181], v[50:53]
	v_mfma_f32_16x16x32_bf16 v[38:41], v[162:165], v[186:189], v[38:41]
	v_mfma_f32_16x16x32_bf16 v[34:37], v[170:173], v[186:189], v[34:37]
	v_mfma_f32_16x16x32_bf16 v[22:25], v[162:165], v[194:197], v[22:25]
	v_mfma_f32_16x16x32_bf16 v[18:21], v[170:173], v[194:197], v[18:21]
	v_mfma_f32_16x16x32_bf16 v[6:9], v[162:165], v[202:205], v[6:9]
	v_mfma_f32_16x16x32_bf16 v[2:5], v[170:173], v[202:205], v[2:5]
	v_mfma_f32_16x16x32_bf16 v[54:57], v[166:169], v[182:185], v[54:57]
	v_mfma_f32_16x16x32_bf16 v[50:53], v[174:177], v[182:185], v[50:53]
	v_mfma_f32_16x16x32_bf16 v[38:41], v[166:169], v[190:193], v[38:41]
	v_mfma_f32_16x16x32_bf16 v[34:37], v[174:177], v[190:193], v[34:37]
	v_mfma_f32_16x16x32_bf16 v[22:25], v[166:169], v[198:201], v[22:25]
	v_mfma_f32_16x16x32_bf16 v[18:21], v[174:177], v[198:201], v[18:21]
	v_mfma_f32_16x16x32_bf16 v[6:9], v[166:169], v[206:209], v[6:9]
	v_mfma_f32_16x16x32_bf16 v[2:5], v[174:177], v[206:209], v[2:5]
	s_setprio 0
	s_barrier
	s_add_i32 s86, s86, 2
	s_add_u32 s56, s56, 0x100
	s_addc_u32 s57, s57, 0
	s_add_u32 s31, s31, 0x100
	s_addc_u32 s85, s85, 0
	s_cmp_gt_u32 s86, 13
	s_cbranch_scc0 .LBB0_1603
	s_and_b64 vcc, exec, s[10:11]
	s_cbranch_vccz .LBB0_1606
	s_barrier

.LBB0_1670:
	s_ashr_i32 s11, s12, 3
	s_add_i32 s11, s12, s11
	s_and_b64 s[16:17], s[66:67], s[4:5]
	s_add_i32 s11, s11, 1
	s_and_b64 s[16:17], s[16:17], exec
	s_cselect_b32 s12, s11, s12
	s_ashr_i32 s13, s12, 31
	s_lshl_b64 s[16:17], s[12:13], 19
	s_add_u32 s16, s31, s16
	s_addc_u32 s17, s36, s17
	s_and_b64 s[26:27], s[4:5], exec
	s_cselect_b32 s13, s17, s53
	s_cselect_b32 s79, s16, s52
	s_ashr_i32 s11, s10, 31
	s_lshl_b64 s[26:27], s[10:11], 19
	s_add_u32 s26, s37, s26
	s_addc_u32 s27, s60, s27
	s_and_b64 s[64:65], s[4:5], exec
	s_cselect_b32 s11, s27, s57
	s_cselect_b32 s80, s26, s56
	s_add_u32 s52, s52, 0x40080
	s_addc_u32 s53, s53, 0
	s_add_u32 s81, s56, 0x100
	s_addc_u32 s82, s57, 0
	s_mov_b32 s83, -2
	s_add_u32 s56, s52, 0xfffc0080
	s_addc_u32 s57, s53, -1
	s_add_i32 s64, 0, 0x10000
	s_cmp_eq_u32 s83, 12
	s_cselect_b32 s69, s13, s57
	s_cselect_b32 s68, s79, s56
	v_add_u32_e32 v144, s64, v147
	s_cselect_b32 s57, s11, s82
	s_cselect_b32 s56, s80, s81
	s_add_i32 s84, 0, 0x14000
	ds_read_b128 v[150:153], v144
	ds_read_b128 v[154:157], v144 offset:1024
	ds_read_b128 v[158:161], v144 offset:2048
	ds_read_b128 v[162:165], v144 offset:3072
	v_add_u32_e32 v144, s84, v147
	ds_read_b128 v[166:169], v144
	ds_read_b128 v[170:173], v144 offset:1024
	ds_read_b128 v[174:177], v144 offset:2048
	ds_read_b128 v[178:181], v144 offset:3072
	v_lshl_add_u64 v[144:145], s[52:53], 0, v[140:141]
	s_add_i32 m0, s19, 0xc000
	ds_read_b128 v[182:185], v149
	ds_read_b128 v[186:189], v149 offset:1024
	ds_read_b128 v[190:193], v149 offset:2048
	ds_read_b128 v[194:197], v149 offset:3072
	ds_read_b128 v[198:201], v149 offset:4096
	ds_read_b128 v[202:205], v149 offset:5120
	ds_read_b128 v[206:209], v149 offset:6144
	ds_read_b128 v[224:227], v149 offset:7168
	global_load_lds_dwordx4 v[144:145], off
	v_lshl_add_u64 v[144:145], s[52:53], 0, v[142:143]
	s_add_i32 m0, s19, 0xe000
	s_nop 0
	global_load_lds_dwordx4 v[144:145], off
	s_waitcnt vmcnt(8)
	s_waitcnt lgkmcnt(0)
	s_setprio 3
	s_barrier
	s_waitcnt lgkmcnt(0)
	v_mfma_f32_16x16x32_bf16 v[126:129], v[150:153], v[182:185], 0
	v_mfma_f32_16x16x32_bf16 v[122:125], v[158:161], v[182:185], 0
	v_mfma_f32_16x16x32_bf16 v[118:121], v[150:153], v[190:193], 0
	v_mfma_f32_16x16x32_bf16 v[110:113], v[158:161], v[190:193], 0
	v_mfma_f32_16x16x32_bf16 v[102:105], v[150:153], v[198:201], 0
	v_mfma_f32_16x16x32_bf16 v[94:97], v[158:161], v[198:201], 0
	v_mfma_f32_16x16x32_bf16 v[86:89], v[150:153], v[206:209], 0
	v_mfma_f32_16x16x32_bf16 v[78:81], v[158:161], v[206:209], 0
	v_mfma_f32_16x16x32_bf16 v[126:129], v[154:157], v[186:189], v[126:129]
	v_mfma_f32_16x16x32_bf16 v[122:125], v[162:165], v[186:189], v[122:125]
	v_mfma_f32_16x16x32_bf16 v[118:121], v[154:157], v[194:197], v[118:121]
	v_mfma_f32_16x16x32_bf16 v[110:113], v[162:165], v[194:197], v[110:113]
	v_mfma_f32_16x16x32_bf16 v[102:105], v[154:157], v[202:205], v[102:105]
	v_mfma_f32_16x16x32_bf16 v[94:97], v[162:165], v[202:205], v[94:97]
	v_mfma_f32_16x16x32_bf16 v[86:89], v[154:157], v[224:227], v[86:89]
	v_mfma_f32_16x16x32_bf16 v[78:81], v[162:165], v[224:227], v[78:81]
	v_mfma_f32_16x16x32_bf16 v[114:117], v[166:169], v[182:185], 0
	v_mfma_f32_16x16x32_bf16 v[106:109], v[174:177], v[182:185], 0
	v_mfma_f32_16x16x32_bf16 v[98:101], v[166:169], v[190:193], 0
	v_mfma_f32_16x16x32_bf16 v[90:93], v[174:177], v[190:193], 0
	v_mfma_f32_16x16x32_bf16 v[82:85], v[166:169], v[198:201], 0
	v_mfma_f32_16x16x32_bf16 v[74:77], v[174:177], v[198:201], 0
	v_mfma_f32_16x16x32_bf16 v[70:73], v[166:169], v[206:209], 0
	v_mfma_f32_16x16x32_bf16 v[66:69], v[174:177], v[206:209], 0
	v_mfma_f32_16x16x32_bf16 v[114:117], v[170:173], v[186:189], v[114:117]
	v_mfma_f32_16x16x32_bf16 v[106:109], v[178:181], v[186:189], v[106:109]
	v_mfma_f32_16x16x32_bf16 v[98:101], v[170:173], v[194:197], v[98:101]
	v_mfma_f32_16x16x32_bf16 v[90:93], v[178:181], v[194:197], v[90:93]
	v_mfma_f32_16x16x32_bf16 v[82:85], v[170:173], v[202:205], v[82:85]
	v_mfma_f32_16x16x32_bf16 v[74:77], v[178:181], v[202:205], v[74:77]
	v_mfma_f32_16x16x32_bf16 v[70:73], v[170:173], v[224:227], v[70:73]
	v_mfma_f32_16x16x32_bf16 v[66:69], v[178:181], v[224:227], v[66:69]
	s_setprio 0
	s_barrier
	s_add_i32 s64, s64, s63
	v_lshl_add_u64 v[144:145], s[56:57], 0, v[0:1]
	s_mov_b32 m0, s64
	ds_read_b128 v[182:185], v149 offset:16384
	ds_read_b128 v[186:189], v149 offset:17408
	ds_read_b128 v[190:193], v149 offset:18432
	ds_read_b128 v[194:197], v149 offset:19456
	ds_read_b128 v[198:201], v149 offset:20480
	ds_read_b128 v[202:205], v149 offset:21504
	ds_read_b128 v[206:209], v149 offset:22528
	ds_read_b128 v[224:227], v149 offset:23552
	global_load_lds_dwordx4 v[144:145], off
	s_add_i32 m0, s64, 0x2000
	s_add_u32 s64, s56, 0x40000
	v_lshl_add_u64 v[210:211], s[56:57], 0, v[134:135]
	s_addc_u32 s65, s57, 0
	s_add_i32 s84, s84, s63
	global_load_lds_dwordx4 v[210:211], off
	v_lshl_add_u64 v[220:221], s[64:65], 0, v[0:1]
	s_mov_b32 m0, s84
	v_lshl_add_u64 v[228:229], s[68:69], 0, v[136:137]
	global_load_lds_dwordx4 v[220:221], off
	v_lshl_add_u64 v[220:221], s[64:65], 0, v[134:135]
	s_add_i32 m0, s84, 0x2000
	s_nop 0
	global_load_lds_dwordx4 v[220:221], off
	v_lshl_add_u64 v[220:221], s[68:69], 0, v[138:139]
	s_mov_b32 m0, s19
	s_nop 0
	global_load_lds_dwordx4 v[220:221], off
	s_mov_b32 m0, s21
	s_nop 0
	global_load_lds_dwordx4 v[228:229], off
	s_waitcnt vmcnt(8)
	s_waitcnt lgkmcnt(0)
	s_setprio 3
	s_barrier
	s_waitcnt lgkmcnt(0)
	v_mfma_f32_16x16x32_bf16 v[62:65], v[150:153], v[182:185], 0
	v_mfma_f32_16x16x32_bf16 v[58:61], v[158:161], v[182:185], 0
	v_mfma_f32_16x16x32_bf16 v[54:57], v[150:153], v[190:193], 0
	v_mfma_f32_16x16x32_bf16 v[46:49], v[158:161], v[190:193], 0
	v_mfma_f32_16x16x32_bf16 v[38:41], v[150:153], v[198:201], 0
	v_mfma_f32_16x16x32_bf16 v[30:33], v[158:161], v[198:201], 0
	v_mfma_f32_16x16x32_bf16 v[22:25], v[150:153], v[206:209], 0
	v_mfma_f32_16x16x32_bf16 v[14:17], v[158:161], v[206:209], 0
	v_mfma_f32_16x16x32_bf16 v[62:65], v[154:157], v[186:189], v[62:65]
	v_mfma_f32_16x16x32_bf16 v[58:61], v[162:165], v[186:189], v[58:61]
	v_mfma_f32_16x16x32_bf16 v[54:57], v[154:157], v[194:197], v[54:57]
	v_mfma_f32_16x16x32_bf16 v[46:49], v[162:165], v[194:197], v[46:49]
	v_mfma_f32_16x16x32_bf16 v[38:41], v[154:157], v[202:205], v[38:41]
	v_mfma_f32_16x16x32_bf16 v[30:33], v[162:165], v[202:205], v[30:33]
	v_mfma_f32_16x16x32_bf16 v[22:25], v[154:157], v[224:227], v[22:25]
	v_mfma_f32_16x16x32_bf16 v[14:17], v[162:165], v[224:227], v[14:17]
	v_mfma_f32_16x16x32_bf16 v[50:53], v[166:169], v[182:185], 0
	v_mfma_f32_16x16x32_bf16 v[42:45], v[174:177], v[182:185], 0
	v_mfma_f32_16x16x32_bf16 v[34:37], v[166:169], v[190:193], 0
	v_mfma_f32_16x16x32_bf16 v[26:29], v[174:177], v[190:193], 0
	v_mfma_f32_16x16x32_bf16 v[18:21], v[166:169], v[198:201], 0
	v_mfma_f32_16x16x32_bf16 v[10:13], v[174:177], v[198:201], 0
	v_mfma_f32_16x16x32_bf16 v[6:9], v[166:169], v[206:209], 0
	v_mfma_f32_16x16x32_bf16 v[2:5], v[174:177], v[206:209], 0
	v_mfma_f32_16x16x32_bf16 v[50:53], v[170:173], v[186:189], v[50:53]
	v_mfma_f32_16x16x32_bf16 v[42:45], v[178:181], v[186:189], v[42:45]
	v_mfma_f32_16x16x32_bf16 v[34:37], v[170:173], v[194:197], v[34:37]
	v_mfma_f32_16x16x32_bf16 v[26:29], v[178:181], v[194:197], v[26:29]
	v_mfma_f32_16x16x32_bf16 v[18:21], v[170:173], v[202:205], v[18:21]
	v_mfma_f32_16x16x32_bf16 v[10:13], v[178:181], v[202:205], v[10:13]
	v_mfma_f32_16x16x32_bf16 v[6:9], v[170:173], v[224:227], v[6:9]
	v_mfma_f32_16x16x32_bf16 v[2:5], v[178:181], v[224:227], v[2:5]
	s_setprio 0
	s_barrier
	s_add_i32 s84, 0, 0x18000
	s_add_i32 s85, 0, 0x1c000
	v_add_u32_e32 v162, s84, v147
	v_add_u32_e32 v178, s85, v147
	ds_read_b128 v[150:153], v162
	ds_read_b128 v[154:157], v162 offset:1024
	ds_read_b128 v[158:161], v162 offset:2048
	ds_read_b128 v[162:165], v162 offset:3072
	ds_read_b128 v[166:169], v178
	ds_read_b128 v[170:173], v178 offset:1024
	ds_read_b128 v[174:177], v178 offset:2048
	ds_read_b128 v[178:181], v178 offset:3072
	s_add_u32 s64, s68, 0x40000
	s_addc_u32 s65, s69, 0
	s_mov_b32 m0, s71
	v_lshl_add_u64 v[230:231], s[64:65], 0, v[138:139]
	ds_read_b128 v[182:185], v149 offset:32768
	ds_read_b128 v[186:189], v149 offset:33792
	ds_read_b128 v[190:193], v149 offset:34816
	ds_read_b128 v[194:197], v149 offset:35840
	ds_read_b128 v[198:201], v149 offset:36864
	ds_read_b128 v[202:205], v149 offset:37888
	ds_read_b128 v[206:209], v149 offset:38912
	ds_read_b128 v[224:227], v149 offset:39936
	global_load_lds_dwordx4 v[230:231], off
	v_lshl_add_u64 v[230:231], s[64:65], 0, v[136:137]
	s_mov_b32 m0, s72
	s_nop 0
	global_load_lds_dwordx4 v[230:231], off
	s_waitcnt vmcnt(8)
	s_waitcnt lgkmcnt(0)
	s_setprio 3
	s_barrier
	s_waitcnt lgkmcnt(0)
	v_mfma_f32_16x16x32_bf16 v[126:129], v[150:153], v[182:185], v[126:129]
	v_mfma_f32_16x16x32_bf16 v[122:125], v[158:161], v[182:185], v[122:125]
	v_mfma_f32_16x16x32_bf16 v[118:121], v[150:153], v[190:193], v[118:121]
	v_mfma_f32_16x16x32_bf16 v[110:113], v[158:161], v[190:193], v[110:113]
	v_mfma_f32_16x16x32_bf16 v[102:105], v[150:153], v[198:201], v[102:105]
	v_mfma_f32_16x16x32_bf16 v[94:97], v[158:161], v[198:201], v[94:97]
	v_mfma_f32_16x16x32_bf16 v[86:89], v[150:153], v[206:209], v[86:89]
	v_mfma_f32_16x16x32_bf16 v[78:81], v[158:161], v[206:209], v[78:81]
	v_mfma_f32_16x16x32_bf16 v[126:129], v[154:157], v[186:189], v[126:129]
	v_mfma_f32_16x16x32_bf16 v[122:125], v[162:165], v[186:189], v[122:125]
	v_mfma_f32_16x16x32_bf16 v[118:121], v[154:157], v[194:197], v[118:121]
	v_mfma_f32_16x16x32_bf16 v[110:113], v[162:165], v[194:197], v[110:113]
	v_mfma_f32_16x16x32_bf16 v[102:105], v[154:157], v[202:205], v[102:105]
	v_mfma_f32_16x16x32_bf16 v[94:97], v[162:165], v[202:205], v[94:97]
	v_mfma_f32_16x16x32_bf16 v[86:89], v[154:157], v[224:227], v[86:89]
	v_mfma_f32_16x16x32_bf16 v[78:81], v[162:165], v[224:227], v[78:81]
	v_mfma_f32_16x16x32_bf16 v[114:117], v[166:169], v[182:185], v[114:117]
	v_mfma_f32_16x16x32_bf16 v[106:109], v[174:177], v[182:185], v[106:109]
	v_mfma_f32_16x16x32_bf16 v[98:101], v[166:169], v[190:193], v[98:101]
	v_mfma_f32_16x16x32_bf16 v[90:93], v[174:177], v[190:193], v[90:93]
	v_mfma_f32_16x16x32_bf16 v[82:85], v[166:169], v[198:201], v[82:85]
	v_mfma_f32_16x16x32_bf16 v[74:77], v[174:177], v[198:201], v[74:77]
	v_mfma_f32_16x16x32_bf16 v[70:73], v[166:169], v[206:209], v[70:73]
	v_mfma_f32_16x16x32_bf16 v[66:69], v[174:177], v[206:209], v[66:69]
	v_mfma_f32_16x16x32_bf16 v[114:117], v[170:173], v[186:189], v[114:117]
	v_mfma_f32_16x16x32_bf16 v[106:109], v[178:181], v[186:189], v[106:109]
	v_mfma_f32_16x16x32_bf16 v[98:101], v[170:173], v[194:197], v[98:101]
	v_mfma_f32_16x16x32_bf16 v[90:93], v[178:181], v[194:197], v[90:93]
	v_mfma_f32_16x16x32_bf16 v[82:85], v[170:173], v[202:205], v[82:85]
	v_mfma_f32_16x16x32_bf16 v[74:77], v[178:181], v[202:205], v[74:77]
	v_mfma_f32_16x16x32_bf16 v[70:73], v[170:173], v[224:227], v[70:73]
	v_mfma_f32_16x16x32_bf16 v[66:69], v[178:181], v[224:227], v[66:69]
	s_setprio 0
	s_barrier
	s_add_i32 s64, s84, s63
	v_lshl_add_u64 v[144:145], v[144:145], 0, s[48:49]
	s_mov_b32 m0, s64
	ds_read_b128 v[182:185], v149 offset:49152
	ds_read_b128 v[186:189], v149 offset:50176
	ds_read_b128 v[190:193], v149 offset:51200
	ds_read_b128 v[194:197], v149 offset:52224
	ds_read_b128 v[198:201], v149 offset:53248
	ds_read_b128 v[202:205], v149 offset:54272
	ds_read_b128 v[206:209], v149 offset:55296
	ds_read_b128 v[224:227], v149 offset:56320
	global_load_lds_dwordx4 v[144:145], off
	s_add_i32 m0, s64, 0x2000
	s_add_u32 s56, s56, 0x40080
	v_lshl_add_u64 v[144:145], v[210:211], 0, s[48:49]
	s_addc_u32 s57, s57, 0
	s_add_i32 s64, s85, s63
	global_load_lds_dwordx4 v[144:145], off
	v_lshl_add_u64 v[144:145], s[56:57], 0, v[0:1]
	s_mov_b32 m0, s64
	s_nop 0
	global_load_lds_dwordx4 v[144:145], off
	v_lshl_add_u64 v[144:145], s[56:57], 0, v[134:135]
	s_add_i32 m0, s64, 0x2000
	s_nop 0
	global_load_lds_dwordx4 v[144:145], off
	v_lshl_add_u64 v[144:145], v[220:221], 0, s[48:49]
	s_mov_b32 m0, s73
	s_nop 0
	global_load_lds_dwordx4 v[144:145], off
	v_lshl_add_u64 v[144:145], v[228:229], 0, s[48:49]
	s_mov_b32 m0, s74
	s_nop 0
	global_load_lds_dwordx4 v[144:145], off
	s_waitcnt vmcnt(8)
	s_waitcnt lgkmcnt(0)
	s_setprio 3
	s_barrier
	s_waitcnt lgkmcnt(0)
	v_mfma_f32_16x16x32_bf16 v[62:65], v[150:153], v[182:185], v[62:65]
	v_mfma_f32_16x16x32_bf16 v[58:61], v[158:161], v[182:185], v[58:61]
	v_mfma_f32_16x16x32_bf16 v[54:57], v[150:153], v[190:193], v[54:57]
	v_mfma_f32_16x16x32_bf16 v[46:49], v[158:161], v[190:193], v[46:49]
	v_mfma_f32_16x16x32_bf16 v[38:41], v[150:153], v[198:201], v[38:41]
	v_mfma_f32_16x16x32_bf16 v[30:33], v[158:161], v[198:201], v[30:33]
	v_mfma_f32_16x16x32_bf16 v[22:25], v[150:153], v[206:209], v[22:25]
	v_mfma_f32_16x16x32_bf16 v[14:17], v[158:161], v[206:209], v[14:17]
	v_mfma_f32_16x16x32_bf16 v[62:65], v[154:157], v[186:189], v[62:65]
	v_mfma_f32_16x16x32_bf16 v[58:61], v[162:165], v[186:189], v[58:61]
	v_mfma_f32_16x16x32_bf16 v[54:57], v[154:157], v[194:197], v[54:57]
	v_mfma_f32_16x16x32_bf16 v[46:49], v[162:165], v[194:197], v[46:49]
	v_mfma_f32_16x16x32_bf16 v[38:41], v[154:157], v[202:205], v[38:41]
	v_mfma_f32_16x16x32_bf16 v[30:33], v[162:165], v[202:205], v[30:33]
	v_mfma_f32_16x16x32_bf16 v[22:25], v[154:157], v[224:227], v[22:25]
	v_mfma_f32_16x16x32_bf16 v[14:17], v[162:165], v[224:227], v[14:17]
	v_mfma_f32_16x16x32_bf16 v[50:53], v[166:169], v[182:185], v[50:53]
	v_mfma_f32_16x16x32_bf16 v[42:45], v[174:177], v[182:185], v[42:45]
	v_mfma_f32_16x16x32_bf16 v[34:37], v[166:169], v[190:193], v[34:37]
	v_mfma_f32_16x16x32_bf16 v[26:29], v[174:177], v[190:193], v[26:29]
	v_mfma_f32_16x16x32_bf16 v[18:21], v[166:169], v[198:201], v[18:21]
	v_mfma_f32_16x16x32_bf16 v[10:13], v[174:177], v[198:201], v[10:13]
	v_mfma_f32_16x16x32_bf16 v[6:9], v[166:169], v[206:209], v[6:9]
	v_mfma_f32_16x16x32_bf16 v[2:5], v[174:177], v[206:209], v[2:5]
	v_mfma_f32_16x16x32_bf16 v[50:53], v[170:173], v[186:189], v[50:53]
	v_mfma_f32_16x16x32_bf16 v[42:45], v[178:181], v[186:189], v[42:45]
	v_mfma_f32_16x16x32_bf16 v[34:37], v[170:173], v[194:197], v[34:37]
	v_mfma_f32_16x16x32_bf16 v[26:29], v[178:181], v[194:197], v[26:29]
	v_mfma_f32_16x16x32_bf16 v[18:21], v[170:173], v[202:205], v[18:21]
	v_mfma_f32_16x16x32_bf16 v[10:13], v[178:181], v[202:205], v[10:13]
	v_mfma_f32_16x16x32_bf16 v[6:9], v[170:173], v[224:227], v[6:9]
	v_mfma_f32_16x16x32_bf16 v[2:5], v[178:181], v[224:227], v[2:5]
	s_setprio 0
	s_barrier
	s_add_i32 s83, s83, 2
	s_add_u32 s52, s52, 0x100
	s_addc_u32 s53, s53, 0
	s_add_u32 s81, s81, 0x100
	s_addc_u32 s82, s82, 0
.LBB0_1671:
	s_add_u32 s56, s52, 0xfffc0080
	s_addc_u32 s57, s53, -1
	s_add_i32 s64, 0, 0x10000
	s_cmp_eq_u32 s83, 12
	s_cselect_b32 s69, s13, s57
	s_cselect_b32 s68, s79, s56
	v_add_u32_e32 v144, s64, v147
	s_cselect_b32 s57, s11, s82
	s_cselect_b32 s56, s80, s81
	s_add_i32 s84, 0, 0x14000
	ds_read_b128 v[150:153], v144
	ds_read_b128 v[154:157], v144 offset:1024
	ds_read_b128 v[158:161], v144 offset:2048
	ds_read_b128 v[162:165], v144 offset:3072
	v_add_u32_e32 v144, s84, v147
	ds_read_b128 v[166:169], v144
	ds_read_b128 v[170:173], v144 offset:1024
	ds_read_b128 v[174:177], v144 offset:2048
	ds_read_b128 v[178:181], v144 offset:3072
	v_lshl_add_u64 v[144:145], s[52:53], 0, v[140:141]
	s_add_i32 m0, s19, 0xc000
	ds_read_b128 v[182:185], v149
	ds_read_b128 v[186:189], v149 offset:1024
	ds_read_b128 v[190:193], v149 offset:2048
	ds_read_b128 v[194:197], v149 offset:3072
	ds_read_b128 v[198:201], v149 offset:4096
	ds_read_b128 v[202:205], v149 offset:5120
	ds_read_b128 v[206:209], v149 offset:6144
	ds_read_b128 v[224:227], v149 offset:7168
	global_load_lds_dwordx4 v[144:145], off
	v_lshl_add_u64 v[144:145], s[52:53], 0, v[142:143]
	s_add_i32 m0, s19, 0xe000
	s_nop 0
	global_load_lds_dwordx4 v[144:145], off
	s_waitcnt vmcnt(8)
	s_waitcnt lgkmcnt(0)
	s_setprio 3
	s_barrier
	s_waitcnt lgkmcnt(0)
	v_mfma_f32_16x16x32_bf16 v[126:129], v[150:153], v[182:185], v[126:129]
	v_mfma_f32_16x16x32_bf16 v[122:125], v[158:161], v[182:185], v[122:125]
	v_mfma_f32_16x16x32_bf16 v[118:121], v[150:153], v[190:193], v[118:121]
	v_mfma_f32_16x16x32_bf16 v[110:113], v[158:161], v[190:193], v[110:113]
	v_mfma_f32_16x16x32_bf16 v[102:105], v[150:153], v[198:201], v[102:105]
	v_mfma_f32_16x16x32_bf16 v[94:97], v[158:161], v[198:201], v[94:97]
	v_mfma_f32_16x16x32_bf16 v[86:89], v[150:153], v[206:209], v[86:89]
	v_mfma_f32_16x16x32_bf16 v[78:81], v[158:161], v[206:209], v[78:81]
	v_mfma_f32_16x16x32_bf16 v[126:129], v[154:157], v[186:189], v[126:129]
	v_mfma_f32_16x16x32_bf16 v[122:125], v[162:165], v[186:189], v[122:125]
	v_mfma_f32_16x16x32_bf16 v[118:121], v[154:157], v[194:197], v[118:121]
	v_mfma_f32_16x16x32_bf16 v[110:113], v[162:165], v[194:197], v[110:113]
	v_mfma_f32_16x16x32_bf16 v[102:105], v[154:157], v[202:205], v[102:105]
	v_mfma_f32_16x16x32_bf16 v[94:97], v[162:165], v[202:205], v[94:97]
	v_mfma_f32_16x16x32_bf16 v[86:89], v[154:157], v[224:227], v[86:89]
	v_mfma_f32_16x16x32_bf16 v[78:81], v[162:165], v[224:227], v[78:81]
	v_mfma_f32_16x16x32_bf16 v[114:117], v[166:169], v[182:185], v[114:117]
	v_mfma_f32_16x16x32_bf16 v[106:109], v[174:177], v[182:185], v[106:109]
	v_mfma_f32_16x16x32_bf16 v[98:101], v[166:169], v[190:193], v[98:101]
	v_mfma_f32_16x16x32_bf16 v[90:93], v[174:177], v[190:193], v[90:93]
	v_mfma_f32_16x16x32_bf16 v[82:85], v[166:169], v[198:201], v[82:85]
	v_mfma_f32_16x16x32_bf16 v[74:77], v[174:177], v[198:201], v[74:77]
	v_mfma_f32_16x16x32_bf16 v[70:73], v[166:169], v[206:209], v[70:73]
	v_mfma_f32_16x16x32_bf16 v[66:69], v[174:177], v[206:209], v[66:69]
	v_mfma_f32_16x16x32_bf16 v[114:117], v[170:173], v[186:189], v[114:117]
	v_mfma_f32_16x16x32_bf16 v[106:109], v[178:181], v[186:189], v[106:109]
	v_mfma_f32_16x16x32_bf16 v[98:101], v[170:173], v[194:197], v[98:101]
	v_mfma_f32_16x16x32_bf16 v[90:93], v[178:181], v[194:197], v[90:93]
	v_mfma_f32_16x16x32_bf16 v[82:85], v[170:173], v[202:205], v[82:85]
	v_mfma_f32_16x16x32_bf16 v[74:77], v[178:181], v[202:205], v[74:77]
	v_mfma_f32_16x16x32_bf16 v[70:73], v[170:173], v[224:227], v[70:73]
	v_mfma_f32_16x16x32_bf16 v[66:69], v[178:181], v[224:227], v[66:69]
	s_setprio 0
	s_barrier
	s_add_i32 s64, s64, s63
	v_lshl_add_u64 v[144:145], s[56:57], 0, v[0:1]
	s_mov_b32 m0, s64
	ds_read_b128 v[182:185], v149 offset:16384
	ds_read_b128 v[186:189], v149 offset:17408
	ds_read_b128 v[190:193], v149 offset:18432
	ds_read_b128 v[194:197], v149 offset:19456
	ds_read_b128 v[198:201], v149 offset:20480
	ds_read_b128 v[202:205], v149 offset:21504
	ds_read_b128 v[206:209], v149 offset:22528
	ds_read_b128 v[224:227], v149 offset:23552
	global_load_lds_dwordx4 v[144:145], off
	s_add_i32 m0, s64, 0x2000
	s_add_u32 s64, s56, 0x40000
	v_lshl_add_u64 v[210:211], s[56:57], 0, v[134:135]
	s_addc_u32 s65, s57, 0
	s_add_i32 s84, s84, s63
	global_load_lds_dwordx4 v[210:211], off
	v_lshl_add_u64 v[220:221], s[64:65], 0, v[0:1]
	s_mov_b32 m0, s84
	v_lshl_add_u64 v[228:229], s[68:69], 0, v[136:137]
	global_load_lds_dwordx4 v[220:221], off
	v_lshl_add_u64 v[220:221], s[64:65], 0, v[134:135]
	s_add_i32 m0, s84, 0x2000
	s_nop 0
	global_load_lds_dwordx4 v[220:221], off
	v_lshl_add_u64 v[220:221], s[68:69], 0, v[138:139]
	s_mov_b32 m0, s19
	s_nop 0
	global_load_lds_dwordx4 v[220:221], off
	s_mov_b32 m0, s21
	s_nop 0
	global_load_lds_dwordx4 v[228:229], off
	s_waitcnt vmcnt(8)
	s_waitcnt lgkmcnt(0)
	s_setprio 3
	s_barrier
	s_waitcnt lgkmcnt(0)
	v_mfma_f32_16x16x32_bf16 v[62:65], v[150:153], v[182:185], v[62:65]
	v_mfma_f32_16x16x32_bf16 v[58:61], v[158:161], v[182:185], v[58:61]
	v_mfma_f32_16x16x32_bf16 v[54:57], v[150:153], v[190:193], v[54:57]
	v_mfma_f32_16x16x32_bf16 v[46:49], v[158:161], v[190:193], v[46:49]
	v_mfma_f32_16x16x32_bf16 v[38:41], v[150:153], v[198:201], v[38:41]
	v_mfma_f32_16x16x32_bf16 v[30:33], v[158:161], v[198:201], v[30:33]
	v_mfma_f32_16x16x32_bf16 v[22:25], v[150:153], v[206:209], v[22:25]
	v_mfma_f32_16x16x32_bf16 v[14:17], v[158:161], v[206:209], v[14:17]
	v_mfma_f32_16x16x32_bf16 v[62:65], v[154:157], v[186:189], v[62:65]
	v_mfma_f32_16x16x32_bf16 v[58:61], v[162:165], v[186:189], v[58:61]
	v_mfma_f32_16x16x32_bf16 v[54:57], v[154:157], v[194:197], v[54:57]
	v_mfma_f32_16x16x32_bf16 v[46:49], v[162:165], v[194:197], v[46:49]
	v_mfma_f32_16x16x32_bf16 v[38:41], v[154:157], v[202:205], v[38:41]
	v_mfma_f32_16x16x32_bf16 v[30:33], v[162:165], v[202:205], v[30:33]
	v_mfma_f32_16x16x32_bf16 v[22:25], v[154:157], v[224:227], v[22:25]
	v_mfma_f32_16x16x32_bf16 v[14:17], v[162:165], v[224:227], v[14:17]
	v_mfma_f32_16x16x32_bf16 v[50:53], v[166:169], v[182:185], v[50:53]
	v_mfma_f32_16x16x32_bf16 v[42:45], v[174:177], v[182:185], v[42:45]
	v_mfma_f32_16x16x32_bf16 v[34:37], v[166:169], v[190:193], v[34:37]
	v_mfma_f32_16x16x32_bf16 v[26:29], v[174:177], v[190:193], v[26:29]
	v_mfma_f32_16x16x32_bf16 v[18:21], v[166:169], v[198:201], v[18:21]
	v_mfma_f32_16x16x32_bf16 v[10:13], v[174:177], v[198:201], v[10:13]
	v_mfma_f32_16x16x32_bf16 v[6:9], v[166:169], v[206:209], v[6:9]
	v_mfma_f32_16x16x32_bf16 v[2:5], v[174:177], v[206:209], v[2:5]
	v_mfma_f32_16x16x32_bf16 v[50:53], v[170:173], v[186:189], v[50:53]
	v_mfma_f32_16x16x32_bf16 v[42:45], v[178:181], v[186:189], v[42:45]
	v_mfma_f32_16x16x32_bf16 v[34:37], v[170:173], v[194:197], v[34:37]
	v_mfma_f32_16x16x32_bf16 v[26:29], v[178:181], v[194:197], v[26:29]
	v_mfma_f32_16x16x32_bf16 v[18:21], v[170:173], v[202:205], v[18:21]
	v_mfma_f32_16x16x32_bf16 v[10:13], v[178:181], v[202:205], v[10:13]
	v_mfma_f32_16x16x32_bf16 v[6:9], v[170:173], v[224:227], v[6:9]
	v_mfma_f32_16x16x32_bf16 v[2:5], v[178:181], v[224:227], v[2:5]
	s_setprio 0
	s_barrier
	s_add_i32 s84, 0, 0x18000
	s_add_i32 s85, 0, 0x1c000
	v_add_u32_e32 v162, s84, v147
	v_add_u32_e32 v178, s85, v147
	ds_read_b128 v[150:153], v162
	ds_read_b128 v[154:157], v162 offset:1024
	ds_read_b128 v[158:161], v162 offset:2048
	ds_read_b128 v[162:165], v162 offset:3072
	ds_read_b128 v[166:169], v178
	ds_read_b128 v[170:173], v178 offset:1024
	ds_read_b128 v[174:177], v178 offset:2048
	ds_read_b128 v[178:181], v178 offset:3072
	s_add_u32 s64, s68, 0x40000
	s_addc_u32 s65, s69, 0
	s_mov_b32 m0, s71
	v_lshl_add_u64 v[230:231], s[64:65], 0, v[138:139]
	ds_read_b128 v[182:185], v149 offset:32768
	ds_read_b128 v[186:189], v149 offset:33792
	ds_read_b128 v[190:193], v149 offset:34816
	ds_read_b128 v[194:197], v149 offset:35840
	ds_read_b128 v[198:201], v149 offset:36864
	ds_read_b128 v[202:205], v149 offset:37888
	ds_read_b128 v[206:209], v149 offset:38912
	ds_read_b128 v[224:227], v149 offset:39936
	global_load_lds_dwordx4 v[230:231], off
	v_lshl_add_u64 v[230:231], s[64:65], 0, v[136:137]
	s_mov_b32 m0, s72
	s_nop 0
	global_load_lds_dwordx4 v[230:231], off
	s_waitcnt vmcnt(8)
	s_waitcnt lgkmcnt(0)
	s_setprio 3
	s_barrier
	s_waitcnt lgkmcnt(0)
	v_mfma_f32_16x16x32_bf16 v[126:129], v[150:153], v[182:185], v[126:129]
	v_mfma_f32_16x16x32_bf16 v[122:125], v[158:161], v[182:185], v[122:125]
	v_mfma_f32_16x16x32_bf16 v[118:121], v[150:153], v[190:193], v[118:121]
	v_mfma_f32_16x16x32_bf16 v[110:113], v[158:161], v[190:193], v[110:113]
	v_mfma_f32_16x16x32_bf16 v[102:105], v[150:153], v[198:201], v[102:105]
	v_mfma_f32_16x16x32_bf16 v[94:97], v[158:161], v[198:201], v[94:97]
	v_mfma_f32_16x16x32_bf16 v[86:89], v[150:153], v[206:209], v[86:89]
	v_mfma_f32_16x16x32_bf16 v[78:81], v[158:161], v[206:209], v[78:81]
	v_mfma_f32_16x16x32_bf16 v[126:129], v[154:157], v[186:189], v[126:129]
	v_mfma_f32_16x16x32_bf16 v[122:125], v[162:165], v[186:189], v[122:125]
	v_mfma_f32_16x16x32_bf16 v[118:121], v[154:157], v[194:197], v[118:121]
	v_mfma_f32_16x16x32_bf16 v[110:113], v[162:165], v[194:197], v[110:113]
	v_mfma_f32_16x16x32_bf16 v[102:105], v[154:157], v[202:205], v[102:105]
	v_mfma_f32_16x16x32_bf16 v[94:97], v[162:165], v[202:205], v[94:97]
	v_mfma_f32_16x16x32_bf16 v[86:89], v[154:157], v[224:227], v[86:89]
	v_mfma_f32_16x16x32_bf16 v[78:81], v[162:165], v[224:227], v[78:81]
	v_mfma_f32_16x16x32_bf16 v[114:117], v[166:169], v[182:185], v[114:117]
	v_mfma_f32_16x16x32_bf16 v[106:109], v[174:177], v[182:185], v[106:109]
	v_mfma_f32_16x16x32_bf16 v[98:101], v[166:169], v[190:193], v[98:101]
	v_mfma_f32_16x16x32_bf16 v[90:93], v[174:177], v[190:193], v[90:93]
	v_mfma_f32_16x16x32_bf16 v[82:85], v[166:169], v[198:201], v[82:85]
	v_mfma_f32_16x16x32_bf16 v[74:77], v[174:177], v[198:201], v[74:77]
	v_mfma_f32_16x16x32_bf16 v[70:73], v[166:169], v[206:209], v[70:73]
	v_mfma_f32_16x16x32_bf16 v[66:69], v[174:177], v[206:209], v[66:69]
	v_mfma_f32_16x16x32_bf16 v[114:117], v[170:173], v[186:189], v[114:117]
	v_mfma_f32_16x16x32_bf16 v[106:109], v[178:181], v[186:189], v[106:109]
	v_mfma_f32_16x16x32_bf16 v[98:101], v[170:173], v[194:197], v[98:101]
	v_mfma_f32_16x16x32_bf16 v[90:93], v[178:181], v[194:197], v[90:93]
	v_mfma_f32_16x16x32_bf16 v[82:85], v[170:173], v[202:205], v[82:85]
	v_mfma_f32_16x16x32_bf16 v[74:77], v[178:181], v[202:205], v[74:77]
	v_mfma_f32_16x16x32_bf16 v[70:73], v[170:173], v[224:227], v[70:73]
	v_mfma_f32_16x16x32_bf16 v[66:69], v[178:181], v[224:227], v[66:69]
	s_setprio 0
	s_barrier
	s_add_i32 s64, s84, s63
	v_lshl_add_u64 v[144:145], v[144:145], 0, s[48:49]
	s_mov_b32 m0, s64
	ds_read_b128 v[182:185], v149 offset:49152
	ds_read_b128 v[186:189], v149 offset:50176
	ds_read_b128 v[190:193], v149 offset:51200
	ds_read_b128 v[194:197], v149 offset:52224
	ds_read_b128 v[198:201], v149 offset:53248
	ds_read_b128 v[202:205], v149 offset:54272
	ds_read_b128 v[206:209], v149 offset:55296
	ds_read_b128 v[224:227], v149 offset:56320
	global_load_lds_dwordx4 v[144:145], off
	s_add_i32 m0, s64, 0x2000
	s_add_u32 s56, s56, 0x40080
	v_lshl_add_u64 v[144:145], v[210:211], 0, s[48:49]
	s_addc_u32 s57, s57, 0
	s_add_i32 s64, s85, s63
	global_load_lds_dwordx4 v[144:145], off
	v_lshl_add_u64 v[144:145], s[56:57], 0, v[0:1]
	s_mov_b32 m0, s64
	s_nop 0
	global_load_lds_dwordx4 v[144:145], off
	v_lshl_add_u64 v[144:145], s[56:57], 0, v[134:135]
	s_add_i32 m0, s64, 0x2000
	s_nop 0
	global_load_lds_dwordx4 v[144:145], off
	v_lshl_add_u64 v[144:145], v[220:221], 0, s[48:49]
	s_mov_b32 m0, s73
	s_nop 0
	global_load_lds_dwordx4 v[144:145], off
	v_lshl_add_u64 v[144:145], v[228:229], 0, s[48:49]
	s_mov_b32 m0, s74
	s_nop 0
	global_load_lds_dwordx4 v[144:145], off
	s_waitcnt vmcnt(8)
	s_waitcnt lgkmcnt(0)
	s_setprio 3
	s_barrier
	s_waitcnt lgkmcnt(0)
	v_mfma_f32_16x16x32_bf16 v[62:65], v[150:153], v[182:185], v[62:65]
	v_mfma_f32_16x16x32_bf16 v[58:61], v[158:161], v[182:185], v[58:61]
	v_mfma_f32_16x16x32_bf16 v[54:57], v[150:153], v[190:193], v[54:57]
	v_mfma_f32_16x16x32_bf16 v[46:49], v[158:161], v[190:193], v[46:49]
	v_mfma_f32_16x16x32_bf16 v[38:41], v[150:153], v[198:201], v[38:41]
	v_mfma_f32_16x16x32_bf16 v[30:33], v[158:161], v[198:201], v[30:33]
	v_mfma_f32_16x16x32_bf16 v[22:25], v[150:153], v[206:209], v[22:25]
	v_mfma_f32_16x16x32_bf16 v[14:17], v[158:161], v[206:209], v[14:17]
	v_mfma_f32_16x16x32_bf16 v[62:65], v[154:157], v[186:189], v[62:65]
	v_mfma_f32_16x16x32_bf16 v[58:61], v[162:165], v[186:189], v[58:61]
	v_mfma_f32_16x16x32_bf16 v[54:57], v[154:157], v[194:197], v[54:57]
	v_mfma_f32_16x16x32_bf16 v[46:49], v[162:165], v[194:197], v[46:49]
	v_mfma_f32_16x16x32_bf16 v[38:41], v[154:157], v[202:205], v[38:41]
	v_mfma_f32_16x16x32_bf16 v[30:33], v[162:165], v[202:205], v[30:33]
	v_mfma_f32_16x16x32_bf16 v[22:25], v[154:157], v[224:227], v[22:25]
	v_mfma_f32_16x16x32_bf16 v[14:17], v[162:165], v[224:227], v[14:17]
	v_mfma_f32_16x16x32_bf16 v[50:53], v[166:169], v[182:185], v[50:53]
	v_mfma_f32_16x16x32_bf16 v[42:45], v[174:177], v[182:185], v[42:45]
	v_mfma_f32_16x16x32_bf16 v[34:37], v[166:169], v[190:193], v[34:37]
	v_mfma_f32_16x16x32_bf16 v[26:29], v[174:177], v[190:193], v[26:29]
	v_mfma_f32_16x16x32_bf16 v[18:21], v[166:169], v[198:201], v[18:21]
	v_mfma_f32_16x16x32_bf16 v[10:13], v[174:177], v[198:201], v[10:13]
	v_mfma_f32_16x16x32_bf16 v[6:9], v[166:169], v[206:209], v[6:9]
	v_mfma_f32_16x16x32_bf16 v[2:5], v[174:177], v[206:209], v[2:5]
	v_mfma_f32_16x16x32_bf16 v[50:53], v[170:173], v[186:189], v[50:53]
	v_mfma_f32_16x16x32_bf16 v[42:45], v[178:181], v[186:189], v[42:45]
	v_mfma_f32_16x16x32_bf16 v[34:37], v[170:173], v[194:197], v[34:37]
	v_mfma_f32_16x16x32_bf16 v[26:29], v[178:181], v[194:197], v[26:29]
	v_mfma_f32_16x16x32_bf16 v[18:21], v[170:173], v[202:205], v[18:21]
	v_mfma_f32_16x16x32_bf16 v[10:13], v[178:181], v[202:205], v[10:13]
	v_mfma_f32_16x16x32_bf16 v[6:9], v[170:173], v[224:227], v[6:9]
	v_mfma_f32_16x16x32_bf16 v[2:5], v[178:181], v[224:227], v[2:5]
	s_setprio 0
	s_barrier
	s_add_i32 s83, s83, 2
	s_add_u32 s52, s52, 0x100
	s_addc_u32 s53, s53, 0
	s_add_u32 s81, s81, 0x100
	s_addc_u32 s82, s82, 0
	s_cmp_gt_u32 s83, 13
	s_cbranch_scc0 .LBB0_1671
	s_and_b64 vcc, exec, s[8:9]
	s_cbranch_vccnz .LBB0_1675
	s_cmp_gt_i32 s18, 15
	s_cbranch_scc0 .LBB0_1676
